# rsqrt(x+eps) sequences: never-taken denormal rescale path removed (36 sites in epilogues / norms)
# speedup vs baseline: 1.0080x; 1.0080x over previous
;     __device__ __forceinline__ void operator()(const f32x4 (&acc)[2][2][4][2], const Unit& u, int wr, int wc, int fr, int fq) const {
;         const int row0 = u.pm * BM + wr * 64 + fr; const int pn = u.pn;
;         int fqo = fq; asm volatile("" : "+v"(fqo));
;         const float* bp = bias + (size_t)((u.pm * BM) >> 14) * 2048 + pn * BM + wc * 32 + 8 * fqo;
;     ...
;             const bool isq = (pn == 6) || (wc < 2);
;             const int hcol = (pn == 6) ? 64 * wc : (wc < 2 ? 64 * (4 + wc) : 64 * (wc - 2));
;             bf16_t* base = qkv + (isq ? OFF_QC : OFF_KC) + hcol + 8 * fqo;
;             const int pitch = isq ? 384 : 128;
;             const float* gw = (isq ? gq : gk) + 4 * fqo;
;             const float osc = isq ? 0.125f * 1.4426950408889634f : 1.0f;
; #pragma unroll
;             for (int ai = 0; ai < 2; ++ai)
; #pragma unroll
;                 for (int m = 0; m < 4; ++m) {
;                     const int row = row0 + ai * HALF + m * 16; const int t = row & 16383;
;                     const float rv = rsqrtf(rowss[row] * (1.0f / 1024.0f) + 1e-6f);
;                     float ss = 0.f; f32x4 hv[2][2];
; #pragma unroll
;                     for (int bj = 0; bj < 2; ++bj)
; #pragma unroll
;                         for (int n = 0; n < 2; ++n) { const f32x4 v = acc[ai][bj][m][n] * rv + *(const f32x4*)(bp + bj * HALF + 4 * n); hv[bj][n] = v; ss += (v[0] * v[0] + v[1] * v[1]) + (v[2] * v[2] + v[3] * v[3]); }
;                     ss += __shfl_xor(ss, 16); ss += __shfl_xor(ss, 32);
;                     const float rinv = rsqrtf(ss * (1.0f / 64.0f) + 1e-6f) * osc;
.LBB0_259:
	s_ashr_i32 s0, s6, 6
	s_lshl_b32 s4, s6, 8
	s_ashr_i32 s1, s0, 31
	s_add_i32 s4, s4, s11
	s_lshl_b64 s[0:1], s[0:1], 13
	s_add_u32 s5, s79, s0
	s_addc_u32 s6, s10, s1
	s_lshl_b32 s0, s66, 8
	s_ashr_i32 s1, s0, 31
	s_lshl_b64 s[0:1], s[0:1], 2
	s_add_u32 s0, s5, s0
	v_mov_b32_e32 v244, v238
	s_addc_u32 s1, s6, s1
	s_add_u32 s0, s0, s80
	v_lshlrev_b32_e32 v164, 3, v244
	v_or_b32_e32 v162, s4, v237
	s_addc_u32 s1, s1, 0
	v_ashrrev_i32_e32 v165, 31, v164
	v_lshl_add_u64 v[166:167], v[164:165], 2, s[0:1]
	s_mov_b64 s[0:1], -1
	s_cmp_gt_i32 s66, 5
	v_ashrrev_i32_e32 v163, 31, v162
	v_or_b32_e32 v243, 16, v162
	v_or_b32_e32 v242, 32, v162
	v_or_b32_e32 v241, 48, v162
	s_cbranch_scc0 .LBB0_261
	s_cmp_eq_u32 s66, 6
	s_cselect_b64 s[0:1], -1, 0
	s_and_b64 s[6:7], s[0:1], exec
	v_readlane_b32 s5, v255, 23
	s_cselect_b32 s34, s81, s5
	s_or_b64 vcc, s[0:1], s[38:39]
	s_and_b64 s[0:1], vcc, exec
	s_mov_b32 s0, 0x5800000
	s_cselect_b32 s0, s0, 0x7000000
	s_add_u32 s5, s2, s0
	s_addc_u32 s6, s3, 0
	s_lshl_b64 s[0:1], s[34:35], 1
	s_add_u32 s0, s5, s0
	s_addc_u32 s1, s6, s1
	v_readlane_b32 s48, v252, 2
	v_lshl_add_u64 v[170:171], v[164:165], 1, s[0:1]
	s_and_b64 s[0:1], vcc, exec
	v_readlane_b32 s50, v252, 4
	v_readlane_b32 s52, v252, 6
	v_lshlrev_b32_e32 v130, 2, v244
	v_readlane_b32 s51, v252, 5
	v_readlane_b32 s53, v252, 7
	s_cselect_b32 s0, s50, s52
	v_ashrrev_i32_e32 v131, 31, v130
	s_cselect_b32 s1, s51, s53
	s_add_u32 s0, s0, s76
	v_lshlrev_b64 v[186:187], 2, v[130:131]
	v_and_b32_e32 v131, 64, v230
	s_addc_u32 s1, s1, s77
	v_xor_b32_e32 v130, 16, v230
	v_add_u32_e32 v131, 64, v131
	v_lshl_add_u64 v[168:169], s[0:1], 0, v[186:187]
	v_cmp_lt_i32_e64 s[0:1], v130, v131
	v_lshl_add_u64 v[172:173], v[162:163], 2, s[12:13]
	v_cndmask_b32_e32 v245, 1.0, v231, vcc
	v_cndmask_b32_e64 v130, v230, v130, s[0:1]
	v_lshlrev_b32_e32 v246, 2, v130
	v_xor_b32_e32 v130, 32, v230
	v_cmp_lt_i32_e64 s[0:1], v130, v131
	v_mov_b32_e32 v159, v129
	v_mov_b32_e32 v161, v129
	v_cndmask_b32_e64 v130, v230, v130, s[0:1]
	v_lshlrev_b32_e32 v247, 2, v130
	global_load_dword v130, v[172:173], off
	global_load_dword v248, v[172:173], off offset:64
	global_load_dword v249, v[172:173], off offset:128
	global_load_dword v250, v[172:173], off offset:192
	global_load_dword v251, v[172:173], off offset:512
	global_load_dword v143, v[172:173], off offset:576
	global_load_dword v145, v[172:173], off offset:640
	global_load_dword v147, v[172:173], off offset:704
	s_and_b64 s[0:1], vcc, exec
	s_movk_i32 s0, 0x180
	s_cselect_b32 s0, s0, 0x80
	s_and_b32 s1, s4, 0x3fc0
	s_add_u32 s4, s82, s1
	s_addc_u32 s5, s83, 0
	v_readlane_b32 s49, v252, 3
	v_readlane_b32 s54, v252, 8
	v_readlane_b32 s55, v252, 9
	v_readlane_b32 s56, v252, 10
	v_readlane_b32 s57, v252, 11
	v_readlane_b32 s58, v252, 12
	v_readlane_b32 s59, v252, 13
	v_readlane_b32 s60, v252, 14
	v_readlane_b32 s61, v252, 15
	v_readlane_b32 s62, v252, 16
	v_readlane_b32 s63, v252, 17
	s_waitcnt vmcnt(0)
	v_fmamk_f32 v130, v130, 0x3a800000, v227
	s_nop 0
	v_rsq_f32_e32 v130, v130
	s_nop 0
	v_mov_b32_e32 v188, v130
	global_load_dwordx4 v[130:133], v[166:167], off offset:16
	global_load_dwordx4 v[134:137], v[166:167], off
	s_waitcnt vmcnt(1)
	v_pk_fma_f32 v[140:141], v[122:123], v[188:189], v[132:133] op_sel_hi:[1,0,1]
	s_waitcnt vmcnt(0)
	v_pk_fma_f32 v[192:193], v[124:125], v[188:189], v[134:135] op_sel_hi:[1,0,1]
	v_pk_fma_f32 v[194:195], v[126:127], v[188:189], v[136:137] op_sel_hi:[1,0,1]
	v_pk_mul_f32 v[136:137], v[192:193], v[192:193]
	v_pk_mul_f32 v[134:135], v[194:195], v[194:195]
	s_nop 0
	v_pk_mov_b32 v[138:139], v[136:137], v[134:135] op_sel:[1,0]
	v_mov_b32_e32 v137, v135
	v_pk_add_f32 v[134:135], v[138:139], v[136:137]
	v_pk_fma_f32 v[138:139], v[120:121], v[188:189], v[130:131] op_sel_hi:[1,0,1]
	v_pk_mul_f32 v[130:131], v[140:141], v[140:141]
	v_pk_mul_f32 v[132:133], v[138:139], v[138:139]
	v_pk_add_f32 v[198:199], v[134:135], v[134:135] op_sel_hi:[0,1]
	v_pk_mov_b32 v[134:135], v[132:133], v[130:131] op_sel:[1,0]
	v_mov_b32_e32 v133, v131
	v_pk_add_f32 v[130:131], v[134:135], v[132:133]
	s_nop 0
	v_pk_add_f32 v[200:201], v[130:131], v[130:131] op_sel_hi:[0,1]
	global_load_dwordx4 v[130:133], v[166:167], off offset:528
	global_load_dwordx4 v[134:137], v[166:167], off offset:512
	s_waitcnt vmcnt(1)
	v_pk_fma_f32 v[190:191], v[58:59], v[188:189], v[132:133] op_sel_hi:[1,0,1]
	s_waitcnt vmcnt(0)
	v_pk_fma_f32 v[206:207], v[60:61], v[188:189], v[134:135] op_sel_hi:[1,0,1]
	v_pk_fma_f32 v[204:205], v[62:63], v[188:189], v[136:137] op_sel_hi:[1,0,1]
	v_mul_f32_e32 v134, v206, v206
	v_pk_fma_f32 v[134:135], v[206:207], v[206:207], v[134:135] op_sel_hi:[1,1,0]
	v_pk_fma_f32 v[196:197], v[56:57], v[188:189], v[130:131] op_sel_hi:[1,0,1]
	v_mul_f32_e32 v134, v204, v204
	v_pk_fma_f32 v[136:137], v[204:205], v[204:205], v[134:135] op_sel_hi:[1,1,0]
	v_mul_f32_e32 v134, v196, v196
	v_mul_f32_e32 v136, v197, v197
	v_mul_f32_e32 v198, v190, v190
	v_mul_f32_e32 v200, v191, v191
	v_pk_add_f32 v[130:131], v[134:135], v[136:137]
	v_pk_add_f32 v[132:133], v[198:199], v[200:201]
	v_lshl_add_u64 v[200:201], s[4:5], 0, v[186:187]
	v_pk_add_f32 v[130:131], v[130:131], v[132:133]
	s_add_u32 s4, s84, s1
	v_add_f32_e32 v130, v130, v131
	ds_bpermute_b32 v131, v246, v130
	s_addc_u32 s5, s85, 0
	v_lshl_add_u64 v[202:203], s[4:5], 0, v[186:187]
	global_load_dwordx4 v[134:137], v[200:201], off
	s_waitcnt lgkmcnt(0)
	v_add_f32_e32 v130, v130, v131
	ds_bpermute_b32 v131, v247, v130
	s_waitcnt lgkmcnt(0)
; __device__ __forceinline__ unsigned pk_bf16(float lo, float hi) { f32x2 v = {lo, hi}; bf16x2_t b = __builtin_convertvector(v, bf16x2_t); return __builtin_bit_cast(unsigned, b); }
;     __device__ __forceinline__ void operator()(const f32x4 (&acc)[2][2][4][2], const Unit& u, int wr, int wc, int fr, int fq) const {
;     ...
;                     const int row = row0 + ai * HALF + m * 16; const int t = row & 16383;
;                     const float rv = rsqrtf(rowss[row] * (1.0f / 1024.0f) + 1e-6f);
;                     float ss = 0.f; f32x4 hv[2][2];
; #pragma unroll
;                     for (int bj = 0; bj < 2; ++bj)
; #pragma unroll
;                         for (int n = 0; n < 2; ++n) { const f32x4 v = acc[ai][bj][m][n] * rv + *(const f32x4*)(bp + bj * HALF + 4 * n); hv[bj][n] = v; ss += (v[0] * v[0] + v[1] * v[1]) + (v[2] * v[2] + v[3] * v[3]); }
;                     ss += __shfl_xor(ss, 16); ss += __shfl_xor(ss, 32);
;                     const float rinv = rsqrtf(ss * (1.0f / 64.0f) + 1e-6f) * osc;
; #pragma unroll
;                     for (int bj = 0; bj < 2; ++bj) {
;                         const int pos = bj == 0 ? (t >> 6) : (t & 63);
;                         const f32x4 c = *(const f32x4*)(ropec + pos * 16 + 4 * fqo), s = *(const f32x4*)(ropes + pos * 16 + 4 * fqo);
;                         const f32x4 x1 = hv[bj][0] * rinv * *(const f32x4*)(gw + 32 * bj), x2 = hv[bj][1] * rinv * *(const f32x4*)(gw + 32 * bj + 16);
;                         const f32x4 o1 = x1 * c - x2 * s, o2 = x2 * c + x1 * s;
;                         u32x4 w; w.x = pk_bf16(o1[0], o1[1]); w.y = pk_bf16(o1[2], o1[3]); w.z = pk_bf16(o2[0], o2[1]); w.w = pk_bf16(o2[2], o2[3]);
;                         *(u32x4*)(base + (size_t)row * pitch + 32 * bj) = w;
;                     }
	v_add_f32_e32 v130, v130, v131
	v_fmamk_f32 v130, v130, 0x3c800000, v227
	s_nop 0
	v_rsq_f32_e32 v130, v130
	s_nop 0
	v_mul_f32_e32 v198, v245, v130
	v_pk_mul_f32 v[208:209], v[194:195], v[198:199] op_sel_hi:[1,0]
	v_pk_mul_f32 v[210:211], v[192:193], v[198:199] op_sel_hi:[1,0]
	global_load_dwordx4 v[192:195], v[168:169], off
	v_mad_i64_i32 v[130:131], s[6:7], s0, v162, 0
	v_lshl_add_u64 v[188:189], v[130:131], 1, v[170:171]
	global_load_dwordx4 v[130:133], v[202:203], off
	v_pk_mul_f32 v[204:205], v[204:205], v[198:199] op_sel_hi:[1,0]
	v_pk_mul_f32 v[206:207], v[206:207], v[198:199] op_sel_hi:[1,0]
	v_pk_mul_f32 v[196:197], v[196:197], v[198:199] op_sel_hi:[1,0]
	v_pk_mul_f32 v[190:191], v[190:191], v[198:199] op_sel_hi:[1,0]
	s_waitcnt vmcnt(1)
	v_pk_mul_f32 v[192:193], v[192:193], v[210:211]
	v_pk_mul_f32 v[194:195], v[194:195], v[208:209]
	v_pk_mul_f32 v[208:209], v[138:139], v[198:199] op_sel_hi:[1,0]
	v_pk_mul_f32 v[210:211], v[140:141], v[198:199] op_sel_hi:[1,0]
	global_load_dwordx4 v[138:141], v[168:169], off offset:64
	s_waitcnt vmcnt(0)
	v_pk_mul_f32 v[140:141], v[140:141], v[210:211]
	v_pk_mul_f32 v[138:139], v[138:139], v[208:209]
	v_pk_mul_f32 v[210:211], v[132:133], v[140:141]
	v_pk_mul_f32 v[208:209], v[130:131], v[138:139]
	v_pk_fma_f32 v[210:211], v[136:137], v[194:195], v[210:211] neg_lo:[0,0,1] neg_hi:[0,0,1]
	v_pk_fma_f32 v[208:209], v[134:135], v[192:193], v[208:209] neg_lo:[0,0,1] neg_hi:[0,0,1]
	v_pk_mul_f32 v[134:135], v[134:135], v[138:139]
	v_pk_mul_f32 v[136:137], v[136:137], v[140:141]
	s_nop 0
	v_pk_fma_f32 v[136:137], v[132:133], v[194:195], v[136:137]
	v_pk_fma_f32 v[132:133], v[130:131], v[192:193], v[134:135]
	v_cvt_pk_bf16_f32 v130, v208, v209
	v_cvt_pk_bf16_f32 v131, v210, v211
	v_cvt_pk_bf16_f32 v132, v132, v133
	v_cvt_pk_bf16_f32 v133, v136, v137
	global_store_dwordx4 v[188:189], v[130:133], off
	global_load_dwordx4 v[138:141], v[168:169], off offset:128
	v_lshl_add_u64 v[192:193], v[150:151], 0, v[186:187]
	v_lshl_add_u64 v[194:195], v[152:153], 0, v[186:187]
	global_load_dwordx4 v[130:133], v[192:193], off
	global_load_dwordx4 v[134:137], v[194:195], off
	s_waitcnt vmcnt(2)
	v_pk_mul_f32 v[206:207], v[138:139], v[206:207]
	v_pk_mul_f32 v[204:205], v[140:141], v[204:205]
	global_load_dwordx4 v[138:141], v[168:169], off offset:192
	s_waitcnt vmcnt(0)
	v_pk_mul_f32 v[140:141], v[140:141], v[190:191]
	v_pk_mul_f32 v[138:139], v[138:139], v[196:197]
	v_pk_mul_f32 v[196:197], v[136:137], v[140:141]
	v_pk_mul_f32 v[190:191], v[134:135], v[138:139]
	v_pk_fma_f32 v[196:197], v[132:133], v[204:205], v[196:197] neg_lo:[0,0,1] neg_hi:[0,0,1]
	v_pk_fma_f32 v[190:191], v[130:131], v[206:207], v[190:191] neg_lo:[0,0,1] neg_hi:[0,0,1]
	v_pk_mul_f32 v[130:131], v[130:131], v[138:139]
	v_pk_mul_f32 v[132:133], v[132:133], v[140:141]
	s_nop 0
	v_pk_fma_f32 v[136:137], v[136:137], v[204:205], v[132:133]
	v_pk_fma_f32 v[132:133], v[134:135], v[206:207], v[130:131]
	v_cvt_pk_bf16_f32 v130, v190, v191
	v_cvt_pk_bf16_f32 v131, v196, v197
	v_cvt_pk_bf16_f32 v132, v132, v133
	v_cvt_pk_bf16_f32 v133, v136, v137
	global_store_dwordx4 v[188:189], v[130:133], off offset:64
	s_nop 1
	v_fmamk_f32 v130, v248, 0x3a800000, v227
	s_nop 0
	v_rsq_f32_e32 v130, v130
	s_nop 0
	v_mov_b32_e32 v188, v130
	global_load_dwordx4 v[130:133], v[166:167], off offset:16
	global_load_dwordx4 v[134:137], v[166:167], off
	s_waitcnt vmcnt(1)
	v_pk_fma_f32 v[130:131], v[112:113], v[188:189], v[130:131] op_sel_hi:[1,0,1]
	s_waitcnt vmcnt(0)
	v_pk_fma_f32 v[190:191], v[116:117], v[188:189], v[134:135] op_sel_hi:[1,0,1]
	v_pk_fma_f32 v[212:213], v[118:119], v[188:189], v[136:137] op_sel_hi:[1,0,1]
	v_pk_mul_f32 v[136:137], v[190:191], v[190:191]
	v_pk_mul_f32 v[134:135], v[212:213], v[212:213]
	v_pk_fma_f32 v[132:133], v[114:115], v[188:189], v[132:133] op_sel_hi:[1,0,1]
	v_pk_mov_b32 v[138:139], v[136:137], v[134:135] op_sel:[1,0]
	v_mov_b32_e32 v137, v135
	v_pk_add_f32 v[134:135], v[138:139], v[136:137]
	v_pk_mul_f32 v[136:137], v[130:131], v[130:131]
	v_pk_add_f32 v[196:197], v[134:135], v[134:135] op_sel_hi:[0,1]
	v_pk_mul_f32 v[134:135], v[132:133], v[132:133]
	s_nop 0
	v_pk_mov_b32 v[138:139], v[136:137], v[134:135] op_sel:[1,0]
	v_mov_b32_e32 v137, v135
	v_pk_add_f32 v[134:135], v[138:139], v[136:137]
	s_nop 0
	v_pk_add_f32 v[206:207], v[134:135], v[134:135] op_sel_hi:[0,1]
	global_load_dwordx4 v[134:137], v[166:167], off offset:528
	global_load_dwordx4 v[138:141], v[166:167], off offset:512
	s_waitcnt vmcnt(1)
	v_pk_fma_f32 v[198:199], v[50:51], v[188:189], v[136:137] op_sel_hi:[1,0,1]
	s_waitcnt vmcnt(0)
	v_pk_fma_f32 v[210:211], v[52:53], v[188:189], v[138:139] op_sel_hi:[1,0,1]
	v_pk_fma_f32 v[208:209], v[54:55], v[188:189], v[140:141] op_sel_hi:[1,0,1]
	v_mul_f32_e32 v138, v210, v210
	v_pk_fma_f32 v[138:139], v[210:211], v[210:211], v[138:139] op_sel_hi:[1,1,0]
	v_pk_fma_f32 v[204:205], v[48:49], v[188:189], v[134:135] op_sel_hi:[1,0,1]
	v_mul_f32_e32 v138, v208, v208
	v_pk_fma_f32 v[140:141], v[208:209], v[208:209], v[138:139] op_sel_hi:[1,1,0]
	v_mul_f32_e32 v138, v204, v204
	v_mul_f32_e32 v140, v205, v205
	v_mul_f32_e32 v196, v198, v198
	v_mul_f32_e32 v206, v199, v199
	v_pk_add_f32 v[134:135], v[138:139], v[140:141]
	v_pk_add_f32 v[136:137], v[196:197], v[206:207]
	s_nop 0
	v_pk_add_f32 v[134:135], v[134:135], v[136:137]
	s_nop 0
	v_add_f32_e32 v134, v134, v135
	ds_bpermute_b32 v135, v246, v134
	s_waitcnt lgkmcnt(0)
	v_add_f32_e32 v134, v134, v135
	ds_bpermute_b32 v135, v247, v134
	s_waitcnt lgkmcnt(0)
; __device__ __forceinline__ unsigned pk_bf16(float lo, float hi) { f32x2 v = {lo, hi}; bf16x2_t b = __builtin_convertvector(v, bf16x2_t); return __builtin_bit_cast(unsigned, b); }
;     __device__ __forceinline__ void operator()(const f32x4 (&acc)[2][2][4][2], const Unit& u, int wr, int wc, int fr, int fq) const {
;     ...
;                     const int row = row0 + ai * HALF + m * 16; const int t = row & 16383;
;                     const float rv = rsqrtf(rowss[row] * (1.0f / 1024.0f) + 1e-6f);
;                     float ss = 0.f; f32x4 hv[2][2];
; #pragma unroll
;                     for (int bj = 0; bj < 2; ++bj)
; #pragma unroll
;                         for (int n = 0; n < 2; ++n) { const f32x4 v = acc[ai][bj][m][n] * rv + *(const f32x4*)(bp + bj * HALF + 4 * n); hv[bj][n] = v; ss += (v[0] * v[0] + v[1] * v[1]) + (v[2] * v[2] + v[3] * v[3]); }
;                     ss += __shfl_xor(ss, 16); ss += __shfl_xor(ss, 32);
;                     const float rinv = rsqrtf(ss * (1.0f / 64.0f) + 1e-6f) * osc;
; #pragma unroll
;                     for (int bj = 0; bj < 2; ++bj) {
;                         const int pos = bj == 0 ? (t >> 6) : (t & 63);
;                         const f32x4 c = *(const f32x4*)(ropec + pos * 16 + 4 * fqo), s = *(const f32x4*)(ropes + pos * 16 + 4 * fqo);
;                         const f32x4 x1 = hv[bj][0] * rinv * *(const f32x4*)(gw + 32 * bj), x2 = hv[bj][1] * rinv * *(const f32x4*)(gw + 32 * bj + 16);
;                         const f32x4 o1 = x1 * c - x2 * s, o2 = x2 * c + x1 * s;
;                         u32x4 w; w.x = pk_bf16(o1[0], o1[1]); w.y = pk_bf16(o1[2], o1[3]); w.z = pk_bf16(o2[0], o2[1]); w.w = pk_bf16(o2[2], o2[3]);
;                         *(u32x4*)(base + (size_t)row * pitch + 32 * bj) = w;
;                     }
	v_add_f32_e32 v134, v134, v135
	v_fmamk_f32 v134, v134, 0x3c800000, v227
	s_nop 0
	v_rsq_f32_e32 v134, v134
	s_nop 0
	v_mul_f32_e32 v206, v245, v134
	v_mad_i64_i32 v[134:135], s[4:5], s0, v243, 0
	v_lshl_add_u64 v[196:197], v[134:135], 1, v[170:171]
	global_load_dwordx4 v[134:137], v[200:201], off
	global_load_dwordx4 v[138:141], v[202:203], off
	v_pk_mul_f32 v[214:215], v[190:191], v[206:207] op_sel_hi:[1,0]
	global_load_dwordx4 v[188:191], v[168:169], off
	v_pk_mul_f32 v[212:213], v[212:213], v[206:207] op_sel_hi:[1,0]
	v_pk_mul_f32 v[198:199], v[198:199], v[206:207] op_sel_hi:[1,0]
	s_waitcnt vmcnt(0)
	v_pk_mul_f32 v[188:189], v[188:189], v[214:215]
	v_pk_mul_f32 v[190:191], v[190:191], v[212:213]
	v_pk_mul_f32 v[212:213], v[130:131], v[206:207] op_sel_hi:[1,0]
	v_pk_mul_f32 v[214:215], v[132:133], v[206:207] op_sel_hi:[1,0]
	global_load_dwordx4 v[130:133], v[168:169], off offset:64
	s_waitcnt vmcnt(0)
	v_pk_mul_f32 v[132:133], v[132:133], v[214:215]
	v_pk_mul_f32 v[130:131], v[130:131], v[212:213]
	v_pk_mul_f32 v[214:215], v[140:141], v[132:133]
	v_pk_mul_f32 v[212:213], v[138:139], v[130:131]
	v_pk_mul_f32 v[130:131], v[134:135], v[130:131]
	v_pk_mul_f32 v[132:133], v[136:137], v[132:133]
	v_pk_fma_f32 v[214:215], v[136:137], v[190:191], v[214:215] neg_lo:[0,0,1] neg_hi:[0,0,1]
	v_pk_fma_f32 v[212:213], v[134:135], v[188:189], v[212:213] neg_lo:[0,0,1] neg_hi:[0,0,1]
	v_pk_fma_f32 v[134:135], v[140:141], v[190:191], v[132:133]
	v_pk_fma_f32 v[132:133], v[138:139], v[188:189], v[130:131]
	v_cvt_pk_bf16_f32 v130, v212, v213
	v_cvt_pk_bf16_f32 v131, v214, v215
	v_cvt_pk_bf16_f32 v132, v132, v133
	v_cvt_pk_bf16_f32 v133, v134, v135
	global_store_dwordx4 v[196:197], v[130:133], off
	v_pk_mul_f32 v[212:213], v[208:209], v[206:207] op_sel_hi:[1,0]
	v_pk_mul_f32 v[214:215], v[210:211], v[206:207] op_sel_hi:[1,0]
	global_load_dwordx4 v[208:211], v[168:169], off offset:128
	v_lshl_add_u64 v[138:139], s[82:83], 0, v[186:187]
	v_lshl_add_u64 v[140:141], s[84:85], 0, v[186:187]
	v_lshl_add_u64 v[188:189], v[138:139], 0, v[128:129]
	v_lshl_add_u64 v[190:191], v[140:141], 0, v[128:129]
	global_load_dwordx4 v[134:137], v[188:189], off
	global_load_dwordx4 v[130:133], v[190:191], off
	s_waitcnt vmcnt(2)
	v_pk_mul_f32 v[210:211], v[210:211], v[212:213]
	v_pk_mul_f32 v[212:213], v[204:205], v[206:207] op_sel_hi:[1,0]
	global_load_dwordx4 v[204:207], v[168:169], off offset:192
	v_pk_mul_f32 v[208:209], v[208:209], v[214:215]
	s_waitcnt vmcnt(0)
	v_pk_mul_f32 v[198:199], v[206:207], v[198:199]
	v_pk_mul_f32 v[204:205], v[204:205], v[212:213]
	v_pk_mul_f32 v[212:213], v[132:133], v[198:199]
	v_pk_mul_f32 v[206:207], v[130:131], v[204:205]
	v_pk_fma_f32 v[212:213], v[136:137], v[210:211], v[212:213] neg_lo:[0,0,1] neg_hi:[0,0,1]
	v_pk_fma_f32 v[206:207], v[134:135], v[208:209], v[206:207] neg_lo:[0,0,1] neg_hi:[0,0,1]
	v_pk_mul_f32 v[134:135], v[134:135], v[204:205]
	v_pk_mul_f32 v[136:137], v[136:137], v[198:199]
	s_nop 0
	v_pk_fma_f32 v[136:137], v[132:133], v[210:211], v[136:137]
	v_pk_fma_f32 v[132:133], v[130:131], v[208:209], v[134:135]
	v_cvt_pk_bf16_f32 v130, v206, v207
	v_cvt_pk_bf16_f32 v131, v212, v213
	v_cvt_pk_bf16_f32 v132, v132, v133
	v_cvt_pk_bf16_f32 v133, v136, v137
	global_store_dwordx4 v[196:197], v[130:133], off offset:64
	s_nop 1
	v_fmamk_f32 v130, v249, 0x3a800000, v227
	s_nop 0
	v_rsq_f32_e32 v130, v130
	s_nop 0
	v_mov_b32_e32 v196, v130
	global_load_dwordx4 v[130:133], v[166:167], off offset:16
	global_load_dwordx4 v[134:137], v[166:167], off
	s_waitcnt vmcnt(1)
	v_pk_fma_f32 v[216:217], v[104:105], v[196:197], v[130:131] op_sel_hi:[1,0,1]
	s_waitcnt vmcnt(0)
	v_pk_fma_f32 v[198:199], v[108:109], v[196:197], v[134:135] op_sel_hi:[1,0,1]
	v_pk_fma_f32 v[220:221], v[110:111], v[196:197], v[136:137] op_sel_hi:[1,0,1]
	v_pk_mul_f32 v[136:137], v[198:199], v[198:199]
	v_pk_mul_f32 v[134:135], v[220:221], v[220:221]
	v_pk_fma_f32 v[218:219], v[106:107], v[196:197], v[132:133] op_sel_hi:[1,0,1]
	v_pk_mov_b32 v[204:205], v[136:137], v[134:135] op_sel:[1,0]
	v_mov_b32_e32 v137, v135
	v_pk_add_f32 v[134:135], v[204:205], v[136:137]
	v_pk_mul_f32 v[130:131], v[218:219], v[218:219]
	v_pk_mul_f32 v[132:133], v[216:217], v[216:217]
	v_pk_add_f32 v[204:205], v[134:135], v[134:135] op_sel_hi:[0,1]
	v_pk_mov_b32 v[134:135], v[132:133], v[130:131] op_sel:[1,0]
	v_mov_b32_e32 v133, v131
	v_pk_add_f32 v[130:131], v[134:135], v[132:133]
	s_nop 0
	v_pk_add_f32 v[210:211], v[130:131], v[130:131] op_sel_hi:[0,1]
	global_load_dwordx4 v[130:133], v[166:167], off offset:528
	global_load_dwordx4 v[134:137], v[166:167], off offset:512
	s_waitcnt vmcnt(1)
	v_pk_fma_f32 v[206:207], v[42:43], v[196:197], v[132:133] op_sel_hi:[1,0,1]
	s_waitcnt vmcnt(0)
	v_pk_fma_f32 v[214:215], v[44:45], v[196:197], v[134:135] op_sel_hi:[1,0,1]
	v_pk_fma_f32 v[212:213], v[46:47], v[196:197], v[136:137] op_sel_hi:[1,0,1]
	v_mul_f32_e32 v134, v214, v214
	v_pk_fma_f32 v[134:135], v[214:215], v[214:215], v[134:135] op_sel_hi:[1,1,0]
	v_pk_fma_f32 v[208:209], v[40:41], v[196:197], v[130:131] op_sel_hi:[1,0,1]
	v_mul_f32_e32 v134, v212, v212
	v_pk_fma_f32 v[136:137], v[212:213], v[212:213], v[134:135] op_sel_hi:[1,1,0]
	v_mul_f32_e32 v134, v208, v208
	v_mul_f32_e32 v136, v209, v209
	v_mul_f32_e32 v204, v206, v206
	v_mul_f32_e32 v210, v207, v207
	v_pk_add_f32 v[130:131], v[134:135], v[136:137]
	v_pk_add_f32 v[132:133], v[204:205], v[210:211]
	s_nop 0
	v_pk_add_f32 v[130:131], v[130:131], v[132:133]
	s_nop 0
	v_add_f32_e32 v130, v130, v131
	ds_bpermute_b32 v131, v246, v130
	s_waitcnt lgkmcnt(0)
	v_add_f32_e32 v130, v130, v131
	ds_bpermute_b32 v131, v247, v130
	s_waitcnt lgkmcnt(0)
; __device__ __forceinline__ unsigned pk_bf16(float lo, float hi) { f32x2 v = {lo, hi}; bf16x2_t b = __builtin_convertvector(v, bf16x2_t); return __builtin_bit_cast(unsigned, b); }
;     __device__ __forceinline__ void operator()(const f32x4 (&acc)[2][2][4][2], const Unit& u, int wr, int wc, int fr, int fq) const {
;     ...
;                     const int row = row0 + ai * HALF + m * 16; const int t = row & 16383;
;                     const float rv = rsqrtf(rowss[row] * (1.0f / 1024.0f) + 1e-6f);
;                     float ss = 0.f; f32x4 hv[2][2];
; #pragma unroll
;                     for (int bj = 0; bj < 2; ++bj)
; #pragma unroll
;                         for (int n = 0; n < 2; ++n) { const f32x4 v = acc[ai][bj][m][n] * rv + *(const f32x4*)(bp + bj * HALF + 4 * n); hv[bj][n] = v; ss += (v[0] * v[0] + v[1] * v[1]) + (v[2] * v[2] + v[3] * v[3]); }
;                     ss += __shfl_xor(ss, 16); ss += __shfl_xor(ss, 32);
;                     const float rinv = rsqrtf(ss * (1.0f / 64.0f) + 1e-6f) * osc;
; #pragma unroll
;                     for (int bj = 0; bj < 2; ++bj) {
;                         const int pos = bj == 0 ? (t >> 6) : (t & 63);
;                         const f32x4 c = *(const f32x4*)(ropec + pos * 16 + 4 * fqo), s = *(const f32x4*)(ropes + pos * 16 + 4 * fqo);
;                         const f32x4 x1 = hv[bj][0] * rinv * *(const f32x4*)(gw + 32 * bj), x2 = hv[bj][1] * rinv * *(const f32x4*)(gw + 32 * bj + 16);
;                         const f32x4 o1 = x1 * c - x2 * s, o2 = x2 * c + x1 * s;
;                         u32x4 w; w.x = pk_bf16(o1[0], o1[1]); w.y = pk_bf16(o1[2], o1[3]); w.z = pk_bf16(o2[0], o2[1]); w.w = pk_bf16(o2[2], o2[3]);
;                         *(u32x4*)(base + (size_t)row * pitch + 32 * bj) = w;
;                     }
	v_add_f32_e32 v130, v130, v131
	v_fmamk_f32 v130, v130, 0x3c800000, v227
	s_nop 0
	v_rsq_f32_e32 v130, v130
	s_nop 0
	v_mul_f32_e32 v210, v245, v130
	v_mad_i64_i32 v[130:131], s[4:5], s0, v242, 0
	v_lshl_add_u64 v[204:205], v[130:131], 1, v[170:171]
	global_load_dwordx4 v[134:137], v[200:201], off
	global_load_dwordx4 v[130:133], v[202:203], off
	v_pk_mul_f32 v[222:223], v[198:199], v[210:211] op_sel_hi:[1,0]
	global_load_dwordx4 v[196:199], v[168:169], off
	v_pk_mul_f32 v[220:221], v[220:221], v[210:211] op_sel_hi:[1,0]
	v_pk_mul_f32 v[216:217], v[216:217], v[210:211] op_sel_hi:[1,0]
	v_pk_mul_f32 v[218:219], v[218:219], v[210:211] op_sel_hi:[1,0]
	s_waitcnt vmcnt(0)
	v_pk_mul_f32 v[196:197], v[196:197], v[222:223]
	v_pk_mul_f32 v[198:199], v[198:199], v[220:221]
	global_load_dwordx4 v[220:223], v[168:169], off offset:64
	s_waitcnt vmcnt(0)
	v_pk_mul_f32 v[218:219], v[222:223], v[218:219]
	v_pk_mul_f32 v[216:217], v[220:221], v[216:217]
	v_pk_mul_f32 v[222:223], v[132:133], v[218:219]
	v_pk_mul_f32 v[220:221], v[130:131], v[216:217]
	v_pk_fma_f32 v[222:223], v[136:137], v[198:199], v[222:223] neg_lo:[0,0,1] neg_hi:[0,0,1]
	v_pk_fma_f32 v[220:221], v[134:135], v[196:197], v[220:221] neg_lo:[0,0,1] neg_hi:[0,0,1]
	v_pk_mul_f32 v[134:135], v[134:135], v[216:217]
	v_pk_mul_f32 v[136:137], v[136:137], v[218:219]
	v_pk_mul_f32 v[216:217], v[212:213], v[210:211] op_sel_hi:[1,0]
	v_pk_fma_f32 v[136:137], v[132:133], v[198:199], v[136:137]
	v_pk_fma_f32 v[132:133], v[130:131], v[196:197], v[134:135]
	v_cvt_pk_bf16_f32 v130, v220, v221
	v_cvt_pk_bf16_f32 v131, v222, v223
	v_cvt_pk_bf16_f32 v132, v132, v133
	v_cvt_pk_bf16_f32 v133, v136, v137
	global_store_dwordx4 v[204:205], v[130:133], off
	v_pk_mul_f32 v[218:219], v[214:215], v[210:211] op_sel_hi:[1,0]
	global_load_dwordx4 v[212:215], v[168:169], off offset:128
	v_lshl_add_u64 v[196:197], v[138:139], 0, v[158:159]
	v_lshl_add_u64 v[198:199], v[140:141], 0, v[158:159]
	global_load_dwordx4 v[130:133], v[196:197], off
	global_load_dwordx4 v[134:137], v[198:199], off
	v_add_u32_e32 v159, 0x80, v162
	s_waitcnt vmcnt(2)
	v_pk_mul_f32 v[214:215], v[214:215], v[216:217]
	v_pk_mul_f32 v[216:217], v[208:209], v[210:211] op_sel_hi:[1,0]
	v_pk_mul_f32 v[210:211], v[206:207], v[210:211] op_sel_hi:[1,0]
	global_load_dwordx4 v[206:209], v[168:169], off offset:192
	v_pk_mul_f32 v[212:213], v[212:213], v[218:219]
	s_waitcnt vmcnt(0)
	v_pk_mul_f32 v[208:209], v[208:209], v[210:211]
	v_pk_mul_f32 v[206:207], v[206:207], v[216:217]
	v_pk_mul_f32 v[216:217], v[136:137], v[208:209]
	v_pk_mul_f32 v[210:211], v[134:135], v[206:207]
	v_pk_fma_f32 v[216:217], v[132:133], v[214:215], v[216:217] neg_lo:[0,0,1] neg_hi:[0,0,1]
	v_pk_fma_f32 v[210:211], v[130:131], v[212:213], v[210:211] neg_lo:[0,0,1] neg_hi:[0,0,1]
	v_pk_mul_f32 v[130:131], v[130:131], v[206:207]
	v_pk_mul_f32 v[132:133], v[132:133], v[208:209]
	s_nop 0
	v_pk_fma_f32 v[136:137], v[136:137], v[214:215], v[132:133]
	v_pk_fma_f32 v[132:133], v[134:135], v[212:213], v[130:131]
	v_cvt_pk_bf16_f32 v130, v210, v211
	v_cvt_pk_bf16_f32 v131, v216, v217
	v_cvt_pk_bf16_f32 v132, v132, v133
	v_cvt_pk_bf16_f32 v133, v136, v137
	global_store_dwordx4 v[204:205], v[130:133], off offset:64
	s_nop 1
	v_fmamk_f32 v130, v250, 0x3a800000, v227
	s_nop 0
	v_rsq_f32_e32 v130, v130
	s_nop 0
	v_mov_b32_e32 v204, v130
	global_load_dwordx4 v[130:133], v[166:167], off offset:16
	global_load_dwordx4 v[134:137], v[166:167], off
	s_waitcnt vmcnt(1)
	v_pk_fma_f32 v[216:217], v[96:97], v[204:205], v[130:131] op_sel_hi:[1,0,1]
	s_waitcnt vmcnt(0)
	v_pk_fma_f32 v[220:221], v[100:101], v[204:205], v[134:135] op_sel_hi:[1,0,1]
	v_pk_fma_f32 v[222:223], v[102:103], v[204:205], v[136:137] op_sel_hi:[1,0,1]
	v_pk_mul_f32 v[136:137], v[220:221], v[220:221]
	v_pk_mul_f32 v[134:135], v[222:223], v[222:223]
	v_pk_fma_f32 v[218:219], v[98:99], v[204:205], v[132:133] op_sel_hi:[1,0,1]
	v_pk_mov_b32 v[206:207], v[136:137], v[134:135] op_sel:[1,0]
	v_mov_b32_e32 v137, v135
	v_pk_add_f32 v[134:135], v[206:207], v[136:137]
	v_pk_mul_f32 v[130:131], v[218:219], v[218:219]
	v_pk_mul_f32 v[132:133], v[216:217], v[216:217]
	v_pk_add_f32 v[210:211], v[134:135], v[134:135] op_sel_hi:[0,1]
	v_pk_mov_b32 v[134:135], v[132:133], v[130:131] op_sel:[1,0]
	v_mov_b32_e32 v133, v131
	v_pk_add_f32 v[130:131], v[134:135], v[132:133]
	s_nop 0
	v_pk_add_f32 v[224:225], v[130:131], v[130:131] op_sel_hi:[0,1]
	global_load_dwordx4 v[130:133], v[166:167], off offset:528
	global_load_dwordx4 v[134:137], v[166:167], off offset:512
	s_waitcnt vmcnt(1)
	v_pk_fma_f32 v[206:207], v[34:35], v[204:205], v[132:133] op_sel_hi:[1,0,1]
	s_waitcnt vmcnt(0)
	v_pk_fma_f32 v[214:215], v[36:37], v[204:205], v[134:135] op_sel_hi:[1,0,1]
	v_pk_fma_f32 v[212:213], v[38:39], v[204:205], v[136:137] op_sel_hi:[1,0,1]
	v_mul_f32_e32 v134, v214, v214
	v_pk_fma_f32 v[134:135], v[214:215], v[214:215], v[134:135] op_sel_hi:[1,1,0]
	v_pk_fma_f32 v[208:209], v[32:33], v[204:205], v[130:131] op_sel_hi:[1,0,1]
	v_mul_f32_e32 v134, v212, v212
	v_pk_fma_f32 v[136:137], v[212:213], v[212:213], v[134:135] op_sel_hi:[1,1,0]
	v_mul_f32_e32 v134, v208, v208
	v_mul_f32_e32 v136, v209, v209
	v_mul_f32_e32 v210, v206, v206
	v_mul_f32_e32 v224, v207, v207
	v_pk_add_f32 v[130:131], v[134:135], v[136:137]
	v_pk_add_f32 v[132:133], v[210:211], v[224:225]
	s_nop 0
	v_pk_add_f32 v[130:131], v[130:131], v[132:133]
	s_nop 0
	v_add_f32_e32 v130, v130, v131
	ds_bpermute_b32 v131, v246, v130
	s_waitcnt lgkmcnt(0)
	v_add_f32_e32 v130, v130, v131
	ds_bpermute_b32 v131, v247, v130
	s_waitcnt lgkmcnt(0)
; __device__ __forceinline__ unsigned pk_bf16(float lo, float hi) { f32x2 v = {lo, hi}; bf16x2_t b = __builtin_convertvector(v, bf16x2_t); return __builtin_bit_cast(unsigned, b); }
;     __device__ __forceinline__ void operator()(const f32x4 (&acc)[2][2][4][2], const Unit& u, int wr, int wc, int fr, int fq) const {
;     ...
;                     const int row = row0 + ai * HALF + m * 16; const int t = row & 16383;
;                     const float rv = rsqrtf(rowss[row] * (1.0f / 1024.0f) + 1e-6f);
;                     float ss = 0.f; f32x4 hv[2][2];
; #pragma unroll
;                     for (int bj = 0; bj < 2; ++bj)
; #pragma unroll
;                         for (int n = 0; n < 2; ++n) { const f32x4 v = acc[ai][bj][m][n] * rv + *(const f32x4*)(bp + bj * HALF + 4 * n); hv[bj][n] = v; ss += (v[0] * v[0] + v[1] * v[1]) + (v[2] * v[2] + v[3] * v[3]); }
;                     ss += __shfl_xor(ss, 16); ss += __shfl_xor(ss, 32);
;                     const float rinv = rsqrtf(ss * (1.0f / 64.0f) + 1e-6f) * osc;
; #pragma unroll
;                     for (int bj = 0; bj < 2; ++bj) {
;                         const int pos = bj == 0 ? (t >> 6) : (t & 63);
;                         const f32x4 c = *(const f32x4*)(ropec + pos * 16 + 4 * fqo), s = *(const f32x4*)(ropes + pos * 16 + 4 * fqo);
;                         const f32x4 x1 = hv[bj][0] * rinv * *(const f32x4*)(gw + 32 * bj), x2 = hv[bj][1] * rinv * *(const f32x4*)(gw + 32 * bj + 16);
;                         const f32x4 o1 = x1 * c - x2 * s, o2 = x2 * c + x1 * s;
;                         u32x4 w; w.x = pk_bf16(o1[0], o1[1]); w.y = pk_bf16(o1[2], o1[3]); w.z = pk_bf16(o2[0], o2[1]); w.w = pk_bf16(o2[2], o2[3]);
;                         *(u32x4*)(base + (size_t)row * pitch + 32 * bj) = w;
;                     }
	v_add_f32_e32 v130, v130, v131
	v_fmamk_f32 v130, v130, 0x3c800000, v227
	s_nop 0
	v_rsq_f32_e32 v130, v130
	s_nop 0
	v_mul_f32_e32 v210, v245, v130
	v_mad_i64_i32 v[130:131], s[4:5], s0, v241, 0
	v_lshl_add_u64 v[204:205], v[130:131], 1, v[170:171]
	global_load_dwordx4 v[134:137], v[200:201], off
	global_load_dwordx4 v[130:133], v[202:203], off
	v_pk_mul_f32 v[222:223], v[222:223], v[210:211] op_sel_hi:[1,0]
	global_load_dwordx4 v[200:203], v[168:169], off
	v_pk_mul_f32 v[220:221], v[220:221], v[210:211] op_sel_hi:[1,0]
	v_pk_mul_f32 v[216:217], v[216:217], v[210:211] op_sel_hi:[1,0]
	v_pk_mul_f32 v[218:219], v[218:219], v[210:211] op_sel_hi:[1,0]
	v_pk_mul_f32 v[212:213], v[212:213], v[210:211] op_sel_hi:[1,0]
	v_pk_mul_f32 v[214:215], v[214:215], v[210:211] op_sel_hi:[1,0]
	v_pk_mul_f32 v[208:209], v[208:209], v[210:211] op_sel_hi:[1,0]
	v_pk_mul_f32 v[206:207], v[206:207], v[210:211] op_sel_hi:[1,0]
	s_waitcnt vmcnt(0)
	v_pk_mul_f32 v[200:201], v[200:201], v[220:221]
	v_pk_mul_f32 v[202:203], v[202:203], v[222:223]
	global_load_dwordx4 v[220:223], v[168:169], off offset:64
	s_waitcnt vmcnt(0)
	v_pk_mul_f32 v[218:219], v[222:223], v[218:219]
	v_pk_mul_f32 v[216:217], v[220:221], v[216:217]
	v_pk_mul_f32 v[222:223], v[132:133], v[218:219]
	v_pk_mul_f32 v[220:221], v[130:131], v[216:217]
	v_pk_fma_f32 v[222:223], v[136:137], v[202:203], v[222:223] neg_lo:[0,0,1] neg_hi:[0,0,1]
	v_pk_fma_f32 v[220:221], v[134:135], v[200:201], v[220:221] neg_lo:[0,0,1] neg_hi:[0,0,1]
	v_pk_mul_f32 v[134:135], v[134:135], v[216:217]
	v_pk_mul_f32 v[136:137], v[136:137], v[218:219]
	s_nop 0
	v_pk_fma_f32 v[136:137], v[132:133], v[202:203], v[136:137]
	v_pk_fma_f32 v[132:133], v[130:131], v[200:201], v[134:135]
	v_cvt_pk_bf16_f32 v130, v220, v221
	v_cvt_pk_bf16_f32 v131, v222, v223
	v_cvt_pk_bf16_f32 v132, v132, v133
	v_cvt_pk_bf16_f32 v133, v136, v137
	global_store_dwordx4 v[204:205], v[130:133], off
	v_lshl_add_u64 v[200:201], v[138:139], 0, v[160:161]
	v_lshl_add_u64 v[202:203], v[140:141], 0, v[160:161]
	global_load_dwordx4 v[138:141], v[168:169], off offset:128
	global_load_dwordx4 v[130:133], v[200:201], off
	global_load_dwordx4 v[134:137], v[202:203], off
	s_waitcnt vmcnt(2)
	v_pk_mul_f32 v[214:215], v[138:139], v[214:215]
	v_pk_mul_f32 v[212:213], v[140:141], v[212:213]
	global_load_dwordx4 v[138:141], v[168:169], off offset:192
	s_waitcnt vmcnt(0)
	v_pk_mul_f32 v[140:141], v[140:141], v[206:207]
	v_pk_mul_f32 v[138:139], v[138:139], v[208:209]
	v_pk_mul_f32 v[208:209], v[136:137], v[140:141]
	v_pk_mul_f32 v[206:207], v[134:135], v[138:139]
	v_pk_fma_f32 v[208:209], v[132:133], v[212:213], v[208:209] neg_lo:[0,0,1] neg_hi:[0,0,1]
	v_pk_fma_f32 v[206:207], v[130:131], v[214:215], v[206:207] neg_lo:[0,0,1] neg_hi:[0,0,1]
	v_pk_mul_f32 v[130:131], v[130:131], v[138:139]
	v_pk_mul_f32 v[132:133], v[132:133], v[140:141]
	s_nop 0
	v_pk_fma_f32 v[136:137], v[136:137], v[212:213], v[132:133]
	v_pk_fma_f32 v[132:133], v[134:135], v[214:215], v[130:131]
	v_cvt_pk_bf16_f32 v130, v206, v207
	v_cvt_pk_bf16_f32 v131, v208, v209
	v_cvt_pk_bf16_f32 v132, v132, v133
	v_cvt_pk_bf16_f32 v133, v136, v137
	global_store_dwordx4 v[204:205], v[130:133], off offset:64
	s_nop 1
	v_fmamk_f32 v130, v251, 0x3a800000, v227
	s_nop 0
	v_rsq_f32_e32 v130, v130
	s_nop 0
	v_mov_b32_e32 v204, v130
	global_load_dwordx4 v[130:133], v[166:167], off offset:16
	global_load_dwordx4 v[134:137], v[166:167], off
	s_waitcnt vmcnt(1)
	v_pk_fma_f32 v[140:141], v[90:91], v[204:205], v[132:133] op_sel_hi:[1,0,1]
	s_waitcnt vmcnt(0)
	v_pk_fma_f32 v[218:219], v[92:93], v[204:205], v[134:135] op_sel_hi:[1,0,1]
	v_pk_fma_f32 v[220:221], v[94:95], v[204:205], v[136:137] op_sel_hi:[1,0,1]
	v_pk_mul_f32 v[136:137], v[218:219], v[218:219]
	v_pk_mul_f32 v[134:135], v[220:221], v[220:221]
	s_nop 0
	v_pk_mov_b32 v[138:139], v[136:137], v[134:135] op_sel:[1,0]
	v_mov_b32_e32 v137, v135
	v_pk_add_f32 v[134:135], v[138:139], v[136:137]
	v_pk_fma_f32 v[138:139], v[88:89], v[204:205], v[130:131] op_sel_hi:[1,0,1]
	v_pk_mul_f32 v[130:131], v[140:141], v[140:141]
	v_pk_mul_f32 v[132:133], v[138:139], v[138:139]
	v_pk_add_f32 v[206:207], v[134:135], v[134:135] op_sel_hi:[0,1]
	v_pk_mov_b32 v[134:135], v[132:133], v[130:131] op_sel:[1,0]
	v_mov_b32_e32 v133, v131
	v_pk_add_f32 v[130:131], v[134:135], v[132:133]
	s_nop 0
	v_pk_add_f32 v[216:217], v[130:131], v[130:131] op_sel_hi:[0,1]
	global_load_dwordx4 v[130:133], v[166:167], off offset:528
	global_load_dwordx4 v[134:137], v[166:167], off offset:512
	s_waitcnt vmcnt(1)
	v_pk_fma_f32 v[208:209], v[26:27], v[204:205], v[132:133] op_sel_hi:[1,0,1]
	s_waitcnt vmcnt(0)
	v_pk_fma_f32 v[214:215], v[28:29], v[204:205], v[134:135] op_sel_hi:[1,0,1]
	v_pk_fma_f32 v[212:213], v[30:31], v[204:205], v[136:137] op_sel_hi:[1,0,1]
	v_mul_f32_e32 v134, v214, v214
	v_pk_fma_f32 v[134:135], v[214:215], v[214:215], v[134:135] op_sel_hi:[1,1,0]
	v_pk_fma_f32 v[210:211], v[24:25], v[204:205], v[130:131] op_sel_hi:[1,0,1]
	v_mul_f32_e32 v134, v212, v212
	v_pk_fma_f32 v[136:137], v[212:213], v[212:213], v[134:135] op_sel_hi:[1,1,0]
	v_mul_f32_e32 v134, v210, v210
	v_mul_f32_e32 v136, v211, v211
	v_mul_f32_e32 v206, v208, v208
	v_mul_f32_e32 v216, v209, v209
	v_pk_add_f32 v[130:131], v[134:135], v[136:137]
	v_pk_add_f32 v[132:133], v[206:207], v[216:217]
	s_nop 0
	v_pk_add_f32 v[130:131], v[130:131], v[132:133]
	s_nop 0
	v_add_f32_e32 v130, v130, v131
	ds_bpermute_b32 v131, v246, v130
	s_waitcnt lgkmcnt(0)
	v_add_f32_e32 v130, v130, v131
	ds_bpermute_b32 v131, v247, v130
	s_waitcnt lgkmcnt(0)
; __device__ __forceinline__ unsigned pk_bf16(float lo, float hi) { f32x2 v = {lo, hi}; bf16x2_t b = __builtin_convertvector(v, bf16x2_t); return __builtin_bit_cast(unsigned, b); }
;     __device__ __forceinline__ void operator()(const f32x4 (&acc)[2][2][4][2], const Unit& u, int wr, int wc, int fr, int fq) const {
;     ...
;                     const int row = row0 + ai * HALF + m * 16; const int t = row & 16383;
;                     const float rv = rsqrtf(rowss[row] * (1.0f / 1024.0f) + 1e-6f);
;                     float ss = 0.f; f32x4 hv[2][2];
; #pragma unroll
;                     for (int bj = 0; bj < 2; ++bj)
; #pragma unroll
;                         for (int n = 0; n < 2; ++n) { const f32x4 v = acc[ai][bj][m][n] * rv + *(const f32x4*)(bp + bj * HALF + 4 * n); hv[bj][n] = v; ss += (v[0] * v[0] + v[1] * v[1]) + (v[2] * v[2] + v[3] * v[3]); }
;                     ss += __shfl_xor(ss, 16); ss += __shfl_xor(ss, 32);
;                     const float rinv = rsqrtf(ss * (1.0f / 64.0f) + 1e-6f) * osc;
; #pragma unroll
;                     for (int bj = 0; bj < 2; ++bj) {
;                         const int pos = bj == 0 ? (t >> 6) : (t & 63);
;                         const f32x4 c = *(const f32x4*)(ropec + pos * 16 + 4 * fqo), s = *(const f32x4*)(ropes + pos * 16 + 4 * fqo);
;                         const f32x4 x1 = hv[bj][0] * rinv * *(const f32x4*)(gw + 32 * bj), x2 = hv[bj][1] * rinv * *(const f32x4*)(gw + 32 * bj + 16);
;                         const f32x4 o1 = x1 * c - x2 * s, o2 = x2 * c + x1 * s;
;                         u32x4 w; w.x = pk_bf16(o1[0], o1[1]); w.y = pk_bf16(o1[2], o1[3]); w.z = pk_bf16(o2[0], o2[1]); w.w = pk_bf16(o2[2], o2[3]);
;                         *(u32x4*)(base + (size_t)row * pitch + 32 * bj) = w;
;                     }
	v_add_f32_e32 v130, v130, v131
	v_fmamk_f32 v130, v130, 0x3c800000, v227
	s_nop 0
	v_rsq_f32_e32 v130, v130
	s_nop 0
	v_mul_f32_e32 v216, v245, v130
	v_pk_mul_f32 v[222:223], v[220:221], v[216:217] op_sel_hi:[1,0]
	v_pk_mul_f32 v[224:225], v[218:219], v[216:217] op_sel_hi:[1,0]
	global_load_dwordx4 v[218:221], v[168:169], off
	v_mad_i64_i32 v[130:131], s[4:5], s0, v159, 0
	v_lshl_add_u64 v[206:207], v[130:131], 1, v[170:171]
	v_and_b32_e32 v130, 0x3fc0, v159
	v_mov_b32_e32 v131, v129
	v_lshl_add_u64 v[132:133], s[82:83], 0, v[130:131]
	v_lshl_add_u64 v[130:131], s[84:85], 0, v[130:131]
	v_lshl_add_u64 v[204:205], v[132:133], 0, v[186:187]
	v_lshl_add_u64 v[186:187], v[130:131], 0, v[186:187]
	global_load_dwordx4 v[134:137], v[204:205], off
	global_load_dwordx4 v[130:133], v[186:187], off
	v_pk_mul_f32 v[210:211], v[210:211], v[216:217] op_sel_hi:[1,0]
	v_pk_mul_f32 v[208:209], v[208:209], v[216:217] op_sel_hi:[1,0]
	v_add_u32_e32 v159, 0x90, v162
	s_waitcnt vmcnt(2)
	v_pk_mul_f32 v[218:219], v[218:219], v[224:225]
	v_pk_mul_f32 v[220:221], v[220:221], v[222:223]
	v_pk_mul_f32 v[222:223], v[138:139], v[216:217] op_sel_hi:[1,0]
	v_pk_mul_f32 v[224:225], v[140:141], v[216:217] op_sel_hi:[1,0]
	global_load_dwordx4 v[138:141], v[168:169], off offset:64
	s_waitcnt vmcnt(0)
	v_pk_mul_f32 v[140:141], v[140:141], v[224:225]
	v_pk_mul_f32 v[138:139], v[138:139], v[222:223]
	v_pk_mul_f32 v[224:225], v[132:133], v[140:141]
	v_pk_mul_f32 v[222:223], v[130:131], v[138:139]
	v_pk_fma_f32 v[224:225], v[136:137], v[220:221], v[224:225] neg_lo:[0,0,1] neg_hi:[0,0,1]
	v_pk_fma_f32 v[222:223], v[134:135], v[218:219], v[222:223] neg_lo:[0,0,1] neg_hi:[0,0,1]
	v_pk_mul_f32 v[134:135], v[134:135], v[138:139]
	v_pk_mul_f32 v[136:137], v[136:137], v[140:141]
	s_nop 0
	v_pk_fma_f32 v[136:137], v[132:133], v[220:221], v[136:137]
	v_pk_fma_f32 v[132:133], v[130:131], v[218:219], v[134:135]
	v_cvt_pk_bf16_f32 v130, v222, v223
	v_cvt_pk_bf16_f32 v131, v224, v225
	v_cvt_pk_bf16_f32 v132, v132, v133
	v_cvt_pk_bf16_f32 v133, v136, v137
	global_store_dwordx4 v[206:207], v[130:133], off
	global_load_dwordx4 v[130:133], v[192:193], off
	s_nop 0
	global_load_dwordx4 v[134:137], v[194:195], off
	global_load_dwordx4 v[138:141], v[168:169], off offset:128
	v_pk_mul_f32 v[192:193], v[212:213], v[216:217] op_sel_hi:[1,0]
	v_pk_mul_f32 v[194:195], v[214:215], v[216:217] op_sel_hi:[1,0]
	s_waitcnt vmcnt(0)
	v_pk_mul_f32 v[192:193], v[140:141], v[192:193]
	v_pk_mul_f32 v[194:195], v[138:139], v[194:195]
	global_load_dwordx4 v[138:141], v[168:169], off offset:192
	s_waitcnt vmcnt(0)
	v_pk_mul_f32 v[140:141], v[140:141], v[208:209]
	v_pk_mul_f32 v[138:139], v[138:139], v[210:211]
	v_pk_mul_f32 v[210:211], v[136:137], v[140:141]
	v_pk_mul_f32 v[208:209], v[134:135], v[138:139]
	v_pk_fma_f32 v[210:211], v[132:133], v[192:193], v[210:211] neg_lo:[0,0,1] neg_hi:[0,0,1]
	v_pk_fma_f32 v[208:209], v[130:131], v[194:195], v[208:209] neg_lo:[0,0,1] neg_hi:[0,0,1]
	v_pk_mul_f32 v[130:131], v[130:131], v[138:139]
	v_pk_mul_f32 v[132:133], v[132:133], v[140:141]
	s_nop 0
	v_pk_fma_f32 v[136:137], v[136:137], v[192:193], v[132:133]
	v_pk_fma_f32 v[132:133], v[134:135], v[194:195], v[130:131]
	v_cvt_pk_bf16_f32 v130, v208, v209
	v_cvt_pk_bf16_f32 v131, v210, v211
	v_cvt_pk_bf16_f32 v132, v132, v133
	v_cvt_pk_bf16_f32 v133, v136, v137
	global_store_dwordx4 v[206:207], v[130:133], off offset:64
	s_nop 1
	v_fmamk_f32 v130, v143, 0x3a800000, v227
	s_nop 0
	v_rsq_f32_e32 v130, v130
	s_nop 0
	v_mov_b32_e32 v192, v130
	global_load_dwordx4 v[130:133], v[166:167], off offset:16
	global_load_dwordx4 v[134:137], v[166:167], off
	s_waitcnt vmcnt(1)
	v_pk_fma_f32 v[140:141], v[82:83], v[192:193], v[132:133] op_sel_hi:[1,0,1]
	s_waitcnt vmcnt(0)
	v_pk_fma_f32 v[214:215], v[84:85], v[192:193], v[134:135] op_sel_hi:[1,0,1]
	v_pk_fma_f32 v[216:217], v[86:87], v[192:193], v[136:137] op_sel_hi:[1,0,1]
	v_pk_mul_f32 v[136:137], v[214:215], v[214:215]
	v_pk_mul_f32 v[134:135], v[216:217], v[216:217]
	s_nop 0
	v_pk_mov_b32 v[138:139], v[136:137], v[134:135] op_sel:[1,0]
	v_mov_b32_e32 v137, v135
	v_pk_add_f32 v[134:135], v[138:139], v[136:137]
	v_pk_fma_f32 v[138:139], v[80:81], v[192:193], v[130:131] op_sel_hi:[1,0,1]
	v_pk_mul_f32 v[130:131], v[140:141], v[140:141]
	v_pk_mul_f32 v[132:133], v[138:139], v[138:139]
	v_pk_add_f32 v[212:213], v[134:135], v[134:135] op_sel_hi:[0,1]
	v_pk_mov_b32 v[134:135], v[132:133], v[130:131] op_sel:[1,0]
	v_mov_b32_e32 v133, v131
	v_pk_add_f32 v[130:131], v[134:135], v[132:133]
	s_nop 0
	v_pk_add_f32 v[218:219], v[130:131], v[130:131] op_sel_hi:[0,1]
	global_load_dwordx4 v[130:133], v[166:167], off offset:528
	global_load_dwordx4 v[134:137], v[166:167], off offset:512
	s_waitcnt vmcnt(1)
	v_pk_fma_f32 v[194:195], v[18:19], v[192:193], v[132:133] op_sel_hi:[1,0,1]
	s_waitcnt vmcnt(0)
	v_pk_fma_f32 v[210:211], v[20:21], v[192:193], v[134:135] op_sel_hi:[1,0,1]
	v_pk_fma_f32 v[208:209], v[22:23], v[192:193], v[136:137] op_sel_hi:[1,0,1]
	v_mul_f32_e32 v134, v210, v210
	v_pk_fma_f32 v[134:135], v[210:211], v[210:211], v[134:135] op_sel_hi:[1,1,0]
	v_pk_fma_f32 v[206:207], v[16:17], v[192:193], v[130:131] op_sel_hi:[1,0,1]
	v_mul_f32_e32 v134, v208, v208
	v_pk_fma_f32 v[136:137], v[208:209], v[208:209], v[134:135] op_sel_hi:[1,1,0]
	v_mul_f32_e32 v134, v206, v206
	v_mul_f32_e32 v136, v207, v207
	v_mul_f32_e32 v212, v194, v194
	v_mul_f32_e32 v218, v195, v195
	v_pk_add_f32 v[130:131], v[134:135], v[136:137]
	v_pk_add_f32 v[132:133], v[212:213], v[218:219]
	s_nop 0
	v_pk_add_f32 v[130:131], v[130:131], v[132:133]
	s_nop 0
	v_add_f32_e32 v130, v130, v131
	ds_bpermute_b32 v131, v246, v130
	s_waitcnt lgkmcnt(0)
; __device__ __forceinline__ unsigned pk_bf16(float lo, float hi) { f32x2 v = {lo, hi}; bf16x2_t b = __builtin_convertvector(v, bf16x2_t); return __builtin_bit_cast(unsigned, b); }
;     __device__ __forceinline__ void operator()(const f32x4 (&acc)[2][2][4][2], const Unit& u, int wr, int wc, int fr, int fq) const {
;     ...
;                     const int row = row0 + ai * HALF + m * 16; const int t = row & 16383;
;                     const float rv = rsqrtf(rowss[row] * (1.0f / 1024.0f) + 1e-6f);
;                     float ss = 0.f; f32x4 hv[2][2];
; #pragma unroll
;                     for (int bj = 0; bj < 2; ++bj)
; #pragma unroll
;                         for (int n = 0; n < 2; ++n) { const f32x4 v = acc[ai][bj][m][n] * rv + *(const f32x4*)(bp + bj * HALF + 4 * n); hv[bj][n] = v; ss += (v[0] * v[0] + v[1] * v[1]) + (v[2] * v[2] + v[3] * v[3]); }
;                     ss += __shfl_xor(ss, 16); ss += __shfl_xor(ss, 32);
;                     const float rinv = rsqrtf(ss * (1.0f / 64.0f) + 1e-6f) * osc;
; #pragma unroll
;                     for (int bj = 0; bj < 2; ++bj) {
;                         const int pos = bj == 0 ? (t >> 6) : (t & 63);
;                         const f32x4 c = *(const f32x4*)(ropec + pos * 16 + 4 * fqo), s = *(const f32x4*)(ropes + pos * 16 + 4 * fqo);
;                         const f32x4 x1 = hv[bj][0] * rinv * *(const f32x4*)(gw + 32 * bj), x2 = hv[bj][1] * rinv * *(const f32x4*)(gw + 32 * bj + 16);
;                         const f32x4 o1 = x1 * c - x2 * s, o2 = x2 * c + x1 * s;
;                         u32x4 w; w.x = pk_bf16(o1[0], o1[1]); w.y = pk_bf16(o1[2], o1[3]); w.z = pk_bf16(o2[0], o2[1]); w.w = pk_bf16(o2[2], o2[3]);
;                         *(u32x4*)(base + (size_t)row * pitch + 32 * bj) = w;
;                     }
	v_add_f32_e32 v130, v130, v131
	ds_bpermute_b32 v131, v247, v130
	s_waitcnt lgkmcnt(0)
	v_add_f32_e32 v130, v130, v131
	v_fmamk_f32 v130, v130, 0x3c800000, v227
	s_nop 0
	v_rsq_f32_e32 v130, v130
	s_nop 0
	v_mul_f32_e32 v212, v245, v130
	v_mad_i64_i32 v[130:131], s[4:5], s0, v159, 0
	v_lshl_add_u64 v[192:193], v[130:131], 1, v[170:171]
	global_load_dwordx4 v[134:137], v[204:205], off
	global_load_dwordx4 v[130:133], v[186:187], off
	v_pk_mul_f32 v[218:219], v[216:217], v[212:213] op_sel_hi:[1,0]
	v_pk_mul_f32 v[220:221], v[214:215], v[212:213] op_sel_hi:[1,0]
	global_load_dwordx4 v[214:217], v[168:169], off
	v_pk_mul_f32 v[206:207], v[206:207], v[212:213] op_sel_hi:[1,0]
	v_pk_mul_f32 v[194:195], v[194:195], v[212:213] op_sel_hi:[1,0]
	v_add_u32_e32 v159, 0xa0, v162
	s_waitcnt vmcnt(0)
	v_pk_mul_f32 v[214:215], v[214:215], v[220:221]
	v_pk_mul_f32 v[216:217], v[216:217], v[218:219]
	v_pk_mul_f32 v[218:219], v[138:139], v[212:213] op_sel_hi:[1,0]
	v_pk_mul_f32 v[220:221], v[140:141], v[212:213] op_sel_hi:[1,0]
	global_load_dwordx4 v[138:141], v[168:169], off offset:64
	s_waitcnt vmcnt(0)
	v_pk_mul_f32 v[140:141], v[140:141], v[220:221]
	v_pk_mul_f32 v[138:139], v[138:139], v[218:219]
	v_pk_mul_f32 v[220:221], v[132:133], v[140:141]
	v_pk_mul_f32 v[218:219], v[130:131], v[138:139]
	v_pk_fma_f32 v[220:221], v[136:137], v[216:217], v[220:221] neg_lo:[0,0,1] neg_hi:[0,0,1]
	v_pk_fma_f32 v[218:219], v[134:135], v[214:215], v[218:219] neg_lo:[0,0,1] neg_hi:[0,0,1]
	v_pk_mul_f32 v[134:135], v[134:135], v[138:139]
	v_pk_mul_f32 v[136:137], v[136:137], v[140:141]
	s_nop 0
	v_pk_fma_f32 v[136:137], v[132:133], v[216:217], v[136:137]
	v_pk_fma_f32 v[132:133], v[130:131], v[214:215], v[134:135]
	v_cvt_pk_bf16_f32 v130, v218, v219
	v_cvt_pk_bf16_f32 v131, v220, v221
	v_cvt_pk_bf16_f32 v132, v132, v133
	v_cvt_pk_bf16_f32 v133, v136, v137
	global_store_dwordx4 v[192:193], v[130:133], off
	global_load_dwordx4 v[130:133], v[188:189], off
	s_nop 0
	global_load_dwordx4 v[134:137], v[190:191], off
	global_load_dwordx4 v[138:141], v[168:169], off offset:128
	v_pk_mul_f32 v[188:189], v[208:209], v[212:213] op_sel_hi:[1,0]
	v_pk_mul_f32 v[190:191], v[210:211], v[212:213] op_sel_hi:[1,0]
	s_waitcnt vmcnt(0)
	v_pk_mul_f32 v[188:189], v[140:141], v[188:189]
	v_pk_mul_f32 v[190:191], v[138:139], v[190:191]
	global_load_dwordx4 v[138:141], v[168:169], off offset:192
	s_waitcnt vmcnt(0)
	v_pk_mul_f32 v[140:141], v[140:141], v[194:195]
	v_pk_mul_f32 v[138:139], v[138:139], v[206:207]
	v_pk_mul_f32 v[206:207], v[136:137], v[140:141]
	v_pk_mul_f32 v[194:195], v[134:135], v[138:139]
	v_pk_fma_f32 v[206:207], v[132:133], v[188:189], v[206:207] neg_lo:[0,0,1] neg_hi:[0,0,1]
	v_pk_fma_f32 v[194:195], v[130:131], v[190:191], v[194:195] neg_lo:[0,0,1] neg_hi:[0,0,1]
	v_pk_mul_f32 v[130:131], v[130:131], v[138:139]
	v_pk_mul_f32 v[132:133], v[132:133], v[140:141]
	s_nop 0
	v_pk_fma_f32 v[136:137], v[136:137], v[188:189], v[132:133]
	v_pk_fma_f32 v[132:133], v[134:135], v[190:191], v[130:131]
	v_cvt_pk_bf16_f32 v130, v194, v195
	v_cvt_pk_bf16_f32 v131, v206, v207
	v_cvt_pk_bf16_f32 v132, v132, v133
	v_cvt_pk_bf16_f32 v133, v136, v137
	global_store_dwordx4 v[192:193], v[130:133], off offset:64
	s_nop 1
	v_fmamk_f32 v130, v145, 0x3a800000, v227
	s_nop 0
	v_rsq_f32_e32 v130, v130
	s_nop 0
	v_mov_b32_e32 v188, v130
	global_load_dwordx4 v[130:133], v[166:167], off offset:16
	global_load_dwordx4 v[134:137], v[166:167], off
	s_waitcnt vmcnt(1)
	v_pk_fma_f32 v[140:141], v[74:75], v[188:189], v[132:133] op_sel_hi:[1,0,1]
	s_waitcnt vmcnt(0)
	v_pk_fma_f32 v[210:211], v[76:77], v[188:189], v[134:135] op_sel_hi:[1,0,1]
	v_pk_fma_f32 v[212:213], v[78:79], v[188:189], v[136:137] op_sel_hi:[1,0,1]
	v_pk_mul_f32 v[136:137], v[210:211], v[210:211]
	v_pk_mul_f32 v[134:135], v[212:213], v[212:213]
	s_nop 0
	v_pk_mov_b32 v[138:139], v[136:137], v[134:135] op_sel:[1,0]
	v_mov_b32_e32 v137, v135
	v_pk_add_f32 v[134:135], v[138:139], v[136:137]
	v_pk_fma_f32 v[138:139], v[72:73], v[188:189], v[130:131] op_sel_hi:[1,0,1]
	v_pk_mul_f32 v[130:131], v[140:141], v[140:141]
	v_pk_mul_f32 v[132:133], v[138:139], v[138:139]
	v_pk_add_f32 v[208:209], v[134:135], v[134:135] op_sel_hi:[0,1]
	v_pk_mov_b32 v[134:135], v[132:133], v[130:131] op_sel:[1,0]
	v_mov_b32_e32 v133, v131
	v_pk_add_f32 v[130:131], v[134:135], v[132:133]
	s_nop 0
	v_pk_add_f32 v[214:215], v[130:131], v[130:131] op_sel_hi:[0,1]
	global_load_dwordx4 v[130:133], v[166:167], off offset:528
	global_load_dwordx4 v[134:137], v[166:167], off offset:512
	s_waitcnt vmcnt(1)
	v_pk_fma_f32 v[190:191], v[10:11], v[188:189], v[132:133] op_sel_hi:[1,0,1]
	s_waitcnt vmcnt(0)
	v_pk_fma_f32 v[206:207], v[12:13], v[188:189], v[134:135] op_sel_hi:[1,0,1]
	v_pk_fma_f32 v[194:195], v[14:15], v[188:189], v[136:137] op_sel_hi:[1,0,1]
	v_mul_f32_e32 v134, v206, v206
	v_pk_fma_f32 v[134:135], v[206:207], v[206:207], v[134:135] op_sel_hi:[1,1,0]
	v_pk_fma_f32 v[192:193], v[8:9], v[188:189], v[130:131] op_sel_hi:[1,0,1]
	v_mul_f32_e32 v134, v194, v194
	v_pk_fma_f32 v[136:137], v[194:195], v[194:195], v[134:135] op_sel_hi:[1,1,0]
	v_mul_f32_e32 v134, v192, v192
	v_mul_f32_e32 v136, v193, v193
	v_mul_f32_e32 v208, v190, v190
	v_mul_f32_e32 v214, v191, v191
	v_pk_add_f32 v[130:131], v[134:135], v[136:137]
	v_pk_add_f32 v[132:133], v[208:209], v[214:215]
	s_nop 0
	v_pk_add_f32 v[130:131], v[130:131], v[132:133]
	s_nop 0
	v_add_f32_e32 v130, v130, v131
	ds_bpermute_b32 v131, v246, v130
	s_waitcnt lgkmcnt(0)
	v_add_f32_e32 v130, v130, v131
	ds_bpermute_b32 v131, v247, v130
	s_waitcnt lgkmcnt(0)
; __device__ __forceinline__ unsigned pk_bf16(float lo, float hi) { f32x2 v = {lo, hi}; bf16x2_t b = __builtin_convertvector(v, bf16x2_t); return __builtin_bit_cast(unsigned, b); }
;     __device__ __forceinline__ void operator()(const f32x4 (&acc)[2][2][4][2], const Unit& u, int wr, int wc, int fr, int fq) const {
;     ...
;                     const int row = row0 + ai * HALF + m * 16; const int t = row & 16383;
;                     const float rv = rsqrtf(rowss[row] * (1.0f / 1024.0f) + 1e-6f);
;                     float ss = 0.f; f32x4 hv[2][2];
; #pragma unroll
;                     for (int bj = 0; bj < 2; ++bj)
; #pragma unroll
;                         for (int n = 0; n < 2; ++n) { const f32x4 v = acc[ai][bj][m][n] * rv + *(const f32x4*)(bp + bj * HALF + 4 * n); hv[bj][n] = v; ss += (v[0] * v[0] + v[1] * v[1]) + (v[2] * v[2] + v[3] * v[3]); }
;                     ss += __shfl_xor(ss, 16); ss += __shfl_xor(ss, 32);
;                     const float rinv = rsqrtf(ss * (1.0f / 64.0f) + 1e-6f) * osc;
; #pragma unroll
;                     for (int bj = 0; bj < 2; ++bj) {
;                         const int pos = bj == 0 ? (t >> 6) : (t & 63);
;                         const f32x4 c = *(const f32x4*)(ropec + pos * 16 + 4 * fqo), s = *(const f32x4*)(ropes + pos * 16 + 4 * fqo);
;                         const f32x4 x1 = hv[bj][0] * rinv * *(const f32x4*)(gw + 32 * bj), x2 = hv[bj][1] * rinv * *(const f32x4*)(gw + 32 * bj + 16);
;                         const f32x4 o1 = x1 * c - x2 * s, o2 = x2 * c + x1 * s;
;                         u32x4 w; w.x = pk_bf16(o1[0], o1[1]); w.y = pk_bf16(o1[2], o1[3]); w.z = pk_bf16(o2[0], o2[1]); w.w = pk_bf16(o2[2], o2[3]);
;                         *(u32x4*)(base + (size_t)row * pitch + 32 * bj) = w;
;                     }
	v_add_f32_e32 v130, v130, v131
	v_fmamk_f32 v130, v130, 0x3c800000, v227
	s_nop 0
	v_rsq_f32_e32 v130, v130
	s_nop 0
	v_mul_f32_e32 v208, v245, v130
	v_mad_i64_i32 v[130:131], s[4:5], s0, v159, 0
	v_lshl_add_u64 v[188:189], v[130:131], 1, v[170:171]
	global_load_dwordx4 v[134:137], v[204:205], off
	global_load_dwordx4 v[130:133], v[186:187], off
	v_pk_mul_f32 v[214:215], v[212:213], v[208:209] op_sel_hi:[1,0]
	v_pk_mul_f32 v[216:217], v[210:211], v[208:209] op_sel_hi:[1,0]
	global_load_dwordx4 v[210:213], v[168:169], off
	v_pk_mul_f32 v[194:195], v[194:195], v[208:209] op_sel_hi:[1,0]
	v_pk_mul_f32 v[192:193], v[192:193], v[208:209] op_sel_hi:[1,0]
	v_pk_mul_f32 v[190:191], v[190:191], v[208:209] op_sel_hi:[1,0]
	v_add_u32_e32 v159, 0xb0, v162
	s_waitcnt vmcnt(0)
	v_pk_mul_f32 v[210:211], v[210:211], v[216:217]
	v_pk_mul_f32 v[212:213], v[212:213], v[214:215]
	v_pk_mul_f32 v[214:215], v[138:139], v[208:209] op_sel_hi:[1,0]
	v_pk_mul_f32 v[216:217], v[140:141], v[208:209] op_sel_hi:[1,0]
	global_load_dwordx4 v[138:141], v[168:169], off offset:64
	s_waitcnt vmcnt(0)
	v_pk_mul_f32 v[140:141], v[140:141], v[216:217]
	v_pk_mul_f32 v[138:139], v[138:139], v[214:215]
	v_pk_mul_f32 v[216:217], v[132:133], v[140:141]
	v_pk_mul_f32 v[214:215], v[130:131], v[138:139]
	v_pk_fma_f32 v[216:217], v[136:137], v[212:213], v[216:217] neg_lo:[0,0,1] neg_hi:[0,0,1]
	v_pk_fma_f32 v[214:215], v[134:135], v[210:211], v[214:215] neg_lo:[0,0,1] neg_hi:[0,0,1]
	v_pk_mul_f32 v[134:135], v[134:135], v[138:139]
	v_pk_mul_f32 v[136:137], v[136:137], v[140:141]
	s_nop 0
	v_pk_fma_f32 v[136:137], v[132:133], v[212:213], v[136:137]
	v_pk_fma_f32 v[132:133], v[130:131], v[210:211], v[134:135]
	v_cvt_pk_bf16_f32 v130, v214, v215
	v_cvt_pk_bf16_f32 v131, v216, v217
	v_cvt_pk_bf16_f32 v132, v132, v133
	v_cvt_pk_bf16_f32 v133, v136, v137
	global_store_dwordx4 v[188:189], v[130:133], off
	global_load_dwordx4 v[130:133], v[196:197], off
	s_nop 0
	global_load_dwordx4 v[134:137], v[198:199], off
	global_load_dwordx4 v[138:141], v[168:169], off offset:128
	v_pk_mul_f32 v[196:197], v[206:207], v[208:209] op_sel_hi:[1,0]
	s_waitcnt vmcnt(0)
	v_pk_mul_f32 v[194:195], v[140:141], v[194:195]
	v_pk_mul_f32 v[196:197], v[138:139], v[196:197]
	global_load_dwordx4 v[138:141], v[168:169], off offset:192
	s_waitcnt vmcnt(0)
	v_pk_mul_f32 v[140:141], v[140:141], v[190:191]
	v_pk_mul_f32 v[138:139], v[138:139], v[192:193]
	v_pk_mul_f32 v[192:193], v[136:137], v[140:141]
	v_pk_mul_f32 v[190:191], v[134:135], v[138:139]
	v_pk_fma_f32 v[192:193], v[132:133], v[194:195], v[192:193] neg_lo:[0,0,1] neg_hi:[0,0,1]
	v_pk_fma_f32 v[190:191], v[130:131], v[196:197], v[190:191] neg_lo:[0,0,1] neg_hi:[0,0,1]
	v_pk_mul_f32 v[130:131], v[130:131], v[138:139]
	v_pk_mul_f32 v[132:133], v[132:133], v[140:141]
	s_nop 0
	v_pk_fma_f32 v[136:137], v[136:137], v[194:195], v[132:133]
	v_pk_fma_f32 v[132:133], v[134:135], v[196:197], v[130:131]
	v_cvt_pk_bf16_f32 v130, v190, v191
	v_cvt_pk_bf16_f32 v131, v192, v193
	v_cvt_pk_bf16_f32 v132, v132, v133
	v_cvt_pk_bf16_f32 v133, v136, v137
	global_store_dwordx4 v[188:189], v[130:133], off offset:64
	s_nop 1
	v_fmamk_f32 v130, v147, 0x3a800000, v227
	s_nop 0
	v_rsq_f32_e32 v130, v130
	s_nop 0
	v_mov_b32_e32 v188, v130
	global_load_dwordx4 v[130:133], v[166:167], off offset:16
	global_load_dwordx4 v[134:137], v[166:167], off
	s_waitcnt vmcnt(1)
	v_pk_fma_f32 v[140:141], v[66:67], v[188:189], v[132:133] op_sel_hi:[1,0,1]
	s_waitcnt vmcnt(0)
	v_pk_fma_f32 v[196:197], v[68:69], v[188:189], v[134:135] op_sel_hi:[1,0,1]
	v_pk_fma_f32 v[198:199], v[70:71], v[188:189], v[136:137] op_sel_hi:[1,0,1]
	v_pk_mul_f32 v[136:137], v[196:197], v[196:197]
	v_pk_mul_f32 v[134:135], v[198:199], v[198:199]
	s_nop 0
	v_pk_mov_b32 v[138:139], v[136:137], v[134:135] op_sel:[1,0]
	v_mov_b32_e32 v137, v135
	v_pk_add_f32 v[134:135], v[138:139], v[136:137]
	v_pk_fma_f32 v[138:139], v[64:65], v[188:189], v[130:131] op_sel_hi:[1,0,1]
	v_pk_mul_f32 v[130:131], v[140:141], v[140:141]
	v_pk_mul_f32 v[132:133], v[138:139], v[138:139]
	v_pk_add_f32 v[194:195], v[134:135], v[134:135] op_sel_hi:[0,1]
	v_pk_mov_b32 v[134:135], v[132:133], v[130:131] op_sel:[1,0]
	v_mov_b32_e32 v133, v131
	v_pk_add_f32 v[130:131], v[134:135], v[132:133]
	s_nop 0
	v_pk_add_f32 v[206:207], v[130:131], v[130:131] op_sel_hi:[0,1]
	global_load_dwordx4 v[130:133], v[166:167], off offset:528
	global_load_dwordx4 v[134:137], v[166:167], off offset:512
	s_waitcnt vmcnt(1)
; __device__ __forceinline__ unsigned pk_bf16(float lo, float hi) { f32x2 v = {lo, hi}; bf16x2_t b = __builtin_convertvector(v, bf16x2_t); return __builtin_bit_cast(unsigned, b); }
;     __device__ __forceinline__ void operator()(const f32x4 (&acc)[2][2][4][2], const Unit& u, int wr, int wc, int fr, int fq) const {
;     ...
;                         for (int n = 0; n < 2; ++n) { const f32x4 v = acc[ai][bj][m][n] * rv + *(const f32x4*)(bp + bj * HALF + 4 * n); hv[bj][n] = v; ss += (v[0] * v[0] + v[1] * v[1]) + (v[2] * v[2] + v[3] * v[3]); }
;                     ss += __shfl_xor(ss, 16); ss += __shfl_xor(ss, 32);
;                     const float rinv = rsqrtf(ss * (1.0f / 64.0f) + 1e-6f) * osc;
; #pragma unroll
;                     for (int bj = 0; bj < 2; ++bj) {
;                         const int pos = bj == 0 ? (t >> 6) : (t & 63);
;                         const f32x4 c = *(const f32x4*)(ropec + pos * 16 + 4 * fqo), s = *(const f32x4*)(ropes + pos * 16 + 4 * fqo);
;                         const f32x4 x1 = hv[bj][0] * rinv * *(const f32x4*)(gw + 32 * bj), x2 = hv[bj][1] * rinv * *(const f32x4*)(gw + 32 * bj + 16);
;                         const f32x4 o1 = x1 * c - x2 * s, o2 = x2 * c + x1 * s;
;                         u32x4 w; w.x = pk_bf16(o1[0], o1[1]); w.y = pk_bf16(o1[2], o1[3]); w.z = pk_bf16(o2[0], o2[1]); w.w = pk_bf16(o2[2], o2[3]);
;                         *(u32x4*)(base + (size_t)row * pitch + 32 * bj) = w;
	v_pk_fma_f32 v[172:173], v[2:3], v[188:189], v[132:133] op_sel_hi:[1,0,1]
	s_waitcnt vmcnt(0)
	v_pk_fma_f32 v[192:193], v[4:5], v[188:189], v[134:135] op_sel_hi:[1,0,1]
	v_pk_fma_f32 v[190:191], v[6:7], v[188:189], v[136:137] op_sel_hi:[1,0,1]
	v_mul_f32_e32 v134, v192, v192
	v_pk_fma_f32 v[134:135], v[192:193], v[192:193], v[134:135] op_sel_hi:[1,1,0]
	v_pk_fma_f32 v[188:189], v[0:1], v[188:189], v[130:131] op_sel_hi:[1,0,1]
	v_mul_f32_e32 v134, v190, v190
	v_pk_fma_f32 v[136:137], v[190:191], v[190:191], v[134:135] op_sel_hi:[1,1,0]
	v_mul_f32_e32 v134, v188, v188
	v_mul_f32_e32 v136, v189, v189
	v_mul_f32_e32 v194, v172, v172
	v_mul_f32_e32 v206, v173, v173
	v_pk_add_f32 v[130:131], v[134:135], v[136:137]
	v_pk_add_f32 v[132:133], v[194:195], v[206:207]
	s_nop 0
	v_pk_add_f32 v[130:131], v[130:131], v[132:133]
	s_nop 0
	v_add_f32_e32 v130, v130, v131
	ds_bpermute_b32 v131, v246, v130
	s_waitcnt lgkmcnt(0)
	v_add_f32_e32 v130, v130, v131
	ds_bpermute_b32 v131, v247, v130
	s_waitcnt lgkmcnt(0)
	v_add_f32_e32 v130, v130, v131
	v_fmamk_f32 v130, v130, 0x3c800000, v227
	s_nop 0
	v_rsq_f32_e32 v130, v130
	s_nop 0
	v_mul_f32_e32 v194, v245, v130
	v_mad_i64_i32 v[130:131], s[0:1], s0, v159, 0
	v_lshl_add_u64 v[170:171], v[130:131], 1, v[170:171]
	global_load_dwordx4 v[134:137], v[204:205], off
	global_load_dwordx4 v[130:133], v[186:187], off
	v_pk_mul_f32 v[204:205], v[198:199], v[194:195] op_sel_hi:[1,0]
	v_pk_mul_f32 v[186:187], v[196:197], v[194:195] op_sel_hi:[1,0]
	global_load_dwordx4 v[196:199], v[168:169], off
	v_pk_mul_f32 v[188:189], v[188:189], v[194:195] op_sel_hi:[1,0]
	v_pk_mul_f32 v[172:173], v[172:173], v[194:195] op_sel_hi:[1,0]
	s_mov_b64 s[0:1], 0
	s_waitcnt vmcnt(0)
	v_pk_mul_f32 v[186:187], v[196:197], v[186:187]
	v_pk_mul_f32 v[196:197], v[198:199], v[204:205]
	v_pk_mul_f32 v[198:199], v[138:139], v[194:195] op_sel_hi:[1,0]
	v_pk_mul_f32 v[204:205], v[140:141], v[194:195] op_sel_hi:[1,0]
	global_load_dwordx4 v[138:141], v[168:169], off offset:64
	s_waitcnt vmcnt(0)
	v_pk_mul_f32 v[140:141], v[140:141], v[204:205]
	v_pk_mul_f32 v[138:139], v[138:139], v[198:199]
	v_pk_mul_f32 v[204:205], v[132:133], v[140:141]
	v_pk_mul_f32 v[198:199], v[130:131], v[138:139]
	v_pk_fma_f32 v[204:205], v[136:137], v[196:197], v[204:205] neg_lo:[0,0,1] neg_hi:[0,0,1]
	v_pk_fma_f32 v[198:199], v[134:135], v[186:187], v[198:199] neg_lo:[0,0,1] neg_hi:[0,0,1]
	v_pk_mul_f32 v[134:135], v[134:135], v[138:139]
	v_pk_mul_f32 v[136:137], v[136:137], v[140:141]
	s_nop 0
	v_pk_fma_f32 v[136:137], v[132:133], v[196:197], v[136:137]
	v_pk_fma_f32 v[132:133], v[130:131], v[186:187], v[134:135]
	v_cvt_pk_bf16_f32 v130, v198, v199
	v_cvt_pk_bf16_f32 v131, v204, v205
	v_cvt_pk_bf16_f32 v132, v132, v133
	v_cvt_pk_bf16_f32 v133, v136, v137
	global_store_dwordx4 v[170:171], v[130:133], off
	global_load_dwordx4 v[130:133], v[200:201], off
	s_nop 0
	global_load_dwordx4 v[134:137], v[202:203], off
	global_load_dwordx4 v[138:141], v[168:169], off offset:128
	v_pk_mul_f32 v[186:187], v[190:191], v[194:195] op_sel_hi:[1,0]
	v_pk_mul_f32 v[190:191], v[192:193], v[194:195] op_sel_hi:[1,0]
	s_waitcnt vmcnt(0)
	v_pk_mul_f32 v[186:187], v[140:141], v[186:187]
	v_pk_mul_f32 v[190:191], v[138:139], v[190:191]
	global_load_dwordx4 v[138:141], v[168:169], off offset:192
	s_waitcnt vmcnt(0)
	v_pk_mul_f32 v[140:141], v[140:141], v[172:173]
	v_pk_mul_f32 v[138:139], v[138:139], v[188:189]
	v_pk_mul_f32 v[172:173], v[136:137], v[140:141]
	v_pk_mul_f32 v[168:169], v[134:135], v[138:139]
	v_pk_fma_f32 v[172:173], v[132:133], v[186:187], v[172:173] neg_lo:[0,0,1] neg_hi:[0,0,1]
	v_pk_fma_f32 v[168:169], v[130:131], v[190:191], v[168:169] neg_lo:[0,0,1] neg_hi:[0,0,1]
	v_pk_mul_f32 v[130:131], v[130:131], v[138:139]
	v_pk_mul_f32 v[132:133], v[132:133], v[140:141]
	s_nop 0
	v_pk_fma_f32 v[136:137], v[136:137], v[186:187], v[132:133]
	v_pk_fma_f32 v[132:133], v[134:135], v[190:191], v[130:131]
	v_cvt_pk_bf16_f32 v130, v168, v169
	v_cvt_pk_bf16_f32 v131, v172, v173
	v_cvt_pk_bf16_f32 v132, v132, v133
	v_cvt_pk_bf16_f32 v133, v136, v137
	global_store_dwordx4 v[170:171], v[130:133], off offset:64

;     __device__ __forceinline__ void operator()(const f32x4 (&acc)[2][2][4][2], const Unit& u, int wr, int wc, int fr, int fq) const {
;     ...
;                         const int row = row0 + ai * HALF + m * 16;
;                         const float rv = rsqrtf(rowss[row] * (1.0f / 1024.0f) + 1e-6f);
;                         const f32x4 v0 = (acc[ai][bj][m][0] * rv + bz0) * qsc, v1 = (acc[ai][bj][m][1] * rv + bz1) * qsc;
;                         if (isk) { float s2 = (v0[0] * v0[0] + v0[1] * v0[1]) + (v0[2] * v0[2] + v0[3] * v0[3]) + (v1[0] * v1[0] + v1[1] * v1[1]) + (v1[2] * v1[2] + v1[3] * v1[3]);
;                             s2 += __shfl_xor(s2, 16); s2 += __shfl_xor(s2, 32); kmx = fmaxf(kmx, s2); }
.LBB0_277:
	v_lshl_add_u64 v[138:139], v[162:163], 2, s[12:13]
	global_load_dword v141, v[138:139], off
	global_load_dword v188, v[138:139], off offset:64
	global_load_dword v189, v[138:139], off offset:128
	global_load_dword v190, v[138:139], off offset:192
	global_load_dword v191, v[138:139], off offset:512
	global_load_dword v192, v[138:139], off offset:576
	global_load_dword v193, v[138:139], off offset:640
	global_load_dword v194, v[138:139], off offset:704
	global_load_dword v195, v[138:139], off offset:128
	global_load_dword v196, v[138:139], off offset:192
	global_load_dword v197, v[138:139], off offset:512
	global_load_dword v198, v[138:139], off offset:576
	global_load_dword v199, v[138:139], off offset:640
	global_load_dword v200, v[138:139], off offset:704
	s_cmp_eq_u32 s66, 1
	s_cselect_b64 s[68:69], -1, 0
	s_cmp_lg_u32 s66, 1
	s_waitcnt vmcnt(0)
	v_fmamk_f32 v141, v141, 0x3a800000, v227
	s_nop 1
	v_rsq_f32_e32 v141, v141
	s_nop 0
	v_mov_b32_e32 v168, v141
	v_pk_fma_f32 v[170:171], v[124:125], v[168:169], v[134:135] op_sel_hi:[1,0,1]
	v_pk_fma_f32 v[124:125], v[126:127], v[168:169], v[136:137] op_sel_hi:[1,0,1]
	v_pk_fma_f32 v[120:121], v[120:121], v[168:169], v[130:131] op_sel_hi:[1,0,1]
	v_pk_fma_f32 v[122:123], v[122:123], v[168:169], v[132:133] op_sel_hi:[1,0,1]
	v_pk_mul_f32 v[124:125], v[140:141], v[124:125] op_sel_hi:[0,1]
	v_pk_mul_f32 v[168:169], v[140:141], v[170:171] op_sel_hi:[0,1]
	v_pk_mul_f32 v[122:123], v[140:141], v[122:123] op_sel_hi:[0,1]
	v_pk_mul_f32 v[126:127], v[140:141], v[120:121] op_sel_hi:[0,1]
	v_mov_b32_e32 v159, 0
	s_cbranch_scc1 .LBB0_279
	v_pk_mul_f32 v[120:121], v[124:125], v[124:125]
	v_pk_mul_f32 v[170:171], v[168:169], v[168:169]
	v_and_b32_e32 v141, 64, v230
	v_pk_mov_b32 v[172:173], v[170:171], v[120:121] op_sel:[1,0]
	v_mov_b32_e32 v171, v121
	v_pk_add_f32 v[120:121], v[172:173], v[170:171]
	v_pk_mul_f32 v[170:171], v[122:123], v[122:123]
	v_pk_mul_f32 v[172:173], v[126:127], v[126:127]
	v_mov_b32_e32 v186, v170
	v_mov_b32_e32 v187, v172
	v_mov_b32_e32 v172, v171
	v_add_f32_e32 v120, v120, v121
	v_xor_b32_e32 v121, 16, v230
	v_add_u32_e32 v141, 64, v141
	v_pk_add_f32 v[170:171], v[186:187], v[172:173]
	v_cmp_lt_i32_e32 vcc, v121, v141
	v_add_f32_e32 v120, v171, v120
	v_add_f32_e32 v120, v170, v120
	v_cndmask_b32_e32 v121, v230, v121, vcc
	v_lshlrev_b32_e32 v121, 2, v121
	ds_bpermute_b32 v121, v121, v120
	s_waitcnt lgkmcnt(0)
	v_add_f32_e32 v120, v120, v121
	v_xor_b32_e32 v121, 32, v230
	v_cmp_lt_i32_e32 vcc, v121, v141
	s_nop 1
	v_cndmask_b32_e32 v121, v230, v121, vcc
	v_lshlrev_b32_e32 v121, 2, v121
	ds_bpermute_b32 v121, v121, v120
	s_waitcnt lgkmcnt(0)
	v_add_f32_e32 v120, v120, v121
	v_max_f32_e32 v159, 0, v120

; __device__ __forceinline__ unsigned pk_bf16(float lo, float hi) { f32x2 v = {lo, hi}; bf16x2_t b = __builtin_convertvector(v, bf16x2_t); return __builtin_bit_cast(unsigned, b); }
;     __device__ __forceinline__ void operator()(const f32x4 (&acc)[2][2][4][2], const Unit& u, int wr, int wc, int fr, int fq) const {
;     ...
;                         const int row = row0 + ai * HALF + m * 16;
;                         const float rv = rsqrtf(rowss[row] * (1.0f / 1024.0f) + 1e-6f);
;                         const f32x4 v0 = (acc[ai][bj][m][0] * rv + bz0) * qsc, v1 = (acc[ai][bj][m][1] * rv + bz1) * qsc;
;                         if (isk) { float s2 = (v0[0] * v0[0] + v0[1] * v0[1]) + (v0[2] * v0[2] + v0[3] * v0[3]) + (v1[0] * v1[0] + v1[1] * v1[1]) + (v1[2] * v1[2] + v1[3] * v1[3]);
;                             s2 += __shfl_xor(s2, 16); s2 += __shfl_xor(s2, 32); kmx = fmaxf(kmx, s2); }
;                         u32x4 w; w.x = pk_bf16(v0[0], v0[1]); w.y = pk_bf16(v0[2], v0[3]); w.z = pk_bf16(v1[0], v1[1]); w.w = pk_bf16(v1[2], v1[3]);
;                         *(u32x4*)(base + (size_t)row * pitch) = w;
.LBB0_281:
	v_cvt_pk_bf16_f32 v127, v112, v113
	v_mad_i64_i32 v[112:113], s[0:1], s74, v243, 0
	v_cvt_pk_bf16_f32 v124, v118, v119
	v_cvt_pk_bf16_f32 v125, v114, v115
	v_cvt_pk_bf16_f32 v126, v116, v117
	v_lshl_add_u64 v[112:113], v[112:113], 1, v[120:121]
	global_store_dwordx4 v[112:113], v[124:127], off
	s_nop 0
	s_and_b64 vcc, exec, s[42:43]
	v_fmamk_f32 v112, v189, 0x3a800000, v227
	s_nop 1
	v_rsq_f32_e32 v112, v112
	s_nop 0
	v_pk_fma_f32 v[108:109], v[108:109], v[112:113], v[134:135] op_sel_hi:[1,0,1]
	v_pk_fma_f32 v[110:111], v[110:111], v[112:113], v[136:137] op_sel_hi:[1,0,1]
	v_pk_fma_f32 v[114:115], v[104:105], v[112:113], v[130:131] op_sel_hi:[1,0,1]
	v_pk_fma_f32 v[104:105], v[106:107], v[112:113], v[132:133] op_sel_hi:[1,0,1]
	v_pk_mul_f32 v[106:107], v[122:123], v[110:111]
	v_pk_mul_f32 v[110:111], v[140:141], v[108:109]
	v_pk_mul_f32 v[104:105], v[122:123], v[104:105]
	v_pk_mul_f32 v[108:109], v[140:141], v[114:115]
	s_cbranch_vccnz .LBB0_283
	v_pk_mul_f32 v[112:113], v[106:107], v[106:107]
	v_pk_mul_f32 v[114:115], v[110:111], v[110:111]
	s_nop 0
	v_pk_mov_b32 v[116:117], v[114:115], v[112:113] op_sel:[1,0]
	v_mov_b32_e32 v115, v113
	v_pk_add_f32 v[112:113], v[116:117], v[114:115]
	v_pk_mul_f32 v[114:115], v[104:105], v[104:105]
	v_pk_mul_f32 v[116:117], v[108:109], v[108:109]
	v_mov_b32_e32 v118, v114
	v_mov_b32_e32 v119, v116
	v_mov_b32_e32 v116, v115
	v_pk_add_f32 v[114:115], v[118:119], v[116:117]
	v_add_f32_e32 v112, v112, v113
	v_add_f32_e32 v112, v115, v112
	v_add_f32_e32 v112, v114, v112
	v_and_b32_e32 v114, 64, v230
	v_xor_b32_e32 v113, 16, v230
	v_add_u32_e32 v114, 64, v114
	v_cmp_lt_i32_e32 vcc, v113, v114
	s_nop 1
	v_cndmask_b32_e32 v113, v230, v113, vcc
	v_lshlrev_b32_e32 v113, 2, v113
	ds_bpermute_b32 v113, v113, v112
	s_waitcnt lgkmcnt(0)
	v_add_f32_e32 v112, v112, v113
	v_xor_b32_e32 v113, 32, v230
	v_cmp_lt_i32_e32 vcc, v113, v114
	s_nop 1
	v_cndmask_b32_e32 v113, v230, v113, vcc
	v_lshlrev_b32_e32 v113, 2, v113
	ds_bpermute_b32 v113, v113, v112
	s_waitcnt lgkmcnt(0)
	v_add_f32_e32 v112, v112, v113
	v_max_f32_e32 v113, v159, v159
	v_max_f32_e32 v159, v113, v112

; __device__ __forceinline__ unsigned pk_bf16(float lo, float hi) { f32x2 v = {lo, hi}; bf16x2_t b = __builtin_convertvector(v, bf16x2_t); return __builtin_bit_cast(unsigned, b); }
;     __device__ __forceinline__ void operator()(const f32x4 (&acc)[2][2][4][2], const Unit& u, int wr, int wc, int fr, int fq) const {
;     ...
;                         const int row = row0 + ai * HALF + m * 16;
;                         const float rv = rsqrtf(rowss[row] * (1.0f / 1024.0f) + 1e-6f);
;                         const f32x4 v0 = (acc[ai][bj][m][0] * rv + bz0) * qsc, v1 = (acc[ai][bj][m][1] * rv + bz1) * qsc;
;                         if (isk) { float s2 = (v0[0] * v0[0] + v0[1] * v0[1]) + (v0[2] * v0[2] + v0[3] * v0[3]) + (v1[0] * v1[0] + v1[1] * v1[1]) + (v1[2] * v1[2] + v1[3] * v1[3]);
;                             s2 += __shfl_xor(s2, 16); s2 += __shfl_xor(s2, 32); kmx = fmaxf(kmx, s2); }
;                         u32x4 w; w.x = pk_bf16(v0[0], v0[1]); w.y = pk_bf16(v0[2], v0[3]); w.z = pk_bf16(v1[0], v1[1]); w.w = pk_bf16(v1[2], v1[3]);
;                         *(u32x4*)(base + (size_t)row * pitch) = w;
.LBB0_285:
	v_cvt_pk_bf16_f32 v109, v96, v97
	v_mad_i64_i32 v[96:97], s[0:1], s74, v241, 0
	v_cvt_pk_bf16_f32 v106, v102, v103
	v_cvt_pk_bf16_f32 v107, v98, v99
	v_cvt_pk_bf16_f32 v108, v100, v101
	v_lshl_add_u64 v[96:97], v[96:97], 1, v[120:121]
	global_store_dwordx4 v[96:97], v[106:109], off
	s_nop 0
	s_and_b64 vcc, exec, s[42:43]
	v_fmamk_f32 v96, v191, 0x3a800000, v227
	s_nop 1
	v_rsq_f32_e32 v96, v96
	s_nop 0
	v_pk_fma_f32 v[92:93], v[92:93], v[96:97], v[134:135] op_sel_hi:[1,0,1]
	v_pk_fma_f32 v[94:95], v[94:95], v[96:97], v[136:137] op_sel_hi:[1,0,1]
	v_pk_fma_f32 v[98:99], v[88:89], v[96:97], v[130:131] op_sel_hi:[1,0,1]
	v_pk_fma_f32 v[88:89], v[90:91], v[96:97], v[132:133] op_sel_hi:[1,0,1]
	v_pk_mul_f32 v[90:91], v[104:105], v[94:95]
	v_pk_mul_f32 v[94:95], v[140:141], v[92:93]
	v_pk_mul_f32 v[88:89], v[104:105], v[88:89]
	v_pk_mul_f32 v[92:93], v[140:141], v[98:99]
	s_cbranch_vccnz .LBB0_287
	v_pk_mul_f32 v[96:97], v[90:91], v[90:91]
	v_pk_mul_f32 v[98:99], v[94:95], v[94:95]
	s_nop 0
	v_pk_mov_b32 v[100:101], v[98:99], v[96:97] op_sel:[1,0]
	v_mov_b32_e32 v99, v97
	v_pk_add_f32 v[96:97], v[100:101], v[98:99]
	v_pk_mul_f32 v[98:99], v[88:89], v[88:89]
	v_pk_mul_f32 v[100:101], v[92:93], v[92:93]
	v_mov_b32_e32 v102, v98
	v_mov_b32_e32 v103, v100
	v_mov_b32_e32 v100, v99
	v_pk_add_f32 v[98:99], v[102:103], v[100:101]
	v_add_f32_e32 v96, v96, v97
	v_add_f32_e32 v96, v99, v96
	v_add_f32_e32 v96, v98, v96
	v_and_b32_e32 v98, 64, v230
	v_xor_b32_e32 v97, 16, v230
	v_add_u32_e32 v98, 64, v98
	v_cmp_lt_i32_e32 vcc, v97, v98
	s_nop 1
	v_cndmask_b32_e32 v97, v230, v97, vcc
	v_lshlrev_b32_e32 v97, 2, v97
	ds_bpermute_b32 v97, v97, v96
	s_waitcnt lgkmcnt(0)
	v_add_f32_e32 v96, v96, v97
	v_xor_b32_e32 v97, 32, v230
	v_cmp_lt_i32_e32 vcc, v97, v98
	s_nop 1
	v_cndmask_b32_e32 v97, v230, v97, vcc
	v_lshlrev_b32_e32 v97, 2, v97
	ds_bpermute_b32 v97, v97, v96
	s_waitcnt lgkmcnt(0)
	v_add_f32_e32 v96, v96, v97
	v_max_f32_e32 v97, v159, v159
	v_max_f32_e32 v159, v97, v96

; __device__ __forceinline__ unsigned pk_bf16(float lo, float hi) { f32x2 v = {lo, hi}; bf16x2_t b = __builtin_convertvector(v, bf16x2_t); return __builtin_bit_cast(unsigned, b); }
;     __device__ __forceinline__ void operator()(const f32x4 (&acc)[2][2][4][2], const Unit& u, int wr, int wc, int fr, int fq) const {
;     ...
;                         const int row = row0 + ai * HALF + m * 16;
;                         const float rv = rsqrtf(rowss[row] * (1.0f / 1024.0f) + 1e-6f);
;                         const f32x4 v0 = (acc[ai][bj][m][0] * rv + bz0) * qsc, v1 = (acc[ai][bj][m][1] * rv + bz1) * qsc;
;                         if (isk) { float s2 = (v0[0] * v0[0] + v0[1] * v0[1]) + (v0[2] * v0[2] + v0[3] * v0[3]) + (v1[0] * v1[0] + v1[1] * v1[1]) + (v1[2] * v1[2] + v1[3] * v1[3]);
;                             s2 += __shfl_xor(s2, 16); s2 += __shfl_xor(s2, 32); kmx = fmaxf(kmx, s2); }
;                         u32x4 w; w.x = pk_bf16(v0[0], v0[1]); w.y = pk_bf16(v0[2], v0[3]); w.z = pk_bf16(v1[0], v1[1]); w.w = pk_bf16(v1[2], v1[3]);
;                         *(u32x4*)(base + (size_t)row * pitch) = w;
.LBB0_289:
	v_add_u32_e32 v90, 0x90, v162
	v_cvt_pk_bf16_f32 v95, v80, v81
	v_mad_i64_i32 v[80:81], s[0:1], s74, v90, 0
	v_cvt_pk_bf16_f32 v92, v86, v87
	v_cvt_pk_bf16_f32 v93, v82, v83
	v_cvt_pk_bf16_f32 v94, v84, v85
	v_lshl_add_u64 v[80:81], v[80:81], 1, v[120:121]
	global_store_dwordx4 v[80:81], v[92:95], off
	s_nop 0
	s_and_b64 vcc, exec, s[42:43]
	v_fmamk_f32 v80, v193, 0x3a800000, v227
	s_nop 1
	v_rsq_f32_e32 v80, v80
	s_nop 0
	v_pk_fma_f32 v[76:77], v[76:77], v[80:81], v[134:135] op_sel_hi:[1,0,1]
	v_pk_fma_f32 v[78:79], v[78:79], v[80:81], v[136:137] op_sel_hi:[1,0,1]
	v_pk_fma_f32 v[82:83], v[72:73], v[80:81], v[130:131] op_sel_hi:[1,0,1]
	v_pk_fma_f32 v[72:73], v[74:75], v[80:81], v[132:133] op_sel_hi:[1,0,1]
	v_pk_mul_f32 v[74:75], v[88:89], v[78:79]
	v_pk_mul_f32 v[78:79], v[140:141], v[76:77]
	v_pk_mul_f32 v[72:73], v[88:89], v[72:73]
	v_pk_mul_f32 v[76:77], v[140:141], v[82:83]
	s_cbranch_vccnz .LBB0_291
	v_pk_mul_f32 v[80:81], v[74:75], v[74:75]
	v_pk_mul_f32 v[82:83], v[78:79], v[78:79]
	s_nop 0
	v_pk_mov_b32 v[84:85], v[82:83], v[80:81] op_sel:[1,0]
	v_mov_b32_e32 v83, v81
	v_pk_add_f32 v[80:81], v[84:85], v[82:83]
	v_pk_mul_f32 v[82:83], v[72:73], v[72:73]
	v_pk_mul_f32 v[84:85], v[76:77], v[76:77]
	v_mov_b32_e32 v86, v82
	v_mov_b32_e32 v87, v84
	v_mov_b32_e32 v84, v83
	v_pk_add_f32 v[82:83], v[86:87], v[84:85]
	v_add_f32_e32 v80, v80, v81
	v_add_f32_e32 v80, v83, v80
	v_add_f32_e32 v80, v82, v80
	v_and_b32_e32 v82, 64, v230
	v_xor_b32_e32 v81, 16, v230
	v_add_u32_e32 v82, 64, v82
	v_cmp_lt_i32_e32 vcc, v81, v82
	s_nop 1
	v_cndmask_b32_e32 v81, v230, v81, vcc
	v_lshlrev_b32_e32 v81, 2, v81
	ds_bpermute_b32 v81, v81, v80
	s_waitcnt lgkmcnt(0)
	v_add_f32_e32 v80, v80, v81
	v_xor_b32_e32 v81, 32, v230
	v_cmp_lt_i32_e32 vcc, v81, v82
	s_nop 1
	v_cndmask_b32_e32 v81, v230, v81, vcc
	v_lshlrev_b32_e32 v81, 2, v81
	ds_bpermute_b32 v81, v81, v80
	s_waitcnt lgkmcnt(0)
	v_add_f32_e32 v80, v80, v81
	v_max_f32_e32 v81, v159, v159
	v_max_f32_e32 v159, v81, v80

;     __device__ __forceinline__ void khook(f32x4 (&acc)[2][2][4][2], const Unit& u, int t, int wr, int fr) const {
;         const int row0 = u.pm * BM + wr * 64 + fr;
;         const float* s0 = gss + (t == 4 ? 0 : 32768); const float w0 = t == 4 ? (1.0f / 256.0f) : (1.0f / 384.0f);
; #pragma unroll
;         for (int ai = 0; ai < 2; ++ai)
; #pragma unroll
;             for (int m = 0; m < 4; ++m) { const int row = row0 + ai * HALF + m * 16;
;                 const float ratio = rsqrtf(s0[row] * w0 + 1e-6f) * __builtin_sqrtf(s0[32768 + row] * (1.0f / 384.0f) + 1e-6f);
; #pragma unroll
;                 for (int bj = 0; bj < 2; ++bj)
; #pragma unroll
;                     for (int n = 0; n < 2; ++n) acc[ai][bj][m][n] *= ratio; }
.LBB0_800:
	s_cmpk_eq_i32 s62, 0x200
	s_cselect_b64 vcc, -1, 0
	s_and_b64 s[0:1], vcc, exec
	s_cselect_b32 s34, 0, 0x20000
	v_lshl_add_u64 v[136:137], v[188:189], 0, s[34:35]
	global_load_dword v130, v[136:137], off
	global_load_dword v191, v[136:137], off offset:64
	global_load_dword v192, v[136:137], off offset:128
	global_load_dword v193, v[136:137], off offset:192
	global_load_dword v194, v[136:137], off offset:512
	global_load_dword v195, v[136:137], off offset:576
	global_load_dword v196, v[136:137], off offset:640
	global_load_dword v197, v[136:137], off offset:704
	s_mov_b32 s98, 0x20000
	s_mov_b32 s99, 0
	v_lshl_add_u64 v[200:201], v[136:137], 0, s[98:99]
	global_load_dword v202, v[200:201], off
	global_load_dword v203, v[200:201], off offset:64
	global_load_dword v204, v[200:201], off offset:128
	global_load_dword v205, v[200:201], off offset:192
	global_load_dword v206, v[200:201], off offset:512
	global_load_dword v207, v[200:201], off offset:576
	global_load_dword v208, v[200:201], off offset:640
	global_load_dword v209, v[200:201], off offset:704
	v_cndmask_b32_e32 v128, v235, v236, vcc
	s_mov_b32 s0, 0x20000
	s_waitcnt vmcnt(0)
	v_fmaak_f32 v130, v128, v130, 0x358637bd
	s_nop 0
	v_rsq_f32_e32 v130, v130
	s_nop 0
	v_mov_b32_e32 v138, v130
	v_add_co_u32_e32 v130, vcc, s0, v136
	s_nop 1
	v_addc_co_u32_e32 v131, vcc, 0, v137, vcc
	v_fmamk_f32 v139, v202, 0x3b2aaaab, v227
	v_cmp_gt_f32_e32 vcc, s88, v139
	v_mul_f32_e32 v140, 0x4f800000, v139
	s_nop 0
	v_cndmask_b32_e32 v139, v139, v140, vcc
	v_sqrt_f32_e32 v140, v139
	s_nop 0
	v_add_u32_e32 v141, -1, v140
	v_fma_f32 v142, -v141, v140, v139
	v_cmp_ge_f32_e64 s[0:1], 0, v142
	v_add_u32_e32 v142, 1, v140
	s_nop 0
	v_cndmask_b32_e64 v141, v140, v141, s[0:1]
	v_fma_f32 v140, -v142, v140, v139
	v_cmp_lt_f32_e64 s[0:1], 0, v140
	s_nop 1
	v_cndmask_b32_e64 v140, v141, v142, s[0:1]
	v_mul_f32_e32 v141, 0x37800000, v140
	v_cndmask_b32_e32 v140, v140, v141, vcc
	v_cmp_class_f32_e32 vcc, v139, v229
	s_nop 1
	v_cndmask_b32_e32 v139, v140, v139, vcc
	v_mul_f32_e32 v138, v139, v138
	v_pk_mul_f32 v[126:127], v[126:127], v[138:139] op_sel_hi:[1,0]
	v_pk_mul_f32 v[124:125], v[124:125], v[138:139] op_sel_hi:[1,0]
	v_pk_mul_f32 v[122:123], v[122:123], v[138:139] op_sel_hi:[1,0]
	v_pk_mul_f32 v[120:121], v[120:121], v[138:139] op_sel_hi:[1,0]
	v_pk_mul_f32 v[62:63], v[62:63], v[138:139] op_sel_hi:[1,0]
	v_pk_mul_f32 v[60:61], v[60:61], v[138:139] op_sel_hi:[1,0]
	v_pk_mul_f32 v[58:59], v[58:59], v[138:139] op_sel_hi:[1,0]
	v_pk_mul_f32 v[56:57], v[56:57], v[138:139] op_sel_hi:[1,0]
	v_fmaak_f32 v138, v128, v191, 0x358637bd
	s_nop 0
	v_rsq_f32_e32 v138, v138
	s_nop 0
	v_fmamk_f32 v139, v203, 0x3b2aaaab, v227
	v_cmp_gt_f32_e32 vcc, s88, v139
	v_mul_f32_e32 v140, 0x4f800000, v139
	s_nop 0
	v_cndmask_b32_e32 v139, v139, v140, vcc
	v_sqrt_f32_e32 v140, v139
	s_nop 0
	v_add_u32_e32 v141, -1, v140
	v_fma_f32 v142, -v141, v140, v139
	v_cmp_ge_f32_e64 s[0:1], 0, v142
	v_add_u32_e32 v142, 1, v140
	s_nop 0
	v_cndmask_b32_e64 v141, v140, v141, s[0:1]
	v_fma_f32 v140, -v142, v140, v139
	v_cmp_lt_f32_e64 s[0:1], 0, v140
	s_nop 1
	v_cndmask_b32_e64 v140, v141, v142, s[0:1]
	v_mul_f32_e32 v141, 0x37800000, v140
	v_cndmask_b32_e32 v140, v140, v141, vcc
	v_cmp_class_f32_e32 vcc, v139, v229
	s_nop 1
	v_cndmask_b32_e32 v139, v140, v139, vcc
	v_mul_f32_e32 v138, v139, v138
	v_pk_mul_f32 v[118:119], v[118:119], v[138:139] op_sel_hi:[1,0]
	v_pk_mul_f32 v[116:117], v[116:117], v[138:139] op_sel_hi:[1,0]
	v_pk_mul_f32 v[114:115], v[114:115], v[138:139] op_sel_hi:[1,0]
	v_pk_mul_f32 v[112:113], v[112:113], v[138:139] op_sel_hi:[1,0]
	v_pk_mul_f32 v[54:55], v[54:55], v[138:139] op_sel_hi:[1,0]
	v_pk_mul_f32 v[52:53], v[52:53], v[138:139] op_sel_hi:[1,0]
	v_pk_mul_f32 v[50:51], v[50:51], v[138:139] op_sel_hi:[1,0]
	v_pk_mul_f32 v[48:49], v[48:49], v[138:139] op_sel_hi:[1,0]
	v_fmaak_f32 v138, v128, v192, 0x358637bd
	s_nop 0
	v_rsq_f32_e32 v138, v138
	s_nop 0
	v_fmamk_f32 v139, v204, 0x3b2aaaab, v227
	v_cmp_gt_f32_e32 vcc, s88, v139
	v_mul_f32_e32 v140, 0x4f800000, v139
	s_nop 0
	v_cndmask_b32_e32 v139, v139, v140, vcc
	v_sqrt_f32_e32 v140, v139
	s_nop 0
	v_add_u32_e32 v141, -1, v140
	v_fma_f32 v142, -v141, v140, v139
	v_cmp_ge_f32_e64 s[0:1], 0, v142
	v_add_u32_e32 v142, 1, v140
	s_nop 0
	v_cndmask_b32_e64 v141, v140, v141, s[0:1]
	v_fma_f32 v140, -v142, v140, v139
	v_cmp_lt_f32_e64 s[0:1], 0, v140
	s_nop 1
	v_cndmask_b32_e64 v140, v141, v142, s[0:1]
	v_mul_f32_e32 v141, 0x37800000, v140
	v_cndmask_b32_e32 v140, v140, v141, vcc
	v_cmp_class_f32_e32 vcc, v139, v229
	s_nop 1
	v_cndmask_b32_e32 v139, v140, v139, vcc
	v_mul_f32_e32 v138, v139, v138
	v_pk_mul_f32 v[110:111], v[110:111], v[138:139] op_sel_hi:[1,0]
	v_pk_mul_f32 v[108:109], v[108:109], v[138:139] op_sel_hi:[1,0]
	v_pk_mul_f32 v[106:107], v[106:107], v[138:139] op_sel_hi:[1,0]
	v_pk_mul_f32 v[104:105], v[104:105], v[138:139] op_sel_hi:[1,0]
	v_pk_mul_f32 v[46:47], v[46:47], v[138:139] op_sel_hi:[1,0]
	v_pk_mul_f32 v[44:45], v[44:45], v[138:139] op_sel_hi:[1,0]
	v_pk_mul_f32 v[42:43], v[42:43], v[138:139] op_sel_hi:[1,0]
	v_pk_mul_f32 v[40:41], v[40:41], v[138:139] op_sel_hi:[1,0]
	v_fmaak_f32 v138, v128, v193, 0x358637bd
	s_nop 0
	v_rsq_f32_e32 v138, v138
	s_nop 0
	v_fmamk_f32 v139, v205, 0x3b2aaaab, v227
	v_cmp_gt_f32_e32 vcc, s88, v139
	v_mul_f32_e32 v140, 0x4f800000, v139
	s_nop 0
	v_cndmask_b32_e32 v139, v139, v140, vcc
	v_sqrt_f32_e32 v140, v139
	s_nop 0
	v_add_u32_e32 v141, -1, v140
	v_fma_f32 v142, -v141, v140, v139
	v_cmp_ge_f32_e64 s[0:1], 0, v142
	v_add_u32_e32 v142, 1, v140
	s_nop 0
	v_cndmask_b32_e64 v141, v140, v141, s[0:1]
	v_fma_f32 v140, -v142, v140, v139
;     __device__ __forceinline__ void khook(f32x4 (&acc)[2][2][4][2], const Unit& u, int t, int wr, int fr) const {
;         const int row0 = u.pm * BM + wr * 64 + fr;
;         const float* s0 = gss + (t == 4 ? 0 : 32768); const float w0 = t == 4 ? (1.0f / 256.0f) : (1.0f / 384.0f);
; #pragma unroll
;         for (int ai = 0; ai < 2; ++ai)
; #pragma unroll
;             for (int m = 0; m < 4; ++m) { const int row = row0 + ai * HALF + m * 16;
;                 const float ratio = rsqrtf(s0[row] * w0 + 1e-6f) * __builtin_sqrtf(s0[32768 + row] * (1.0f / 384.0f) + 1e-6f);
; #pragma unroll
;                 for (int bj = 0; bj < 2; ++bj)
; #pragma unroll
;                     for (int n = 0; n < 2; ++n) acc[ai][bj][m][n] *= ratio; }
	v_cmp_lt_f32_e64 s[0:1], 0, v140
	s_nop 1
	v_cndmask_b32_e64 v140, v141, v142, s[0:1]
	v_mul_f32_e32 v141, 0x37800000, v140
	v_cndmask_b32_e32 v140, v140, v141, vcc
	v_cmp_class_f32_e32 vcc, v139, v229
	s_nop 1
	v_cndmask_b32_e32 v139, v140, v139, vcc
	v_mul_f32_e32 v138, v139, v138
	v_pk_mul_f32 v[102:103], v[102:103], v[138:139] op_sel_hi:[1,0]
	v_pk_mul_f32 v[100:101], v[100:101], v[138:139] op_sel_hi:[1,0]
	v_pk_mul_f32 v[98:99], v[98:99], v[138:139] op_sel_hi:[1,0]
	v_pk_mul_f32 v[96:97], v[96:97], v[138:139] op_sel_hi:[1,0]
	v_pk_mul_f32 v[38:39], v[38:39], v[138:139] op_sel_hi:[1,0]
	v_pk_mul_f32 v[36:37], v[36:37], v[138:139] op_sel_hi:[1,0]
	v_pk_mul_f32 v[34:35], v[34:35], v[138:139] op_sel_hi:[1,0]
	v_pk_mul_f32 v[32:33], v[32:33], v[138:139] op_sel_hi:[1,0]
	v_fmaak_f32 v138, v128, v194, 0x358637bd
	s_nop 0
	v_rsq_f32_e32 v138, v138
	s_nop 0
	v_fmamk_f32 v139, v206, 0x3b2aaaab, v227
	v_cmp_gt_f32_e32 vcc, s88, v139
	v_mul_f32_e32 v140, 0x4f800000, v139
	s_nop 0
	v_cndmask_b32_e32 v139, v139, v140, vcc
	v_sqrt_f32_e32 v140, v139
	s_nop 0
	v_add_u32_e32 v141, -1, v140
	v_fma_f32 v142, -v141, v140, v139
	v_cmp_ge_f32_e64 s[0:1], 0, v142
	v_add_u32_e32 v142, 1, v140
	s_nop 0
	v_cndmask_b32_e64 v141, v140, v141, s[0:1]
	v_fma_f32 v140, -v142, v140, v139
	v_cmp_lt_f32_e64 s[0:1], 0, v140
	s_nop 1
	v_cndmask_b32_e64 v140, v141, v142, s[0:1]
	v_mul_f32_e32 v141, 0x37800000, v140
	v_cndmask_b32_e32 v140, v140, v141, vcc
	v_cmp_class_f32_e32 vcc, v139, v229
	s_nop 1
	v_cndmask_b32_e32 v139, v140, v139, vcc
	v_mul_f32_e32 v138, v139, v138
	v_pk_mul_f32 v[94:95], v[94:95], v[138:139] op_sel_hi:[1,0]
	v_pk_mul_f32 v[92:93], v[92:93], v[138:139] op_sel_hi:[1,0]
	v_pk_mul_f32 v[90:91], v[90:91], v[138:139] op_sel_hi:[1,0]
	v_pk_mul_f32 v[88:89], v[88:89], v[138:139] op_sel_hi:[1,0]
	v_pk_mul_f32 v[30:31], v[30:31], v[138:139] op_sel_hi:[1,0]
	v_pk_mul_f32 v[28:29], v[28:29], v[138:139] op_sel_hi:[1,0]
	v_pk_mul_f32 v[26:27], v[26:27], v[138:139] op_sel_hi:[1,0]
	v_pk_mul_f32 v[24:25], v[24:25], v[138:139] op_sel_hi:[1,0]
	v_fmaak_f32 v138, v128, v195, 0x358637bd
	s_nop 0
	v_rsq_f32_e32 v138, v138
	s_nop 0
	v_fmamk_f32 v139, v207, 0x3b2aaaab, v227
	v_cmp_gt_f32_e32 vcc, s88, v139
	v_mul_f32_e32 v140, 0x4f800000, v139
	s_nop 0
	v_cndmask_b32_e32 v139, v139, v140, vcc
	v_sqrt_f32_e32 v140, v139
	s_nop 0
	v_add_u32_e32 v141, -1, v140
	v_fma_f32 v142, -v141, v140, v139
	v_cmp_ge_f32_e64 s[0:1], 0, v142
	v_add_u32_e32 v142, 1, v140
	s_nop 0
	v_cndmask_b32_e64 v141, v140, v141, s[0:1]
	v_fma_f32 v140, -v142, v140, v139
	v_cmp_lt_f32_e64 s[0:1], 0, v140
	s_nop 1
	v_cndmask_b32_e64 v140, v141, v142, s[0:1]
	v_mul_f32_e32 v141, 0x37800000, v140
	v_cndmask_b32_e32 v140, v140, v141, vcc
	v_cmp_class_f32_e32 vcc, v139, v229
	s_nop 1
	v_cndmask_b32_e32 v139, v140, v139, vcc
	v_mul_f32_e32 v138, v139, v138
	v_pk_mul_f32 v[86:87], v[86:87], v[138:139] op_sel_hi:[1,0]
	v_pk_mul_f32 v[84:85], v[84:85], v[138:139] op_sel_hi:[1,0]
	v_pk_mul_f32 v[82:83], v[82:83], v[138:139] op_sel_hi:[1,0]
	v_pk_mul_f32 v[80:81], v[80:81], v[138:139] op_sel_hi:[1,0]
	v_pk_mul_f32 v[22:23], v[22:23], v[138:139] op_sel_hi:[1,0]
	v_pk_mul_f32 v[20:21], v[20:21], v[138:139] op_sel_hi:[1,0]
	v_pk_mul_f32 v[18:19], v[18:19], v[138:139] op_sel_hi:[1,0]
	v_pk_mul_f32 v[16:17], v[16:17], v[138:139] op_sel_hi:[1,0]
	v_fmaak_f32 v138, v128, v196, 0x358637bd
	v_rsq_f32_e32 v138, v138
	v_fmaak_f32 v128, v128, v197, 0x358637bd
	v_mul_f32_e32 v136, 0x4b800000, v128
	v_fmamk_f32 v139, v208, 0x3b2aaaab, v227
	v_cmp_gt_f32_e32 vcc, s88, v139
	v_mul_f32_e32 v140, 0x4f800000, v139
	v_fmamk_f32 v130, v209, 0x3b2aaaab, v227
	v_cndmask_b32_e32 v139, v139, v140, vcc
	v_sqrt_f32_e32 v140, v139
	v_mul_f32_e32 v131, 0x4f800000, v130
	v_add_u32_e32 v141, -1, v140
	v_fma_f32 v142, -v141, v140, v139
	v_cmp_ge_f32_e64 s[0:1], 0, v142
	v_add_u32_e32 v142, 1, v140
	s_nop 0
	v_cndmask_b32_e64 v141, v140, v141, s[0:1]
	v_fma_f32 v140, -v142, v140, v139
	v_cmp_lt_f32_e64 s[0:1], 0, v140
	s_nop 1
	v_cndmask_b32_e64 v140, v141, v142, s[0:1]
	v_mul_f32_e32 v141, 0x37800000, v140
	v_cndmask_b32_e32 v140, v140, v141, vcc
	v_cmp_class_f32_e32 vcc, v139, v229
	s_nop 1
	v_cndmask_b32_e32 v139, v140, v139, vcc
	v_cmp_gt_f32_e32 vcc, s36, v128
	v_mul_f32_e32 v138, v139, v138
	v_pk_mul_f32 v[78:79], v[78:79], v[138:139] op_sel_hi:[1,0]
	v_cndmask_b32_e32 v128, v128, v136, vcc
	v_rsq_f32_e32 v128, v128
	v_pk_mul_f32 v[76:77], v[76:77], v[138:139] op_sel_hi:[1,0]
	v_pk_mul_f32 v[74:75], v[74:75], v[138:139] op_sel_hi:[1,0]
	v_pk_mul_f32 v[72:73], v[72:73], v[138:139] op_sel_hi:[1,0]
	v_mul_f32_e32 v136, 0x45800000, v128
	v_cndmask_b32_e32 v128, v128, v136, vcc
	v_cmp_gt_f32_e32 vcc, s88, v130
	v_pk_mul_f32 v[14:15], v[14:15], v[138:139] op_sel_hi:[1,0]
	v_pk_mul_f32 v[12:13], v[12:13], v[138:139] op_sel_hi:[1,0]
	v_cndmask_b32_e32 v130, v130, v131, vcc
	v_sqrt_f32_e32 v131, v130
	v_pk_mul_f32 v[10:11], v[10:11], v[138:139] op_sel_hi:[1,0]
	v_pk_mul_f32 v[8:9], v[8:9], v[138:139] op_sel_hi:[1,0]
	v_add_u32_e32 v136, -1, v131
	v_fma_f32 v137, -v136, v131, v130
	v_cmp_ge_f32_e64 s[0:1], 0, v137
	v_add_u32_e32 v137, 1, v131
	s_nop 0
	v_cndmask_b32_e64 v136, v131, v136, s[0:1]
	v_fma_f32 v131, -v137, v131, v130
	v_cmp_lt_f32_e64 s[0:1], 0, v131
	s_nop 1
	v_cndmask_b32_e64 v131, v136, v137, s[0:1]
	v_mul_f32_e32 v136, 0x37800000, v131
	v_cndmask_b32_e32 v131, v131, v136, vcc
	v_cmp_class_f32_e32 vcc, v130, v229
	s_nop 1
	v_cndmask_b32_e32 v130, v131, v130, vcc
	v_mul_f32_e32 v128, v130, v128
	v_pk_mul_f32 v[70:71], v[70:71], v[128:129] op_sel_hi:[1,0]
	v_pk_mul_f32 v[68:69], v[68:69], v[128:129] op_sel_hi:[1,0]
	v_pk_mul_f32 v[66:67], v[66:67], v[128:129] op_sel_hi:[1,0]
	v_pk_mul_f32 v[64:65], v[64:65], v[128:129] op_sel_hi:[1,0]
	v_pk_mul_f32 v[6:7], v[6:7], v[128:129] op_sel_hi:[1,0]
	v_pk_mul_f32 v[4:5], v[4:5], v[128:129] op_sel_hi:[1,0]
	v_pk_mul_f32 v[2:3], v[2:3], v[128:129] op_sel_hi:[1,0]
	v_pk_mul_f32 v[0:1], v[0:1], v[128:129] op_sel_hi:[1,0]

; __device__ __forceinline__ unsigned pk_f16(float lo, float hi) { f32x2 v = {lo, hi}; f16x2_t h = __builtin_convertvector(v, f16x2_t); return __builtin_bit_cast(unsigned, h); }
; __device__ __forceinline__ f32x2 up_f16(unsigned w) { return __builtin_convertvector(__builtin_bit_cast(f16x2_t, w), f32x2); }
;     __device__ __forceinline__ void operator()(const f32x4 (&acc)[2][2][4][2], const Unit& u, int wr, int wc, int fr, int fq) const {
;     ...
;             for (int n = 0; n < 2; ++n) gv[n] = *(const f32x4*)(gate + (size_t)b * gstride + col0 + bj * HALF + 4 * n);
;             u32x4 pq[2][4];
; #pragma unroll
;             for (int ai = 0; ai < 2; ++ai)
; #pragma unroll
;                 for (int m = 0; m < 4; ++m) pq[ai][m] = *(const u32x4*)(base + (size_t)(row0 + ai * HALF + m * 16) * 1024 + col0 + bj * HALF);
;             asm volatile("" ::: "memory");
; #pragma unroll
;             for (int ai = 0; ai < 2; ++ai) {
; #pragma unroll
;                 for (int m = 0; m < 4; ++m) { const size_t off = (size_t)(row0 + ai * HALF + m * 16) * 1024 + col0 + bj * HALF;
;                     float rc = 1.0f; if constexpr (GN) rc = rsqrtf(gss[2 * 32768 + row0 + ai * HALF + m * 16] * (1.0f / 384.0f) + 1e-6f);
;                     const u32x4 q = pq[ai][m];
;                     const f32x2 qa_ = up_f16(q.x), qb_ = up_f16(q.y), qc_ = up_f16(q.z), qd_ = up_f16(q.w);
;                     const f32x4 x0 = (f32x4){qa_[0], qa_[1], qb_[0], qb_[1]} + gv[0] * (acc[ai][bj][m][0] * rc),
;                                 x1 = (f32x4){qc_[0], qc_[1], qd_[0], qd_[1]} + gv[1] * (acc[ai][bj][m][1] * rc);
;                     { u32x4 wx; wx.x = pk_f16(x0[0], x0[1]); wx.y = pk_f16(x0[2], x0[3]); wx.z = pk_f16(x1[0], x1[1]); wx.w = pk_f16(x1[2], x1[3]); *(u32x4*)(out + off) = wx; }
.LBB0_806:
	s_lshl_b32 s1, s68, 8
	v_mov_b32_e32 v128, v237
	s_ashr_i32 s0, s69, 6
	s_or_b32 s1, s1, s29
	v_or_b32_e32 v140, 16, v186
	v_lshl_add_u32 v138, v128, 3, s1
	s_mul_hi_i32 s1, s0, 0x6000
	s_mulk_i32 s0, 0x6000
	s_add_u32 s0, s20, s0
	v_ashrrev_i32_e32 v139, 31, v138
	s_addc_u32 s1, s21, s1
	v_ashrrev_i32_e32 v141, 31, v140
	v_lshlrev_b64 v[208:209], 11, v[186:187]
	v_lshl_add_u64 v[190:191], v[138:139], 2, s[0:1]
	v_lshlrev_b64 v[246:247], 11, v[140:141]
	v_or_b32_e32 v140, 32, v186
	s_mov_b64 s[0:1], 0x48000
	v_ashrrev_i32_e32 v141, 31, v140
	v_lshl_add_u64 v[220:221], v[208:209], 0, s[0:1]
	s_mov_b64 s[0:1], 0x50000
	s_mov_b64 s[4:5], 0x40000
	v_lshlrev_b64 v[206:207], 1, v[138:139]
	v_lshlrev_b64 v[248:249], 11, v[140:141]
	v_or_b32_e32 v140, 48, v186
	v_lshl_add_u64 v[222:223], v[208:209], 0, s[0:1]
	s_mov_b64 s[0:1], 0x58000
	v_lshl_add_u64 v[218:219], v[208:209], 0, s[4:5]
	v_lshl_add_u64 v[138:139], s[96:97], 0, v[206:207]
	v_ashrrev_i32_e32 v141, 31, v140
	v_lshl_add_u64 v[216:217], v[208:209], 0, s[0:1]
	s_mov_b32 s0, 0x40000
	v_lshl_add_u64 v[192:193], v[138:139], 0, v[208:209]
	v_lshl_add_u64 v[196:197], v[138:139], 0, v[248:249]
	v_lshlrev_b64 v[224:225], 11, v[140:141]
	v_lshl_add_u64 v[200:201], v[138:139], 0, v[218:219]
	v_lshl_add_u64 v[204:205], v[138:139], 0, v[222:223]
	v_add_co_u32_e32 v188, vcc, s0, v188
	global_load_dwordx4 v[130:133], v[190:191], off offset:16
	global_load_dwordx4 v[134:137], v[190:191], off
	v_lshl_add_u64 v[194:195], v[138:139], 0, v[246:247]
	global_load_dwordx4 v[212:215], v[192:193], off
	global_load_dwordx4 v[242:245], v[194:195], off
	v_lshl_add_u64 v[198:199], v[138:139], 0, v[224:225]
	global_load_dwordx4 v[158:161], v[196:197], off
	global_load_dwordx4 v[154:157], v[198:199], off
	v_lshl_add_u64 v[202:203], v[138:139], 0, v[220:221]
	global_load_dwordx4 v[150:153], v[200:201], off
	global_load_dwordx4 v[146:149], v[202:203], off
	v_lshl_add_u64 v[210:211], v[138:139], 0, v[216:217]
	global_load_dwordx4 v[142:145], v[204:205], off
	global_load_dwordx4 v[138:141], v[210:211], off
	v_addc_co_u32_e32 v189, vcc, 0, v189, vcc
	global_load_dword v128, v[188:189], off
	global_load_dword v163, v[188:189], off offset:64
	global_load_dword v165, v[188:189], off offset:128
	global_load_dword v167, v[188:189], off offset:192
	global_load_dword v169, v[188:189], off offset:512
	global_load_dword v171, v[188:189], off offset:576
	global_load_dword v173, v[188:189], off offset:640
	v_lshl_add_u64 v[208:209], s[96:97], 0, v[208:209]
	v_lshl_add_u64 v[208:209], v[208:209], 0, v[206:207]
	s_waitcnt vmcnt(0)
	v_cvt_f32_f16_e32 v250, v212
	v_cvt_f32_f16_sdwa v251, v212 dst_sel:DWORD dst_unused:UNUSED_PAD src0_sel:WORD_1
	v_cvt_f32_f16_e32 v212, v213
	v_cvt_f32_f16_sdwa v213, v213 dst_sel:DWORD dst_unused:UNUSED_PAD src0_sel:WORD_1
	v_cvt_f32_f16_e32 v174, v214
	v_fmamk_f32 v128, v128, 0x3b2aaaab, v227
	v_mul_f32_e32 v175, 0x4b800000, v128
	v_cmp_gt_f32_e32 vcc, s36, v128
	s_nop 1
	v_cndmask_b32_e32 v128, v128, v175, vcc
	v_rsq_f32_e32 v128, v128
	v_cvt_f32_f16_sdwa v175, v214 dst_sel:DWORD dst_unused:UNUSED_PAD src0_sel:WORD_1
	v_cvt_f32_f16_e32 v214, v215
	v_cvt_f32_f16_sdwa v215, v215 dst_sel:DWORD dst_unused:UNUSED_PAD src0_sel:WORD_1
	v_mul_f32_e32 v176, 0x45800000, v128
	v_cndmask_b32_e32 v128, v128, v176, vcc
	v_pk_mul_f32 v[124:125], v[124:125], v[128:129] op_sel_hi:[1,0]
	v_pk_mul_f32 v[126:127], v[126:127], v[128:129] op_sel_hi:[1,0]
	v_pk_mul_f32 v[176:177], v[120:121], v[128:129] op_sel_hi:[1,0]
	v_pk_mul_f32 v[122:123], v[122:123], v[128:129] op_sel_hi:[1,0]
	v_pk_fma_f32 v[120:121], v[136:137], v[126:127], v[212:213]
	v_pk_fma_f32 v[124:125], v[134:135], v[124:125], v[250:251]
	v_pk_fma_f32 v[122:123], v[132:133], v[122:123], v[214:215]
	v_pk_fma_f32 v[126:127], v[130:131], v[176:177], v[174:175]
	v_cvt_pk_f16_f32 v212, v124, v125
	v_cvt_pk_f16_f32 v213, v120, v121
	v_cvt_pk_f16_f32 v214, v126, v127
	v_cvt_pk_f16_f32 v215, v122, v123
	global_store_dwordx4 v[208:209], v[212:215], off
	s_nop 0
	v_lshl_add_u64 v[174:175], s[96:97], 0, v[246:247]
	v_lshl_add_u64 v[212:213], v[174:175], 0, v[206:207]
	v_cvt_f32_f16_e32 v174, v242
	v_cvt_f32_f16_sdwa v175, v242 dst_sel:DWORD dst_unused:UNUSED_PAD src0_sel:WORD_1
	v_cvt_f32_f16_e32 v176, v243
	v_cvt_f32_f16_sdwa v177, v243 dst_sel:DWORD dst_unused:UNUSED_PAD src0_sel:WORD_1
	v_cvt_f32_f16_e32 v214, v244
	v_cvt_f32_f16_e32 v242, v245
	v_cvt_f32_f16_sdwa v243, v245 dst_sel:DWORD dst_unused:UNUSED_PAD src0_sel:WORD_1
	v_fmamk_f32 v128, v163, 0x3b2aaaab, v227
	v_mul_f32_e32 v215, 0x4b800000, v128
	v_cmp_gt_f32_e32 vcc, s36, v128
	s_nop 1
	v_cndmask_b32_e32 v128, v128, v215, vcc
	v_rsq_f32_e32 v128, v128
	v_cvt_f32_f16_sdwa v215, v244 dst_sel:DWORD dst_unused:UNUSED_PAD src0_sel:WORD_1
	v_mul_f32_e32 v241, 0x45800000, v128
	v_cndmask_b32_e32 v128, v128, v241, vcc
	v_pk_mul_f32 v[244:245], v[116:117], v[128:129] op_sel_hi:[1,0]
	v_pk_mul_f32 v[116:117], v[118:119], v[128:129] op_sel_hi:[1,0]
	v_pk_mul_f32 v[246:247], v[112:113], v[128:129] op_sel_hi:[1,0]
	v_pk_mul_f32 v[112:113], v[114:115], v[128:129] op_sel_hi:[1,0]
	v_pk_fma_f32 v[116:117], v[136:137], v[116:117], v[176:177]
	v_pk_fma_f32 v[118:119], v[134:135], v[244:245], v[174:175]
	v_pk_fma_f32 v[112:113], v[132:133], v[112:113], v[242:243]
	v_pk_fma_f32 v[114:115], v[130:131], v[246:247], v[214:215]
	v_cvt_pk_f16_f32 v242, v118, v119
	v_cvt_pk_f16_f32 v243, v116, v117
	v_cvt_pk_f16_f32 v244, v114, v115
	v_cvt_pk_f16_f32 v245, v112, v113
	global_store_dwordx4 v[212:213], v[242:245], off
	s_nop 0
	v_lshl_add_u64 v[174:175], s[96:97], 0, v[248:249]
	v_lshl_add_u64 v[214:215], v[174:175], 0, v[206:207]
; __device__ __forceinline__ unsigned pk_f16(float lo, float hi) { f32x2 v = {lo, hi}; f16x2_t h = __builtin_convertvector(v, f16x2_t); return __builtin_bit_cast(unsigned, h); }
; __device__ __forceinline__ f32x2 up_f16(unsigned w) { return __builtin_convertvector(__builtin_bit_cast(f16x2_t, w), f32x2); }
;     __device__ __forceinline__ void operator()(const f32x4 (&acc)[2][2][4][2], const Unit& u, int wr, int wc, int fr, int fq) const {
;     ...
;                 for (int m = 0; m < 4; ++m) { const size_t off = (size_t)(row0 + ai * HALF + m * 16) * 1024 + col0 + bj * HALF;
;                     float rc = 1.0f; if constexpr (GN) rc = rsqrtf(gss[2 * 32768 + row0 + ai * HALF + m * 16] * (1.0f / 384.0f) + 1e-6f);
;                     const u32x4 q = pq[ai][m];
;                     const f32x2 qa_ = up_f16(q.x), qb_ = up_f16(q.y), qc_ = up_f16(q.z), qd_ = up_f16(q.w);
;                     const f32x4 x0 = (f32x4){qa_[0], qa_[1], qb_[0], qb_[1]} + gv[0] * (acc[ai][bj][m][0] * rc),
;                                 x1 = (f32x4){qc_[0], qc_[1], qd_[0], qd_[1]} + gv[1] * (acc[ai][bj][m][1] * rc);
;                     { u32x4 wx; wx.x = pk_f16(x0[0], x0[1]); wx.y = pk_f16(x0[2], x0[3]); wx.z = pk_f16(x1[0], x1[1]); wx.w = pk_f16(x1[2], x1[3]); *(u32x4*)(out + off) = wx; }
	v_cvt_f32_f16_e32 v174, v158
	v_cvt_f32_f16_sdwa v175, v158 dst_sel:DWORD dst_unused:UNUSED_PAD src0_sel:WORD_1
	v_cvt_f32_f16_e32 v158, v159
	v_cvt_f32_f16_sdwa v159, v159 dst_sel:DWORD dst_unused:UNUSED_PAD src0_sel:WORD_1
	v_cvt_f32_f16_e32 v176, v160
	v_fmamk_f32 v128, v165, 0x3b2aaaab, v227
	v_mul_f32_e32 v177, 0x4b800000, v128
	v_cmp_gt_f32_e32 vcc, s36, v128
	s_nop 1
	v_cndmask_b32_e32 v128, v128, v177, vcc
	v_rsq_f32_e32 v128, v128
	v_cvt_f32_f16_sdwa v177, v160 dst_sel:DWORD dst_unused:UNUSED_PAD src0_sel:WORD_1
	v_cvt_f32_f16_e32 v160, v161
	v_cvt_f32_f16_sdwa v161, v161 dst_sel:DWORD dst_unused:UNUSED_PAD src0_sel:WORD_1
	v_mul_f32_e32 v241, 0x45800000, v128
	v_cndmask_b32_e32 v128, v128, v241, vcc
	v_pk_mul_f32 v[242:243], v[108:109], v[128:129] op_sel_hi:[1,0]
	v_pk_mul_f32 v[108:109], v[110:111], v[128:129] op_sel_hi:[1,0]
	v_pk_mul_f32 v[244:245], v[104:105], v[128:129] op_sel_hi:[1,0]
	v_pk_mul_f32 v[104:105], v[106:107], v[128:129] op_sel_hi:[1,0]
	v_pk_fma_f32 v[108:109], v[136:137], v[108:109], v[158:159]
	v_pk_fma_f32 v[110:111], v[134:135], v[242:243], v[174:175]
	v_pk_fma_f32 v[104:105], v[132:133], v[104:105], v[160:161]
	v_pk_fma_f32 v[106:107], v[130:131], v[244:245], v[176:177]
	v_cvt_pk_f16_f32 v158, v110, v111
	v_cvt_pk_f16_f32 v159, v108, v109
	v_cvt_pk_f16_f32 v160, v106, v107
	v_cvt_pk_f16_f32 v161, v104, v105
	global_store_dwordx4 v[214:215], v[158:161], off
	s_nop 0
	v_cvt_f32_f16_e32 v174, v156
	v_cvt_f32_f16_e32 v160, v154
	v_cvt_f32_f16_sdwa v161, v154 dst_sel:DWORD dst_unused:UNUSED_PAD src0_sel:WORD_1
	v_cvt_f32_f16_e32 v154, v155
	v_cvt_f32_f16_sdwa v155, v155 dst_sel:DWORD dst_unused:UNUSED_PAD src0_sel:WORD_1
	v_lshl_add_u64 v[158:159], s[96:97], 0, v[224:225]
	v_lshl_add_u64 v[158:159], v[158:159], 0, v[206:207]
	v_fmamk_f32 v128, v167, 0x3b2aaaab, v227
	v_mul_f32_e32 v175, 0x4b800000, v128
	v_cmp_gt_f32_e32 vcc, s36, v128
	s_nop 1
	v_cndmask_b32_e32 v128, v128, v175, vcc
	v_rsq_f32_e32 v128, v128
	v_cvt_f32_f16_sdwa v175, v156 dst_sel:DWORD dst_unused:UNUSED_PAD src0_sel:WORD_1
	v_cvt_f32_f16_e32 v156, v157
	v_cvt_f32_f16_sdwa v157, v157 dst_sel:DWORD dst_unused:UNUSED_PAD src0_sel:WORD_1
	v_mul_f32_e32 v176, 0x45800000, v128
	v_cndmask_b32_e32 v128, v128, v176, vcc
	v_pk_mul_f32 v[176:177], v[100:101], v[128:129] op_sel_hi:[1,0]
	v_pk_mul_f32 v[100:101], v[102:103], v[128:129] op_sel_hi:[1,0]
	v_pk_mul_f32 v[224:225], v[96:97], v[128:129] op_sel_hi:[1,0]
	v_pk_mul_f32 v[96:97], v[98:99], v[128:129] op_sel_hi:[1,0]
	v_pk_fma_f32 v[100:101], v[136:137], v[100:101], v[154:155]
	v_pk_fma_f32 v[102:103], v[134:135], v[176:177], v[160:161]
	v_pk_fma_f32 v[96:97], v[132:133], v[96:97], v[156:157]
	v_pk_fma_f32 v[98:99], v[130:131], v[224:225], v[174:175]
	v_cvt_pk_f16_f32 v154, v102, v103
	v_cvt_pk_f16_f32 v155, v100, v101
	v_cvt_pk_f16_f32 v156, v98, v99
	v_cvt_pk_f16_f32 v157, v96, v97
	global_store_dwordx4 v[158:159], v[154:157], off
	s_nop 0
	v_fmamk_f32 v128, v169, 0x3b2aaaab, v227
	v_mul_f32_e32 v157, 0x4b800000, v128
	v_cmp_gt_f32_e32 vcc, s36, v128
	v_lshl_add_u64 v[154:155], s[96:97], 0, v[218:219]
	v_lshl_add_u64 v[218:219], v[154:155], 0, v[206:207]
	v_cndmask_b32_e32 v128, v128, v157, vcc
	v_rsq_f32_e32 v128, v128
	v_cvt_f32_f16_e32 v154, v150
	v_cvt_f32_f16_sdwa v155, v150 dst_sel:DWORD dst_unused:UNUSED_PAD src0_sel:WORD_1
	v_cvt_f32_f16_e32 v150, v151
	v_cvt_f32_f16_sdwa v151, v151 dst_sel:DWORD dst_unused:UNUSED_PAD src0_sel:WORD_1
	v_cvt_f32_f16_e32 v156, v152
	v_cvt_f32_f16_sdwa v157, v152 dst_sel:DWORD dst_unused:UNUSED_PAD src0_sel:WORD_1
	v_cvt_f32_f16_e32 v152, v153
	v_cvt_f32_f16_sdwa v153, v153 dst_sel:DWORD dst_unused:UNUSED_PAD src0_sel:WORD_1
	v_mul_f32_e32 v160, 0x45800000, v128
	v_cndmask_b32_e32 v128, v128, v160, vcc
	v_pk_mul_f32 v[160:161], v[92:93], v[128:129] op_sel_hi:[1,0]
	v_pk_mul_f32 v[92:93], v[94:95], v[128:129] op_sel_hi:[1,0]
	v_pk_mul_f32 v[174:175], v[88:89], v[128:129] op_sel_hi:[1,0]
	v_pk_mul_f32 v[88:89], v[90:91], v[128:129] op_sel_hi:[1,0]
	v_pk_fma_f32 v[92:93], v[136:137], v[92:93], v[150:151]
	v_pk_fma_f32 v[94:95], v[134:135], v[160:161], v[154:155]
	v_pk_fma_f32 v[88:89], v[132:133], v[88:89], v[152:153]
	v_pk_fma_f32 v[90:91], v[130:131], v[174:175], v[156:157]
	v_cvt_pk_f16_f32 v150, v94, v95
	v_cvt_pk_f16_f32 v151, v92, v93
	v_cvt_pk_f16_f32 v152, v90, v91
	v_cvt_pk_f16_f32 v153, v88, v89
	global_store_dwordx4 v[218:219], v[150:153], off
	s_nop 0
	v_cvt_f32_f16_e32 v154, v148
	v_lshl_add_u64 v[150:151], s[96:97], 0, v[220:221]
	v_lshl_add_u64 v[220:221], v[150:151], 0, v[206:207]
	v_cvt_f32_f16_e32 v152, v146
	v_cvt_f32_f16_sdwa v153, v146 dst_sel:DWORD dst_unused:UNUSED_PAD src0_sel:WORD_1
	v_cvt_f32_f16_e32 v146, v147
	v_cvt_f32_f16_sdwa v147, v147 dst_sel:DWORD dst_unused:UNUSED_PAD src0_sel:WORD_1
	v_cvt_f32_f16_sdwa v155, v148 dst_sel:DWORD dst_unused:UNUSED_PAD src0_sel:WORD_1
	v_cvt_f32_f16_e32 v148, v149
	v_cvt_f32_f16_sdwa v149, v149 dst_sel:DWORD dst_unused:UNUSED_PAD src0_sel:WORD_1
	v_fmamk_f32 v128, v171, 0x3b2aaaab, v227
	s_nop 1
	v_rsq_f32_e32 v128, v128
	s_nop 0
	v_pk_mul_f32 v[84:85], v[84:85], v[128:129] op_sel_hi:[1,0]
	v_pk_mul_f32 v[86:87], v[86:87], v[128:129] op_sel_hi:[1,0]
	v_pk_mul_f32 v[80:81], v[80:81], v[128:129] op_sel_hi:[1,0]
	v_pk_mul_f32 v[82:83], v[82:83], v[128:129] op_sel_hi:[1,0]
	v_pk_fma_f32 v[150:151], v[136:137], v[86:87], v[146:147]
	v_pk_fma_f32 v[152:153], v[134:135], v[84:85], v[152:153]
	v_pk_fma_f32 v[146:147], v[132:133], v[82:83], v[148:149]
	v_pk_fma_f32 v[148:149], v[130:131], v[80:81], v[154:155]
	v_cvt_pk_f16_f32 v80, v152, v153
	v_cvt_pk_f16_f32 v81, v150, v151
	v_cvt_pk_f16_f32 v82, v148, v149
; __device__ __forceinline__ unsigned pk_f16(float lo, float hi) { f32x2 v = {lo, hi}; f16x2_t h = __builtin_convertvector(v, f16x2_t); return __builtin_bit_cast(unsigned, h); }
; __device__ __forceinline__ f32x2 up_f16(unsigned w) { return __builtin_convertvector(__builtin_bit_cast(f16x2_t, w), f32x2); }
;     __device__ __forceinline__ void operator()(const f32x4 (&acc)[2][2][4][2], const Unit& u, int wr, int wc, int fr, int fq) const {
;     ...
;                 for (int m = 0; m < 4; ++m) { const size_t off = (size_t)(row0 + ai * HALF + m * 16) * 1024 + col0 + bj * HALF;
;                     float rc = 1.0f; if constexpr (GN) rc = rsqrtf(gss[2 * 32768 + row0 + ai * HALF + m * 16] * (1.0f / 384.0f) + 1e-6f);
;                     const u32x4 q = pq[ai][m];
;                     const f32x2 qa_ = up_f16(q.x), qb_ = up_f16(q.y), qc_ = up_f16(q.z), qd_ = up_f16(q.w);
;                     const f32x4 x0 = (f32x4){qa_[0], qa_[1], qb_[0], qb_[1]} + gv[0] * (acc[ai][bj][m][0] * rc),
;                                 x1 = (f32x4){qc_[0], qc_[1], qd_[0], qd_[1]} + gv[1] * (acc[ai][bj][m][1] * rc);
;                     { u32x4 wx; wx.x = pk_f16(x0[0], x0[1]); wx.y = pk_f16(x0[2], x0[3]); wx.z = pk_f16(x1[0], x1[1]); wx.w = pk_f16(x1[2], x1[3]); *(u32x4*)(out + off) = wx; }
;                     ss[ai][m] += ((x0[0] * x0[0] + x0[1] * x0[1]) + (x0[2] * x0[2] + x0[3] * x0[3])) + ((x1[0] * x1[0] + x1[1] * x1[1]) + (x1[2] * x1[2] + x1[3] * x1[3]));
	v_cvt_pk_f16_f32 v83, v146, v147
	global_store_dwordx4 v[220:221], v[80:83], off
	s_nop 0
	v_cvt_f32_f16_e32 v84, v144
	v_lshl_add_u64 v[80:81], s[96:97], 0, v[222:223]
	v_lshl_add_u64 v[222:223], v[80:81], 0, v[206:207]
	v_cvt_f32_f16_e32 v80, v142
	v_cvt_f32_f16_sdwa v81, v142 dst_sel:DWORD dst_unused:UNUSED_PAD src0_sel:WORD_1
	v_cvt_f32_f16_e32 v82, v143
	v_cvt_f32_f16_sdwa v83, v143 dst_sel:DWORD dst_unused:UNUSED_PAD src0_sel:WORD_1
	v_cvt_f32_f16_sdwa v87, v145 dst_sel:DWORD dst_unused:UNUSED_PAD src0_sel:WORD_1
	v_fmamk_f32 v85, v173, 0x3b2aaaab, v227
	v_mul_f32_e32 v86, 0x4b800000, v85
	v_cmp_gt_f32_e32 vcc, s36, v85
	s_nop 1
	v_cndmask_b32_e32 v85, v85, v86, vcc
	v_rsq_f32_e32 v128, v85
	v_cvt_f32_f16_sdwa v85, v144 dst_sel:DWORD dst_unused:UNUSED_PAD src0_sel:WORD_1
	v_cvt_f32_f16_e32 v86, v145
	v_mul_f32_e32 v142, 0x45800000, v128
	v_cndmask_b32_e32 v128, v128, v142, vcc
	v_pk_mul_f32 v[76:77], v[76:77], v[128:129] op_sel_hi:[1,0]
	v_pk_mul_f32 v[78:79], v[78:79], v[128:129] op_sel_hi:[1,0]
	v_pk_mul_f32 v[72:73], v[72:73], v[128:129] op_sel_hi:[1,0]
	v_pk_mul_f32 v[74:75], v[74:75], v[128:129] op_sel_hi:[1,0]
	v_pk_fma_f32 v[154:155], v[136:137], v[78:79], v[82:83]
	v_pk_fma_f32 v[156:157], v[134:135], v[76:77], v[80:81]
	v_pk_fma_f32 v[142:143], v[132:133], v[74:75], v[86:87]
	v_pk_fma_f32 v[144:145], v[130:131], v[72:73], v[84:85]
	v_cvt_pk_f16_f32 v72, v156, v157
	v_cvt_pk_f16_f32 v73, v154, v155
	v_cvt_pk_f16_f32 v74, v144, v145
	v_cvt_pk_f16_f32 v75, v142, v143
	global_store_dwordx4 v[222:223], v[72:75], off
	global_load_dword v77, v[188:189], off offset:704
	v_cvt_f32_f16_e32 v76, v140
	v_lshl_add_u64 v[72:73], s[96:97], 0, v[216:217]
	v_lshl_add_u64 v[160:161], v[72:73], 0, v[206:207]
	v_cvt_f32_f16_e32 v72, v138
	v_cvt_f32_f16_sdwa v73, v138 dst_sel:DWORD dst_unused:UNUSED_PAD src0_sel:WORD_1
	v_cvt_f32_f16_e32 v74, v139
	v_cvt_f32_f16_sdwa v75, v139 dst_sel:DWORD dst_unused:UNUSED_PAD src0_sel:WORD_1
	v_cvt_f32_f16_sdwa v79, v141 dst_sel:DWORD dst_unused:UNUSED_PAD src0_sel:WORD_1
	s_waitcnt vmcnt(0)
	v_fmamk_f32 v77, v77, 0x3b2aaaab, v227
	v_mul_f32_e32 v78, 0x4b800000, v77
	v_cmp_gt_f32_e32 vcc, s36, v77
	s_nop 1
	v_cndmask_b32_e32 v77, v77, v78, vcc
	v_rsq_f32_e32 v80, v77
	v_cvt_f32_f16_sdwa v77, v140 dst_sel:DWORD dst_unused:UNUSED_PAD src0_sel:WORD_1
	v_cvt_f32_f16_e32 v78, v141
	v_mul_f32_e32 v81, 0x45800000, v80
	v_cndmask_b32_e32 v80, v80, v81, vcc
	v_pk_mul_f32 v[68:69], v[68:69], v[80:81] op_sel_hi:[1,0]
	v_pk_mul_f32 v[70:71], v[70:71], v[80:81] op_sel_hi:[1,0]
	v_pk_mul_f32 v[64:65], v[64:65], v[80:81] op_sel_hi:[1,0]
	v_pk_mul_f32 v[66:67], v[66:67], v[80:81] op_sel_hi:[1,0]
	v_pk_fma_f32 v[136:137], v[136:137], v[70:71], v[74:75]
	v_pk_fma_f32 v[134:135], v[134:135], v[68:69], v[72:73]
	v_pk_fma_f32 v[132:133], v[132:133], v[66:67], v[78:79]
	v_pk_fma_f32 v[130:131], v[130:131], v[64:65], v[76:77]
	v_cvt_pk_f16_f32 v64, v134, v135
	v_cvt_pk_f16_f32 v65, v136, v137
	v_cvt_pk_f16_f32 v66, v130, v131
	v_cvt_pk_f16_f32 v67, v132, v133
	global_store_dwordx4 v[160:161], v[64:67], off
	global_load_dwordx4 v[64:67], v[190:191], off offset:528
	global_load_dwordx4 v[68:71], v[190:191], off offset:512
	global_load_dwordx4 v[138:141], v[192:193], off offset:256
	s_nop 0
	global_load_dwordx4 v[190:193], v[194:195], off offset:256
	s_nop 0
	global_load_dwordx4 v[194:197], v[196:197], off offset:256
	s_nop 0
	global_load_dwordx4 v[242:245], v[198:199], off offset:256
	global_load_dwordx4 v[84:87], v[200:201], off offset:256
	global_load_dwordx4 v[80:83], v[202:203], off offset:256
	global_load_dwordx4 v[76:79], v[204:205], off offset:256
	global_load_dwordx4 v[72:75], v[210:211], off offset:256
	global_load_dword v128, v[188:189], off
	s_waitcnt vmcnt(8)
	v_cvt_f32_f16_e32 v174, v138
	v_cvt_f32_f16_sdwa v175, v138 dst_sel:DWORD dst_unused:UNUSED_PAD src0_sel:WORD_1
	v_cvt_f32_f16_e32 v138, v139
	v_cvt_f32_f16_sdwa v139, v139 dst_sel:DWORD dst_unused:UNUSED_PAD src0_sel:WORD_1
	v_cvt_f32_f16_e32 v176, v140
	s_waitcnt vmcnt(0)
	v_fmamk_f32 v128, v128, 0x3b2aaaab, v227
	v_mul_f32_e32 v177, 0x4b800000, v128
	v_cmp_gt_f32_e32 vcc, s36, v128
	s_nop 1
	v_cndmask_b32_e32 v128, v128, v177, vcc
	v_rsq_f32_e32 v128, v128
	v_cvt_f32_f16_sdwa v177, v140 dst_sel:DWORD dst_unused:UNUSED_PAD src0_sel:WORD_1
	v_cvt_f32_f16_e32 v140, v141
	v_cvt_f32_f16_sdwa v141, v141 dst_sel:DWORD dst_unused:UNUSED_PAD src0_sel:WORD_1
	v_mul_f32_e32 v198, 0x45800000, v128
	v_cndmask_b32_e32 v128, v128, v198, vcc
	v_pk_mul_f32 v[60:61], v[60:61], v[128:129] op_sel_hi:[1,0]
	v_pk_mul_f32 v[62:63], v[62:63], v[128:129] op_sel_hi:[1,0]
	v_pk_mul_f32 v[198:199], v[56:57], v[128:129] op_sel_hi:[1,0]
	v_pk_mul_f32 v[200:201], v[58:59], v[128:129] op_sel_hi:[1,0]
	v_pk_fma_f32 v[56:57], v[70:71], v[62:63], v[138:139]
	v_pk_fma_f32 v[58:59], v[68:69], v[60:61], v[174:175]
	v_pk_fma_f32 v[60:61], v[66:67], v[200:201], v[140:141]
	v_pk_fma_f32 v[62:63], v[64:65], v[198:199], v[176:177]
	v_cvt_pk_f16_f32 v138, v58, v59
	v_cvt_pk_f16_f32 v139, v56, v57
	v_cvt_pk_f16_f32 v140, v62, v63
	v_cvt_pk_f16_f32 v141, v60, v61
	global_store_dwordx4 v[208:209], v[138:141], off offset:256
	s_nop 0
	v_cvt_f32_f16_e32 v174, v192
	v_cvt_f32_f16_e32 v138, v190
	v_cvt_f32_f16_sdwa v139, v190 dst_sel:DWORD dst_unused:UNUSED_PAD src0_sel:WORD_1
	v_cvt_f32_f16_e32 v140, v191
	v_cvt_f32_f16_sdwa v141, v191 dst_sel:DWORD dst_unused:UNUSED_PAD src0_sel:WORD_1
	v_cvt_f32_f16_e32 v176, v193
	v_cvt_f32_f16_sdwa v177, v193 dst_sel:DWORD dst_unused:UNUSED_PAD src0_sel:WORD_1
	v_mul_f32_e32 v59, v59, v59
	v_mul_f32_e32 v57, v57, v57
	v_mul_f32_e32 v63, v63, v63
	v_mul_f32_e32 v61, v61, v61
; __device__ __forceinline__ unsigned pk_f16(float lo, float hi) { f32x2 v = {lo, hi}; f16x2_t h = __builtin_convertvector(v, f16x2_t); return __builtin_bit_cast(unsigned, h); }
; __device__ __forceinline__ f32x2 up_f16(unsigned w) { return __builtin_convertvector(__builtin_bit_cast(f16x2_t, w), f32x2); }
;     __device__ __forceinline__ void operator()(const f32x4 (&acc)[2][2][4][2], const Unit& u, int wr, int wc, int fr, int fq) const {
;     ...
;                 for (int m = 0; m < 4; ++m) { const size_t off = (size_t)(row0 + ai * HALF + m * 16) * 1024 + col0 + bj * HALF;
;                     float rc = 1.0f; if constexpr (GN) rc = rsqrtf(gss[2 * 32768 + row0 + ai * HALF + m * 16] * (1.0f / 384.0f) + 1e-6f);
;                     const u32x4 q = pq[ai][m];
;                     const f32x2 qa_ = up_f16(q.x), qb_ = up_f16(q.y), qc_ = up_f16(q.z), qd_ = up_f16(q.w);
;                     const f32x4 x0 = (f32x4){qa_[0], qa_[1], qb_[0], qb_[1]} + gv[0] * (acc[ai][bj][m][0] * rc),
;                                 x1 = (f32x4){qc_[0], qc_[1], qd_[0], qd_[1]} + gv[1] * (acc[ai][bj][m][1] * rc);
;                     { u32x4 wx; wx.x = pk_f16(x0[0], x0[1]); wx.y = pk_f16(x0[2], x0[3]); wx.z = pk_f16(x1[0], x1[1]); wx.w = pk_f16(x1[2], x1[3]); *(u32x4*)(out + off) = wx; }
;                     ss[ai][m] += ((x0[0] * x0[0] + x0[1] * x0[1]) + (x0[2] * x0[2] + x0[3] * x0[3])) + ((x1[0] * x1[0] + x1[1] * x1[1]) + (x1[2] * x1[2] + x1[3] * x1[3]));
	v_fmac_f32_e32 v59, v58, v58
	v_fmac_f32_e32 v57, v56, v56
	v_fmac_f32_e32 v63, v62, v62
	v_fmac_f32_e32 v61, v60, v60
	v_add_f32_e32 v56, v59, v57
	v_add_f32_e32 v57, v63, v61
	v_add_f32_e32 v56, v56, v57
	v_cvt_f32_f16_e32 v60, v75
	v_cvt_f32_f16_sdwa v61, v75 dst_sel:DWORD dst_unused:UNUSED_PAD src0_sel:WORD_1
	v_fmamk_f32 v128, v163, 0x3b2aaaab, v227
	v_mul_f32_e32 v175, 0x4b800000, v128
	v_cmp_gt_f32_e32 vcc, s36, v128
	s_nop 1
	v_cndmask_b32_e32 v128, v128, v175, vcc
	v_rsq_f32_e32 v128, v128
	v_cvt_f32_f16_sdwa v175, v192 dst_sel:DWORD dst_unused:UNUSED_PAD src0_sel:WORD_1
	v_mul_f32_e32 v190, 0x45800000, v128
	v_cndmask_b32_e32 v128, v128, v190, vcc
	v_pk_mul_f32 v[190:191], v[52:53], v[128:129] op_sel_hi:[1,0]
	v_pk_mul_f32 v[52:53], v[54:55], v[128:129] op_sel_hi:[1,0]
	v_pk_mul_f32 v[192:193], v[48:49], v[128:129] op_sel_hi:[1,0]
	v_pk_mul_f32 v[48:49], v[50:51], v[128:129] op_sel_hi:[1,0]
	v_pk_fma_f32 v[52:53], v[70:71], v[52:53], v[140:141]
	v_pk_fma_f32 v[54:55], v[68:69], v[190:191], v[138:139]
	v_pk_fma_f32 v[48:49], v[66:67], v[48:49], v[176:177]
	v_pk_fma_f32 v[50:51], v[64:65], v[192:193], v[174:175]
	v_cvt_pk_f16_f32 v138, v54, v55
	v_cvt_pk_f16_f32 v139, v52, v53
	v_cvt_pk_f16_f32 v140, v50, v51
	v_cvt_pk_f16_f32 v141, v48, v49
	global_store_dwordx4 v[212:213], v[138:141], off offset:256
	s_nop 0
	v_cvt_f32_f16_e32 v174, v196
	v_cvt_f32_f16_e32 v138, v194
	v_cvt_f32_f16_sdwa v139, v194 dst_sel:DWORD dst_unused:UNUSED_PAD src0_sel:WORD_1
	v_cvt_f32_f16_e32 v140, v195
	v_cvt_f32_f16_sdwa v141, v195 dst_sel:DWORD dst_unused:UNUSED_PAD src0_sel:WORD_1
	v_cvt_f32_f16_e32 v176, v197
	v_cvt_f32_f16_sdwa v177, v197 dst_sel:DWORD dst_unused:UNUSED_PAD src0_sel:WORD_1
	v_fmamk_f32 v128, v165, 0x3b2aaaab, v227
	v_mul_f32_e32 v175, 0x4b800000, v128
	v_cmp_gt_f32_e32 vcc, s36, v128
	s_nop 1
	v_cndmask_b32_e32 v128, v128, v175, vcc
	v_rsq_f32_e32 v128, v128
	v_cvt_f32_f16_sdwa v175, v196 dst_sel:DWORD dst_unused:UNUSED_PAD src0_sel:WORD_1
	v_mul_f32_e32 v190, 0x45800000, v128
	v_cndmask_b32_e32 v128, v128, v190, vcc
	v_pk_mul_f32 v[190:191], v[44:45], v[128:129] op_sel_hi:[1,0]
	v_pk_mul_f32 v[44:45], v[46:47], v[128:129] op_sel_hi:[1,0]
	v_pk_mul_f32 v[192:193], v[40:41], v[128:129] op_sel_hi:[1,0]
	v_pk_mul_f32 v[40:41], v[42:43], v[128:129] op_sel_hi:[1,0]
	v_pk_fma_f32 v[44:45], v[70:71], v[44:45], v[140:141]
	v_pk_fma_f32 v[46:47], v[68:69], v[190:191], v[138:139]
	v_pk_fma_f32 v[40:41], v[66:67], v[40:41], v[176:177]
	v_pk_fma_f32 v[42:43], v[64:65], v[192:193], v[174:175]
	v_cvt_pk_f16_f32 v138, v46, v47
	v_cvt_pk_f16_f32 v139, v44, v45
	v_cvt_pk_f16_f32 v140, v42, v43
	v_cvt_pk_f16_f32 v141, v40, v41
	global_store_dwordx4 v[214:215], v[138:141], off offset:256
	s_nop 0
	v_cvt_f32_f16_e32 v174, v244
	v_cvt_f32_f16_e32 v138, v242
	v_cvt_f32_f16_sdwa v139, v242 dst_sel:DWORD dst_unused:UNUSED_PAD src0_sel:WORD_1
	v_cvt_f32_f16_e32 v140, v243
	v_cvt_f32_f16_sdwa v141, v243 dst_sel:DWORD dst_unused:UNUSED_PAD src0_sel:WORD_1
	v_cvt_f32_f16_e32 v176, v245
	v_cvt_f32_f16_sdwa v177, v245 dst_sel:DWORD dst_unused:UNUSED_PAD src0_sel:WORD_1
	v_fmamk_f32 v128, v167, 0x3b2aaaab, v227
	v_mul_f32_e32 v175, 0x4b800000, v128
	v_cmp_gt_f32_e32 vcc, s36, v128
	s_nop 1
	v_cndmask_b32_e32 v128, v128, v175, vcc
	v_rsq_f32_e32 v128, v128
	v_cvt_f32_f16_sdwa v175, v244 dst_sel:DWORD dst_unused:UNUSED_PAD src0_sel:WORD_1
	v_mul_f32_e32 v190, 0x45800000, v128
	v_cndmask_b32_e32 v128, v128, v190, vcc
	v_pk_mul_f32 v[190:191], v[36:37], v[128:129] op_sel_hi:[1,0]
	v_pk_mul_f32 v[36:37], v[38:39], v[128:129] op_sel_hi:[1,0]
	v_pk_mul_f32 v[192:193], v[32:33], v[128:129] op_sel_hi:[1,0]
	v_pk_mul_f32 v[32:33], v[34:35], v[128:129] op_sel_hi:[1,0]
	v_pk_fma_f32 v[36:37], v[70:71], v[36:37], v[140:141]
	v_pk_fma_f32 v[38:39], v[68:69], v[190:191], v[138:139]
	v_pk_fma_f32 v[32:33], v[66:67], v[32:33], v[176:177]
	v_pk_fma_f32 v[34:35], v[64:65], v[192:193], v[174:175]
	v_cvt_pk_f16_f32 v138, v38, v39
	v_cvt_pk_f16_f32 v139, v36, v37
	v_cvt_pk_f16_f32 v140, v34, v35
	v_cvt_pk_f16_f32 v141, v32, v33
	global_store_dwordx4 v[158:159], v[138:141], off offset:256
	s_nop 0
	v_fmamk_f32 v128, v169, 0x3b2aaaab, v227
	v_mul_f32_e32 v141, 0x4b800000, v128
	v_cmp_gt_f32_e32 vcc, s36, v128
	v_cvt_f32_f16_e32 v138, v84
	v_cvt_f32_f16_sdwa v139, v84 dst_sel:DWORD dst_unused:UNUSED_PAD src0_sel:WORD_1
	v_cndmask_b32_e32 v128, v128, v141, vcc
	v_rsq_f32_e32 v128, v128
	v_cvt_f32_f16_e32 v84, v85
	v_cvt_f32_f16_sdwa v85, v85 dst_sel:DWORD dst_unused:UNUSED_PAD src0_sel:WORD_1
	v_cvt_f32_f16_e32 v140, v86
	v_cvt_f32_f16_sdwa v141, v86 dst_sel:DWORD dst_unused:UNUSED_PAD src0_sel:WORD_1
	v_cvt_f32_f16_e32 v86, v87
	v_cvt_f32_f16_sdwa v87, v87 dst_sel:DWORD dst_unused:UNUSED_PAD src0_sel:WORD_1
	v_mul_f32_e32 v158, 0x45800000, v128
	v_cndmask_b32_e32 v128, v128, v158, vcc
	v_pk_mul_f32 v[158:159], v[28:29], v[128:129] op_sel_hi:[1,0]
	v_pk_mul_f32 v[28:29], v[30:31], v[128:129] op_sel_hi:[1,0]
	v_pk_mul_f32 v[174:175], v[24:25], v[128:129] op_sel_hi:[1,0]
	v_pk_mul_f32 v[24:25], v[26:27], v[128:129] op_sel_hi:[1,0]
	v_pk_fma_f32 v[28:29], v[70:71], v[28:29], v[84:85]
	v_pk_fma_f32 v[30:31], v[68:69], v[158:159], v[138:139]
	v_pk_fma_f32 v[24:25], v[66:67], v[24:25], v[86:87]
	v_pk_fma_f32 v[26:27], v[64:65], v[174:175], v[140:141]
; __device__ __forceinline__ unsigned pk_f16(float lo, float hi) { f32x2 v = {lo, hi}; f16x2_t h = __builtin_convertvector(v, f16x2_t); return __builtin_bit_cast(unsigned, h); }
; __device__ __forceinline__ f32x2 up_f16(unsigned w) { return __builtin_convertvector(__builtin_bit_cast(f16x2_t, w), f32x2); }
;     __device__ __forceinline__ void operator()(const f32x4 (&acc)[2][2][4][2], const Unit& u, int wr, int wc, int fr, int fq) const {
;     ...
;                 for (int m = 0; m < 4; ++m) { const size_t off = (size_t)(row0 + ai * HALF + m * 16) * 1024 + col0 + bj * HALF;
;                     float rc = 1.0f; if constexpr (GN) rc = rsqrtf(gss[2 * 32768 + row0 + ai * HALF + m * 16] * (1.0f / 384.0f) + 1e-6f);
;                     const u32x4 q = pq[ai][m];
;                     const f32x2 qa_ = up_f16(q.x), qb_ = up_f16(q.y), qc_ = up_f16(q.z), qd_ = up_f16(q.w);
;                     const f32x4 x0 = (f32x4){qa_[0], qa_[1], qb_[0], qb_[1]} + gv[0] * (acc[ai][bj][m][0] * rc),
;                                 x1 = (f32x4){qc_[0], qc_[1], qd_[0], qd_[1]} + gv[1] * (acc[ai][bj][m][1] * rc);
;                     { u32x4 wx; wx.x = pk_f16(x0[0], x0[1]); wx.y = pk_f16(x0[2], x0[3]); wx.z = pk_f16(x1[0], x1[1]); wx.w = pk_f16(x1[2], x1[3]); *(u32x4*)(out + off) = wx; }
;                     ss[ai][m] += ((x0[0] * x0[0] + x0[1] * x0[1]) + (x0[2] * x0[2] + x0[3] * x0[3])) + ((x1[0] * x1[0] + x1[1] * x1[1]) + (x1[2] * x1[2] + x1[3] * x1[3]));
;     ...
;             for (int m = 0; m < 4; ++m) { float t = ss[ai][m]; t += __shfl_xor(t, 16); t += __shfl_xor(t, 32);
;                 if (fq == 0) atomicAdd(rowss + row0 + ai * HALF + m * 16, t); }
	v_cvt_pk_f16_f32 v84, v30, v31
	v_cvt_pk_f16_f32 v85, v28, v29
	v_cvt_pk_f16_f32 v86, v26, v27
	v_cvt_pk_f16_f32 v87, v24, v25
	global_store_dwordx4 v[218:219], v[84:87], off offset:256
	s_nop 0
	s_nop 0
	v_cvt_f32_f16_e32 v84, v80
	v_cvt_f32_f16_sdwa v85, v80 dst_sel:DWORD dst_unused:UNUSED_PAD src0_sel:WORD_1
	v_cvt_f32_f16_e32 v80, v81
	v_cvt_f32_f16_sdwa v81, v81 dst_sel:DWORD dst_unused:UNUSED_PAD src0_sel:WORD_1
	v_cvt_f32_f16_e32 v86, v82
	v_fmamk_f32 v87, v171, 0x3b2aaaab, v227
	v_mul_f32_e32 v128, 0x4b800000, v87
	v_cmp_gt_f32_e32 vcc, s36, v87
	s_nop 1
	v_cndmask_b32_e32 v87, v87, v128, vcc
	v_rsq_f32_e32 v128, v87
	v_cvt_f32_f16_sdwa v87, v82 dst_sel:DWORD dst_unused:UNUSED_PAD src0_sel:WORD_1
	v_cvt_f32_f16_e32 v82, v83
	v_cvt_f32_f16_sdwa v83, v83 dst_sel:DWORD dst_unused:UNUSED_PAD src0_sel:WORD_1
	v_mul_f32_e32 v138, 0x45800000, v128
	v_cndmask_b32_e32 v128, v128, v138, vcc
	v_pk_mul_f32 v[138:139], v[20:21], v[128:129] op_sel_hi:[1,0]
	v_pk_mul_f32 v[20:21], v[22:23], v[128:129] op_sel_hi:[1,0]
	v_pk_mul_f32 v[140:141], v[16:17], v[128:129] op_sel_hi:[1,0]
	v_pk_mul_f32 v[16:17], v[18:19], v[128:129] op_sel_hi:[1,0]
	v_pk_fma_f32 v[20:21], v[70:71], v[20:21], v[80:81]
	v_pk_fma_f32 v[22:23], v[68:69], v[138:139], v[84:85]
	v_pk_fma_f32 v[16:17], v[66:67], v[16:17], v[82:83]
	v_pk_fma_f32 v[18:19], v[64:65], v[140:141], v[86:87]
	v_cvt_pk_f16_f32 v80, v22, v23
	v_cvt_pk_f16_f32 v81, v20, v21
	v_cvt_pk_f16_f32 v82, v18, v19
	v_cvt_pk_f16_f32 v83, v16, v17
	global_store_dwordx4 v[220:221], v[80:83], off offset:256
	s_nop 0
	s_nop 0
	v_cvt_f32_f16_e32 v80, v76
	v_cvt_f32_f16_sdwa v81, v76 dst_sel:DWORD dst_unused:UNUSED_PAD src0_sel:WORD_1
	v_cvt_f32_f16_e32 v76, v77
	v_cvt_f32_f16_sdwa v77, v77 dst_sel:DWORD dst_unused:UNUSED_PAD src0_sel:WORD_1
	v_cvt_f32_f16_e32 v82, v78
	v_fmamk_f32 v83, v173, 0x3b2aaaab, v227
	v_mov_b32_e32 v163, v129
	v_mov_b32_e32 v165, v129
	v_mov_b32_e32 v167, v129
	v_mov_b32_e32 v169, v129
	v_mov_b32_e32 v171, v129
	v_mov_b32_e32 v173, v129
	v_mul_f32_e32 v84, 0x4b800000, v83
	v_cmp_gt_f32_e32 vcc, s36, v83
	s_nop 1
	v_cndmask_b32_e32 v83, v83, v84, vcc
	v_rsq_f32_e32 v84, v83
	v_cvt_f32_f16_sdwa v83, v78 dst_sel:DWORD dst_unused:UNUSED_PAD src0_sel:WORD_1
	v_cvt_f32_f16_e32 v78, v79
	v_cvt_f32_f16_sdwa v79, v79 dst_sel:DWORD dst_unused:UNUSED_PAD src0_sel:WORD_1
	v_mul_f32_e32 v85, 0x45800000, v84
	v_cndmask_b32_e32 v84, v84, v85, vcc
	v_pk_mul_f32 v[86:87], v[12:13], v[84:85] op_sel_hi:[1,0]
	v_pk_mul_f32 v[12:13], v[14:15], v[84:85] op_sel_hi:[1,0]
	v_pk_mul_f32 v[138:139], v[8:9], v[84:85] op_sel_hi:[1,0]
	v_pk_mul_f32 v[8:9], v[10:11], v[84:85] op_sel_hi:[1,0]
	v_pk_fma_f32 v[12:13], v[70:71], v[12:13], v[76:77]
	v_pk_fma_f32 v[14:15], v[68:69], v[86:87], v[80:81]
	v_pk_fma_f32 v[8:9], v[66:67], v[8:9], v[78:79]
	v_pk_fma_f32 v[10:11], v[64:65], v[138:139], v[82:83]
	v_cvt_pk_f16_f32 v76, v14, v15
	v_cvt_pk_f16_f32 v77, v12, v13
	v_cvt_pk_f16_f32 v78, v10, v11
	v_cvt_pk_f16_f32 v79, v8, v9
	global_store_dwordx4 v[222:223], v[76:79], off offset:256
	global_load_dword v82, v[188:189], off offset:704
	v_mul_f32_e32 v80, v127, v127
	v_and_b32_e32 v77, 64, v230
	v_xor_b32_e32 v76, 16, v230
	v_add_u32_e32 v77, 64, v77
	v_xor_b32_e32 v78, 32, v230
	v_cmp_lt_i32_e32 vcc, v76, v77
	v_mul_f32_e32 v79, v121, v121
	v_mul_f32_e32 v81, v123, v123
	v_cndmask_b32_e32 v76, v230, v76, vcc
	v_cmp_lt_i32_e32 vcc, v78, v77
	v_lshlrev_b32_e32 v77, 2, v76
	v_fmac_f32_e32 v79, v120, v120
	v_cndmask_b32_e32 v78, v230, v78, vcc
	v_lshlrev_b32_e32 v76, 2, v78
	v_mul_f32_e32 v78, v125, v125
	v_fmac_f32_e32 v78, v124, v124
	v_fmac_f32_e32 v80, v126, v126
	v_fmac_f32_e32 v81, v122, v122
	v_add_f32_e32 v78, v78, v79
	v_add_f32_e32 v79, v80, v81
	v_add_f32_e32 v83, v78, v79
	v_add_f32_e32 v56, v83, v56
	ds_bpermute_b32 v57, v77, v56
	v_cvt_f32_f16_e32 v78, v72
	v_cvt_f32_f16_sdwa v79, v72 dst_sel:DWORD dst_unused:UNUSED_PAD src0_sel:WORD_1
	v_cvt_f32_f16_e32 v72, v73
	v_cvt_f32_f16_sdwa v73, v73 dst_sel:DWORD dst_unused:UNUSED_PAD src0_sel:WORD_1
	v_cvt_f32_f16_e32 v80, v74
	v_cvt_f32_f16_sdwa v81, v74 dst_sel:DWORD dst_unused:UNUSED_PAD src0_sel:WORD_1
	s_waitcnt vmcnt(0)
	v_fmamk_f32 v58, v82, 0x3b2aaaab, v227
	v_mul_f32_e32 v59, 0x4b800000, v58
	v_cmp_gt_f32_e32 vcc, s36, v58
	s_nop 1
	v_cndmask_b32_e32 v58, v58, v59, vcc
	v_rsq_f32_e32 v59, v58
	s_waitcnt lgkmcnt(0)
	v_add_f32_e32 v58, v56, v57
	v_mul_f32_e32 v56, 0x45800000, v59
	v_cndmask_b32_e32 v56, v59, v56, vcc
	v_pk_mul_f32 v[4:5], v[4:5], v[56:57] op_sel_hi:[1,0]
	v_pk_mul_f32 v[6:7], v[6:7], v[56:57] op_sel_hi:[1,0]
	v_pk_mul_f32 v[0:1], v[0:1], v[56:57] op_sel_hi:[1,0]
	v_pk_mul_f32 v[2:3], v[2:3], v[56:57] op_sel_hi:[1,0]
	v_pk_fma_f32 v[6:7], v[70:71], v[6:7], v[72:73]
	v_pk_fma_f32 v[56:57], v[68:69], v[4:5], v[78:79]
	v_pk_fma_f32 v[2:3], v[66:67], v[2:3], v[60:61]
	v_pk_fma_f32 v[4:5], v[64:65], v[0:1], v[80:81]
	v_cvt_pk_f16_f32 v60, v56, v57
	v_cvt_pk_f16_f32 v61, v6, v7
	v_cvt_pk_f16_f32 v62, v4, v5
	v_cvt_pk_f16_f32 v63, v2, v3
	ds_bpermute_b32 v59, v76, v58
	global_store_dwordx4 v[160:161], v[60:63], off offset:256
	v_lshl_add_u64 v[0:1], v[186:187], 2, s[46:47]
	s_and_saveexec_b64 s[0:1], s[40:41]
	s_cbranch_execz .LBB0_808
	s_waitcnt lgkmcnt(0)
	v_add_f32_e32 v58, v58, v59
	global_atomic_add_f32 v[0:1], v58, off

; __device__ __forceinline__ unsigned pk_bf16(float lo, float hi) { f32x2 v = {lo, hi}; bf16x2_t b = __builtin_convertvector(v, bf16x2_t); return __builtin_bit_cast(unsigned, b); }
;     __device__ __forceinline__ void operator()(const f32x4 (&acc)[2][2][4][2], const Unit& u, int wr, int wc, int fr, int fq) const {
;     ...
;                 float o[8]; const float rv = rsqrtf(rowss[row0 + ai * HALF + m * 16] * (1.0f / 1024.0f) + 1e-6f);
; #pragma unroll
;                 for (int n = 0; n < 2; ++n)
; #pragma unroll
;                     for (int j = 0; j < 4; ++j) { const float g = acc[ai][0][m][n][j] * rv + bz[0][n][j], up = acc[ai][1][m][n][j] * rv + bz[1][n][j];
;                         o[4 * n + j] = g * __builtin_amdgcn_rcpf(1.0f + __expf(-g)) * up; }
;                 u32x4 w; w.x = pk_bf16(o[0], o[1]); w.y = pk_bf16(o[2], o[3]); w.z = pk_bf16(o[4], o[5]); w.w = pk_bf16(o[6], o[7]);
;                 *(u32x4*)(act + (size_t)(row0 + ai * HALF + m * 16) * 2816 + col0) = w;
.LBB0_907:
	s_ashr_i32 s4, s34, 6
	s_mul_hi_i32 s5, s4, 0x5800
	s_mulk_i32 s4, 0x5800
	v_lshl_add_u32 v156, s34, 8, v162
	s_add_u32 s34, s14, s4
	s_addc_u32 s37, s15, s5
	s_lshl_b32 s4, s31, 8
	s_ashr_i32 s5, s4, 31
	s_lshl_b64 s[4:5], s[4:5], 2
	s_add_u32 s4, s34, s4
	s_addc_u32 s5, s37, s5
	s_add_u32 s4, s4, s30
	v_ashrrev_i32_e32 v157, 31, v156
	s_addc_u32 s5, s5, 0
	v_lshl_add_u64 v[158:159], v[156:157], 2, s[42:43]
	global_load_dwordx4 v[36:39], v166, s[4:5] offset:16
	global_load_dwordx4 v[44:47], v166, s[4:5]
	global_load_dwordx4 v[32:35], v166, s[4:5] offset:528
	global_load_dwordx4 v[40:43], v166, s[4:5] offset:512
	global_load_dword v157, v[158:159], off
	global_load_dword v186, v[158:159], off offset:64
	global_load_dword v187, v[158:159], off offset:128
	global_load_dword v188, v[158:159], off offset:192
	global_load_dword v189, v[158:159], off offset:512
	global_load_dword v190, v[158:159], off offset:576
	global_load_dword v191, v[158:159], off offset:640
	global_load_dword v192, v[158:159], off offset:704
	v_lshl_or_b32 v160, s31, 7, v164
	v_ashrrev_i32_e32 v161, 31, v160
	s_movk_i32 s12, 0x1600
	s_mov_b64 s[54:55], -1
	s_waitcnt vmcnt(0)
	v_fmamk_f32 v157, v157, 0x3a800000, v227
	s_nop 0
	v_rsq_f32_e32 v157, v157
	s_nop 0
	v_mov_b32_e32 v168, v157
	v_pk_fma_f32 v[142:143], v[142:143], v[168:169], v[44:45] op_sel_hi:[1,0,1]
	v_pk_fma_f32 v[134:135], v[134:135], v[168:169], v[40:41] op_sel_hi:[1,0,1]
	v_mul_f32_e32 v157, 0xbfb8aa3b, v142
	v_exp_f32_e32 v157, v157
	v_pk_fma_f32 v[136:137], v[136:137], v[168:169], v[42:43] op_sel_hi:[1,0,1]
	v_pk_fma_f32 v[138:139], v[138:139], v[168:169], v[36:37] op_sel_hi:[1,0,1]
	v_pk_fma_f32 v[130:131], v[130:131], v[168:169], v[32:33] op_sel_hi:[1,0,1]
	v_add_f32_e32 v157, 1.0, v157
	v_rcp_f32_e32 v170, v157
	v_mul_f32_e32 v157, 0xbfb8aa3b, v143
	v_exp_f32_e32 v157, v157
	v_pk_fma_f32 v[132:133], v[132:133], v[168:169], v[34:35] op_sel_hi:[1,0,1]
	v_add_f32_e32 v157, 1.0, v157
	v_rcp_f32_e32 v171, v157
	s_nop 0
	v_pk_mul_f32 v[142:143], v[142:143], v[170:171]
	s_nop 0
	v_pk_mul_f32 v[134:135], v[134:135], v[142:143]
	v_pk_fma_f32 v[142:143], v[144:145], v[168:169], v[46:47] op_sel_hi:[1,0,1]
	s_nop 0
	v_mul_f32_e32 v144, 0xbfb8aa3b, v142
	v_mul_f32_e32 v145, 0xbfb8aa3b, v143
	v_exp_f32_e32 v144, v144
	v_exp_f32_e32 v145, v145
	v_add_f32_e32 v144, 1.0, v144
	v_add_f32_e32 v145, 1.0, v145
	v_rcp_f32_e32 v144, v144
	v_rcp_f32_e32 v145, v145
	s_nop 0
	v_pk_mul_f32 v[142:143], v[142:143], v[144:145]
	s_nop 0
	v_pk_mul_f32 v[136:137], v[136:137], v[142:143]
	v_mul_f32_e32 v142, 0xbfb8aa3b, v138
	v_mul_f32_e32 v143, 0xbfb8aa3b, v139
	v_exp_f32_e32 v142, v142
	v_exp_f32_e32 v143, v143
	v_add_f32_e32 v142, 1.0, v142
	v_add_f32_e32 v143, 1.0, v143
	v_rcp_f32_e32 v142, v142
	v_rcp_f32_e32 v143, v143
	s_nop 0
	v_pk_mul_f32 v[138:139], v[138:139], v[142:143]
	s_nop 0
	v_pk_mul_f32 v[138:139], v[130:131], v[138:139]
	v_pk_fma_f32 v[130:131], v[140:141], v[168:169], v[38:39] op_sel_hi:[1,0,1]
	s_nop 0
	v_mul_f32_e32 v140, 0xbfb8aa3b, v130
	v_mul_f32_e32 v141, 0xbfb8aa3b, v131
	v_exp_f32_e32 v140, v140
	v_exp_f32_e32 v141, v141
	v_add_f32_e32 v140, 1.0, v140
	v_add_f32_e32 v141, 1.0, v141
	v_rcp_f32_e32 v140, v140
	v_rcp_f32_e32 v141, v141
	s_nop 0
	v_pk_mul_f32 v[130:131], v[130:131], v[140:141]
	s_nop 0
	v_pk_mul_f32 v[140:141], v[132:133], v[130:131]
	v_cvt_pk_bf16_f32 v130, v134, v135
	v_mov_b64_e32 v[134:135], s[2:3]
	v_cvt_pk_bf16_f32 v131, v136, v137
	v_cvt_pk_bf16_f32 v132, v138, v139
	v_mad_i64_i32 v[138:139], s[4:5], v156, s12, v[134:135]
	v_lshlrev_b64 v[136:137], 1, v[160:161]
	v_cvt_pk_bf16_f32 v133, v140, v141
	v_lshl_add_u64 v[138:139], v[138:139], 0, v[136:137]
	global_store_dwordx4 v[138:139], v[130:133], off
	s_nop 1
	v_or_b32_e32 v130, 16, v156
	v_fmamk_f32 v131, v186, 0x3a800000, v227
	s_nop 0
	v_rsq_f32_e32 v131, v131
	s_nop 0
	v_mov_b32_e32 v132, v131
	v_pk_fma_f32 v[124:125], v[124:125], v[132:133], v[44:45] op_sel_hi:[1,0,1]
	v_pk_fma_f32 v[116:117], v[116:117], v[132:133], v[40:41] op_sel_hi:[1,0,1]
	v_mul_f32_e32 v131, 0xbfb8aa3b, v124
	v_exp_f32_e32 v131, v131
	v_pk_fma_f32 v[118:119], v[118:119], v[132:133], v[42:43] op_sel_hi:[1,0,1]
	v_pk_fma_f32 v[120:121], v[120:121], v[132:133], v[36:37] op_sel_hi:[1,0,1]
	v_pk_fma_f32 v[112:113], v[112:113], v[132:133], v[32:33] op_sel_hi:[1,0,1]
	v_add_f32_e32 v131, 1.0, v131
	v_rcp_f32_e32 v138, v131
	v_mul_f32_e32 v131, 0xbfb8aa3b, v125
	v_exp_f32_e32 v131, v131
	v_pk_fma_f32 v[114:115], v[114:115], v[132:133], v[34:35] op_sel_hi:[1,0,1]
	v_add_f32_e32 v131, 1.0, v131
	v_rcp_f32_e32 v139, v131
	s_nop 0
	v_pk_mul_f32 v[124:125], v[124:125], v[138:139]
	s_nop 0
	v_pk_mul_f32 v[116:117], v[116:117], v[124:125]
	v_pk_fma_f32 v[124:125], v[126:127], v[132:133], v[46:47] op_sel_hi:[1,0,1]
	s_nop 0
	v_mul_f32_e32 v126, 0xbfb8aa3b, v124
	v_mul_f32_e32 v127, 0xbfb8aa3b, v125
	v_exp_f32_e32 v126, v126
	v_exp_f32_e32 v127, v127
	v_add_f32_e32 v126, 1.0, v126
	v_add_f32_e32 v127, 1.0, v127
	v_rcp_f32_e32 v126, v126
	v_rcp_f32_e32 v127, v127
	s_nop 0
	v_pk_mul_f32 v[124:125], v[124:125], v[126:127]
	s_nop 0
	v_pk_mul_f32 v[118:119], v[118:119], v[124:125]
	v_mul_f32_e32 v124, 0xbfb8aa3b, v120
	v_mul_f32_e32 v125, 0xbfb8aa3b, v121
	v_exp_f32_e32 v124, v124
	v_exp_f32_e32 v125, v125
	v_add_f32_e32 v124, 1.0, v124
	v_add_f32_e32 v125, 1.0, v125
	v_rcp_f32_e32 v124, v124
	v_rcp_f32_e32 v125, v125
	s_nop 0
	v_pk_mul_f32 v[120:121], v[120:121], v[124:125]
	s_nop 0
	v_pk_mul_f32 v[120:121], v[112:113], v[120:121]
	v_pk_fma_f32 v[112:113], v[122:123], v[132:133], v[38:39] op_sel_hi:[1,0,1]
	s_nop 0
	v_mul_f32_e32 v122, 0xbfb8aa3b, v112
; __device__ __forceinline__ unsigned pk_bf16(float lo, float hi) { f32x2 v = {lo, hi}; bf16x2_t b = __builtin_convertvector(v, bf16x2_t); return __builtin_bit_cast(unsigned, b); }
;     __device__ __forceinline__ void operator()(const f32x4 (&acc)[2][2][4][2], const Unit& u, int wr, int wc, int fr, int fq) const {
;     ...
;                 float o[8]; const float rv = rsqrtf(rowss[row0 + ai * HALF + m * 16] * (1.0f / 1024.0f) + 1e-6f);
; #pragma unroll
;                 for (int n = 0; n < 2; ++n)
; #pragma unroll
;                     for (int j = 0; j < 4; ++j) { const float g = acc[ai][0][m][n][j] * rv + bz[0][n][j], up = acc[ai][1][m][n][j] * rv + bz[1][n][j];
;                         o[4 * n + j] = g * __builtin_amdgcn_rcpf(1.0f + __expf(-g)) * up; }
;                 u32x4 w; w.x = pk_bf16(o[0], o[1]); w.y = pk_bf16(o[2], o[3]); w.z = pk_bf16(o[4], o[5]); w.w = pk_bf16(o[6], o[7]);
;                 *(u32x4*)(act + (size_t)(row0 + ai * HALF + m * 16) * 2816 + col0) = w;
	v_mul_f32_e32 v123, 0xbfb8aa3b, v113
	v_exp_f32_e32 v122, v122
	v_exp_f32_e32 v123, v123
	v_add_f32_e32 v122, 1.0, v122
	v_add_f32_e32 v123, 1.0, v123
	v_rcp_f32_e32 v122, v122
	v_rcp_f32_e32 v123, v123
	s_nop 0
	v_pk_mul_f32 v[112:113], v[112:113], v[122:123]
	s_nop 0
	v_pk_mul_f32 v[122:123], v[114:115], v[112:113]
	v_cvt_pk_bf16_f32 v112, v116, v117
	v_mad_i64_i32 v[116:117], s[4:5], v130, s12, v[134:135]
	v_cvt_pk_bf16_f32 v113, v118, v119
	v_cvt_pk_bf16_f32 v114, v120, v121
	v_cvt_pk_bf16_f32 v115, v122, v123
	v_lshl_add_u64 v[116:117], v[116:117], 0, v[136:137]
	global_store_dwordx4 v[116:117], v[112:115], off
	s_nop 1
	v_or_b32_e32 v112, 32, v156
	v_fmamk_f32 v113, v187, 0x3a800000, v227
	s_nop 0
	v_rsq_f32_e32 v113, v113
	s_nop 0
	v_mov_b32_e32 v114, v113
	v_pk_fma_f32 v[108:109], v[108:109], v[114:115], v[44:45] op_sel_hi:[1,0,1]
	v_pk_fma_f32 v[100:101], v[100:101], v[114:115], v[40:41] op_sel_hi:[1,0,1]
	v_mul_f32_e32 v113, 0xbfb8aa3b, v108
	v_exp_f32_e32 v113, v113
	v_pk_fma_f32 v[102:103], v[102:103], v[114:115], v[42:43] op_sel_hi:[1,0,1]
	v_pk_fma_f32 v[104:105], v[104:105], v[114:115], v[36:37] op_sel_hi:[1,0,1]
	v_pk_fma_f32 v[96:97], v[96:97], v[114:115], v[32:33] op_sel_hi:[1,0,1]
	v_add_f32_e32 v113, 1.0, v113
	v_rcp_f32_e32 v116, v113
	v_mul_f32_e32 v113, 0xbfb8aa3b, v109
	v_exp_f32_e32 v113, v113
	v_pk_fma_f32 v[98:99], v[98:99], v[114:115], v[34:35] op_sel_hi:[1,0,1]
	v_add_f32_e32 v113, 1.0, v113
	v_rcp_f32_e32 v117, v113
	s_nop 0
	v_pk_mul_f32 v[108:109], v[108:109], v[116:117]
	s_nop 0
	v_pk_mul_f32 v[100:101], v[100:101], v[108:109]
	v_pk_fma_f32 v[108:109], v[110:111], v[114:115], v[46:47] op_sel_hi:[1,0,1]
	s_nop 0
	v_mul_f32_e32 v110, 0xbfb8aa3b, v108
	v_mul_f32_e32 v111, 0xbfb8aa3b, v109
	v_exp_f32_e32 v110, v110
	v_exp_f32_e32 v111, v111
	v_add_f32_e32 v110, 1.0, v110
	v_add_f32_e32 v111, 1.0, v111
	v_rcp_f32_e32 v110, v110
	v_rcp_f32_e32 v111, v111
	s_nop 0
	v_pk_mul_f32 v[108:109], v[108:109], v[110:111]
	s_nop 0
	v_pk_mul_f32 v[102:103], v[102:103], v[108:109]
	v_mul_f32_e32 v108, 0xbfb8aa3b, v104
	v_mul_f32_e32 v109, 0xbfb8aa3b, v105
	v_exp_f32_e32 v108, v108
	v_exp_f32_e32 v109, v109
	v_add_f32_e32 v108, 1.0, v108
	v_add_f32_e32 v109, 1.0, v109
	v_rcp_f32_e32 v108, v108
	v_rcp_f32_e32 v109, v109
	s_nop 0
	v_pk_mul_f32 v[104:105], v[104:105], v[108:109]
	s_nop 0
	v_pk_mul_f32 v[104:105], v[96:97], v[104:105]
	v_pk_fma_f32 v[96:97], v[106:107], v[114:115], v[38:39] op_sel_hi:[1,0,1]
	s_nop 0
	v_mul_f32_e32 v106, 0xbfb8aa3b, v96
	v_mul_f32_e32 v107, 0xbfb8aa3b, v97
	v_exp_f32_e32 v106, v106
	v_exp_f32_e32 v107, v107
	v_add_f32_e32 v106, 1.0, v106
	v_add_f32_e32 v107, 1.0, v107
	v_rcp_f32_e32 v106, v106
	v_rcp_f32_e32 v107, v107
	s_nop 0
	v_pk_mul_f32 v[96:97], v[96:97], v[106:107]
	s_nop 0
	v_pk_mul_f32 v[106:107], v[98:99], v[96:97]
	v_cvt_pk_bf16_f32 v96, v100, v101
	v_mad_i64_i32 v[100:101], s[4:5], v112, s12, v[134:135]
	v_cvt_pk_bf16_f32 v97, v102, v103
	v_cvt_pk_bf16_f32 v98, v104, v105
	v_cvt_pk_bf16_f32 v99, v106, v107
	v_lshl_add_u64 v[100:101], v[100:101], 0, v[136:137]
	global_store_dwordx4 v[100:101], v[96:99], off
	s_nop 1
	v_or_b32_e32 v96, 48, v156
	v_fmamk_f32 v97, v188, 0x3a800000, v227
	s_nop 0
	v_rsq_f32_e32 v97, v97
	s_nop 0
	v_mov_b32_e32 v98, v97
	v_pk_fma_f32 v[92:93], v[92:93], v[98:99], v[44:45] op_sel_hi:[1,0,1]
	v_pk_fma_f32 v[84:85], v[84:85], v[98:99], v[40:41] op_sel_hi:[1,0,1]
	v_mul_f32_e32 v97, 0xbfb8aa3b, v92
	v_exp_f32_e32 v97, v97
	v_pk_fma_f32 v[86:87], v[86:87], v[98:99], v[42:43] op_sel_hi:[1,0,1]
	v_pk_fma_f32 v[88:89], v[88:89], v[98:99], v[36:37] op_sel_hi:[1,0,1]
	v_pk_fma_f32 v[80:81], v[80:81], v[98:99], v[32:33] op_sel_hi:[1,0,1]
	v_add_f32_e32 v97, 1.0, v97
	v_rcp_f32_e32 v100, v97
	v_mul_f32_e32 v97, 0xbfb8aa3b, v93
	v_exp_f32_e32 v97, v97
	v_pk_fma_f32 v[82:83], v[82:83], v[98:99], v[34:35] op_sel_hi:[1,0,1]
	v_add_f32_e32 v97, 1.0, v97
	v_rcp_f32_e32 v101, v97
	s_nop 0
	v_pk_mul_f32 v[92:93], v[92:93], v[100:101]
	s_nop 0
	v_pk_mul_f32 v[84:85], v[84:85], v[92:93]
	v_pk_fma_f32 v[92:93], v[94:95], v[98:99], v[46:47] op_sel_hi:[1,0,1]
	s_nop 0
	v_mul_f32_e32 v94, 0xbfb8aa3b, v92
	v_mul_f32_e32 v95, 0xbfb8aa3b, v93
	v_exp_f32_e32 v94, v94
	v_exp_f32_e32 v95, v95
	v_add_f32_e32 v94, 1.0, v94
	v_add_f32_e32 v95, 1.0, v95
	v_rcp_f32_e32 v94, v94
	v_rcp_f32_e32 v95, v95
	s_nop 0
	v_pk_mul_f32 v[92:93], v[92:93], v[94:95]
	s_nop 0
	v_pk_mul_f32 v[86:87], v[86:87], v[92:93]
	v_mul_f32_e32 v92, 0xbfb8aa3b, v88
	v_mul_f32_e32 v93, 0xbfb8aa3b, v89
	v_exp_f32_e32 v92, v92
	v_exp_f32_e32 v93, v93
	v_add_f32_e32 v92, 1.0, v92
	v_add_f32_e32 v93, 1.0, v93
	v_rcp_f32_e32 v92, v92
	v_rcp_f32_e32 v93, v93
	s_nop 0
	v_pk_mul_f32 v[88:89], v[88:89], v[92:93]
	s_nop 0
	v_pk_mul_f32 v[88:89], v[80:81], v[88:89]
	v_pk_fma_f32 v[80:81], v[90:91], v[98:99], v[38:39] op_sel_hi:[1,0,1]
	s_nop 0
	v_mul_f32_e32 v90, 0xbfb8aa3b, v80
	v_mul_f32_e32 v91, 0xbfb8aa3b, v81
	v_exp_f32_e32 v90, v90
	v_exp_f32_e32 v91, v91
	v_add_f32_e32 v90, 1.0, v90
	v_add_f32_e32 v91, 1.0, v91
	v_rcp_f32_e32 v90, v90
	v_rcp_f32_e32 v91, v91
	s_nop 0
	v_pk_mul_f32 v[80:81], v[80:81], v[90:91]
	s_nop 0
	v_pk_mul_f32 v[90:91], v[82:83], v[80:81]
	v_cvt_pk_bf16_f32 v80, v84, v85
	v_mad_i64_i32 v[84:85], s[4:5], v96, s12, v[134:135]
	v_cvt_pk_bf16_f32 v81, v86, v87
	v_cvt_pk_bf16_f32 v82, v88, v89
	v_cvt_pk_bf16_f32 v83, v90, v91
	v_lshl_add_u64 v[84:85], v[84:85], 0, v[136:137]
	global_store_dwordx4 v[84:85], v[80:83], off
	s_nop 0
	s_nop 0
	v_add_u32_e32 v81, 0x80, v156
	v_fmamk_f32 v80, v189, 0x3a800000, v227
	s_nop 0
	v_rsq_f32_e32 v80, v80
	s_nop 0
	v_pk_fma_f32 v[76:77], v[76:77], v[80:81], v[44:45] op_sel_hi:[1,0,1]
; __device__ __forceinline__ unsigned pk_bf16(float lo, float hi) { f32x2 v = {lo, hi}; bf16x2_t b = __builtin_convertvector(v, bf16x2_t); return __builtin_bit_cast(unsigned, b); }
;     __device__ __forceinline__ void operator()(const f32x4 (&acc)[2][2][4][2], const Unit& u, int wr, int wc, int fr, int fq) const {
;     ...
;                 float o[8]; const float rv = rsqrtf(rowss[row0 + ai * HALF + m * 16] * (1.0f / 1024.0f) + 1e-6f);
; #pragma unroll
;                 for (int n = 0; n < 2; ++n)
; #pragma unroll
;                     for (int j = 0; j < 4; ++j) { const float g = acc[ai][0][m][n][j] * rv + bz[0][n][j], up = acc[ai][1][m][n][j] * rv + bz[1][n][j];
;                         o[4 * n + j] = g * __builtin_amdgcn_rcpf(1.0f + __expf(-g)) * up; }
;                 u32x4 w; w.x = pk_bf16(o[0], o[1]); w.y = pk_bf16(o[2], o[3]); w.z = pk_bf16(o[4], o[5]); w.w = pk_bf16(o[6], o[7]);
;                 *(u32x4*)(act + (size_t)(row0 + ai * HALF + m * 16) * 2816 + col0) = w;
	v_pk_fma_f32 v[68:69], v[68:69], v[80:81], v[40:41] op_sel_hi:[1,0,1]
	v_mul_f32_e32 v82, 0xbfb8aa3b, v76
	v_mul_f32_e32 v83, 0xbfb8aa3b, v77
	v_exp_f32_e32 v82, v82
	v_exp_f32_e32 v83, v83
	v_pk_fma_f32 v[70:71], v[70:71], v[80:81], v[42:43] op_sel_hi:[1,0,1]
	v_pk_fma_f32 v[72:73], v[72:73], v[80:81], v[36:37] op_sel_hi:[1,0,1]
	v_add_f32_e32 v82, 1.0, v82
	v_add_f32_e32 v83, 1.0, v83
	v_rcp_f32_e32 v82, v82
	v_rcp_f32_e32 v83, v83
	v_pk_fma_f32 v[64:65], v[64:65], v[80:81], v[32:33] op_sel_hi:[1,0,1]
	v_pk_fma_f32 v[66:67], v[66:67], v[80:81], v[34:35] op_sel_hi:[1,0,1]
	v_pk_mul_f32 v[76:77], v[76:77], v[82:83]
	s_nop 0
	v_pk_mul_f32 v[68:69], v[68:69], v[76:77]
	v_pk_fma_f32 v[76:77], v[78:79], v[80:81], v[46:47] op_sel_hi:[1,0,1]
	s_nop 0
	v_mul_f32_e32 v78, 0xbfb8aa3b, v76
	v_mul_f32_e32 v79, 0xbfb8aa3b, v77
	v_exp_f32_e32 v78, v78
	v_exp_f32_e32 v79, v79
	v_add_f32_e32 v78, 1.0, v78
	v_add_f32_e32 v79, 1.0, v79
	v_rcp_f32_e32 v78, v78
	v_rcp_f32_e32 v79, v79
	s_nop 0
	v_pk_mul_f32 v[76:77], v[76:77], v[78:79]
	s_nop 0
	v_pk_mul_f32 v[70:71], v[70:71], v[76:77]
	v_mul_f32_e32 v76, 0xbfb8aa3b, v72
	v_mul_f32_e32 v77, 0xbfb8aa3b, v73
	v_exp_f32_e32 v76, v76
	v_exp_f32_e32 v77, v77
	v_add_f32_e32 v76, 1.0, v76
	v_add_f32_e32 v77, 1.0, v77
	v_rcp_f32_e32 v76, v76
	v_rcp_f32_e32 v77, v77
	s_nop 0
	v_pk_mul_f32 v[72:73], v[72:73], v[76:77]
	s_nop 0
	v_pk_mul_f32 v[72:73], v[64:65], v[72:73]
	v_pk_fma_f32 v[64:65], v[74:75], v[80:81], v[38:39] op_sel_hi:[1,0,1]
	s_nop 0
	v_mul_f32_e32 v74, 0xbfb8aa3b, v64
	v_mul_f32_e32 v75, 0xbfb8aa3b, v65
	v_exp_f32_e32 v74, v74
	v_exp_f32_e32 v75, v75
	v_add_f32_e32 v74, 1.0, v74
	v_add_f32_e32 v75, 1.0, v75
	v_rcp_f32_e32 v74, v74
	v_rcp_f32_e32 v75, v75
	s_nop 0
	v_pk_mul_f32 v[64:65], v[64:65], v[74:75]
	s_nop 0
	v_pk_mul_f32 v[74:75], v[66:67], v[64:65]
	v_cvt_pk_bf16_f32 v64, v68, v69
	v_mad_i64_i32 v[68:69], s[4:5], v81, s12, v[134:135]
	v_cvt_pk_bf16_f32 v65, v70, v71
	v_cvt_pk_bf16_f32 v66, v72, v73
	v_cvt_pk_bf16_f32 v67, v74, v75
	v_lshl_add_u64 v[68:69], v[68:69], 0, v[136:137]
	global_store_dwordx4 v[68:69], v[64:67], off
	s_nop 0
	s_nop 0
	v_add_u32_e32 v65, 0x90, v156
	v_fmamk_f32 v64, v190, 0x3a800000, v227
	s_nop 0
	v_rsq_f32_e32 v64, v64
	s_nop 0
	v_pk_fma_f32 v[60:61], v[60:61], v[64:65], v[44:45] op_sel_hi:[1,0,1]
	v_pk_fma_f32 v[52:53], v[52:53], v[64:65], v[40:41] op_sel_hi:[1,0,1]
	v_mul_f32_e32 v66, 0xbfb8aa3b, v60
	v_mul_f32_e32 v67, 0xbfb8aa3b, v61
	v_exp_f32_e32 v66, v66
	v_exp_f32_e32 v67, v67
	v_pk_fma_f32 v[54:55], v[54:55], v[64:65], v[42:43] op_sel_hi:[1,0,1]
	v_pk_fma_f32 v[56:57], v[56:57], v[64:65], v[36:37] op_sel_hi:[1,0,1]
	v_add_f32_e32 v66, 1.0, v66
	v_add_f32_e32 v67, 1.0, v67
	v_rcp_f32_e32 v66, v66
	v_rcp_f32_e32 v67, v67
	v_pk_fma_f32 v[48:49], v[48:49], v[64:65], v[32:33] op_sel_hi:[1,0,1]
	v_pk_fma_f32 v[50:51], v[50:51], v[64:65], v[34:35] op_sel_hi:[1,0,1]
	v_pk_mul_f32 v[60:61], v[60:61], v[66:67]
	s_nop 0
	v_pk_mul_f32 v[52:53], v[52:53], v[60:61]
	v_pk_fma_f32 v[60:61], v[62:63], v[64:65], v[46:47] op_sel_hi:[1,0,1]
	s_nop 0
	v_mul_f32_e32 v62, 0xbfb8aa3b, v60
	v_mul_f32_e32 v63, 0xbfb8aa3b, v61
	v_exp_f32_e32 v62, v62
	v_exp_f32_e32 v63, v63
	v_add_f32_e32 v62, 1.0, v62
	v_add_f32_e32 v63, 1.0, v63
	v_rcp_f32_e32 v62, v62
	v_rcp_f32_e32 v63, v63
	s_nop 0
	v_pk_mul_f32 v[60:61], v[60:61], v[62:63]
	s_nop 0
	v_pk_mul_f32 v[54:55], v[54:55], v[60:61]
	v_mul_f32_e32 v60, 0xbfb8aa3b, v56
	v_mul_f32_e32 v61, 0xbfb8aa3b, v57
	v_exp_f32_e32 v60, v60
	v_exp_f32_e32 v61, v61
	v_add_f32_e32 v60, 1.0, v60
	v_add_f32_e32 v61, 1.0, v61
	v_rcp_f32_e32 v60, v60
	v_rcp_f32_e32 v61, v61
	s_nop 0
	v_pk_mul_f32 v[56:57], v[56:57], v[60:61]
	s_nop 0
	v_pk_mul_f32 v[56:57], v[48:49], v[56:57]
	v_pk_fma_f32 v[48:49], v[58:59], v[64:65], v[38:39] op_sel_hi:[1,0,1]
	s_nop 0
	v_mul_f32_e32 v58, 0xbfb8aa3b, v48
	v_mul_f32_e32 v59, 0xbfb8aa3b, v49
	v_exp_f32_e32 v58, v58
	v_exp_f32_e32 v59, v59
	v_add_f32_e32 v58, 1.0, v58
	v_add_f32_e32 v59, 1.0, v59
	v_rcp_f32_e32 v58, v58
	v_rcp_f32_e32 v59, v59
	s_nop 0
	v_pk_mul_f32 v[48:49], v[48:49], v[58:59]
	s_nop 0
	v_pk_mul_f32 v[58:59], v[50:51], v[48:49]
	v_cvt_pk_bf16_f32 v48, v52, v53
	v_mad_i64_i32 v[52:53], s[4:5], v65, s12, v[134:135]
	v_cvt_pk_bf16_f32 v49, v54, v55
	v_cvt_pk_bf16_f32 v50, v56, v57
	v_cvt_pk_bf16_f32 v51, v58, v59
	v_lshl_add_u64 v[52:53], v[52:53], 0, v[136:137]
	global_store_dwordx4 v[52:53], v[48:51], off
	s_nop 0
	s_nop 0
	v_add_u32_e32 v49, 0xa0, v156
	v_fmamk_f32 v48, v191, 0x3a800000, v227
	s_nop 0
	v_rsq_f32_e32 v48, v48
	s_nop 0
; __device__ __forceinline__ unsigned pk_bf16(float lo, float hi) { f32x2 v = {lo, hi}; bf16x2_t b = __builtin_convertvector(v, bf16x2_t); return __builtin_bit_cast(unsigned, b); }
;     __device__ __forceinline__ void operator()(const f32x4 (&acc)[2][2][4][2], const Unit& u, int wr, int wc, int fr, int fq) const {
;     ...
;                 float o[8]; const float rv = rsqrtf(rowss[row0 + ai * HALF + m * 16] * (1.0f / 1024.0f) + 1e-6f);
; #pragma unroll
;                 for (int n = 0; n < 2; ++n)
; #pragma unroll
;                     for (int j = 0; j < 4; ++j) { const float g = acc[ai][0][m][n][j] * rv + bz[0][n][j], up = acc[ai][1][m][n][j] * rv + bz[1][n][j];
;                         o[4 * n + j] = g * __builtin_amdgcn_rcpf(1.0f + __expf(-g)) * up; }
;                 u32x4 w; w.x = pk_bf16(o[0], o[1]); w.y = pk_bf16(o[2], o[3]); w.z = pk_bf16(o[4], o[5]); w.w = pk_bf16(o[6], o[7]);
;                 *(u32x4*)(act + (size_t)(row0 + ai * HALF + m * 16) * 2816 + col0) = w;
	v_pk_fma_f32 v[28:29], v[28:29], v[48:49], v[44:45] op_sel_hi:[1,0,1]
	v_pk_fma_f32 v[20:21], v[20:21], v[48:49], v[40:41] op_sel_hi:[1,0,1]
	v_mul_f32_e32 v50, 0xbfb8aa3b, v28
	v_mul_f32_e32 v51, 0xbfb8aa3b, v29
	v_exp_f32_e32 v50, v50
	v_exp_f32_e32 v51, v51
	v_pk_fma_f32 v[22:23], v[22:23], v[48:49], v[42:43] op_sel_hi:[1,0,1]
	v_pk_fma_f32 v[24:25], v[24:25], v[48:49], v[36:37] op_sel_hi:[1,0,1]
	v_add_f32_e32 v50, 1.0, v50
	v_add_f32_e32 v51, 1.0, v51
	v_rcp_f32_e32 v50, v50
	v_rcp_f32_e32 v51, v51
	v_pk_fma_f32 v[16:17], v[16:17], v[48:49], v[32:33] op_sel_hi:[1,0,1]
	v_pk_fma_f32 v[18:19], v[18:19], v[48:49], v[34:35] op_sel_hi:[1,0,1]
	v_pk_mul_f32 v[28:29], v[28:29], v[50:51]
	s_nop 0
	v_pk_mul_f32 v[20:21], v[20:21], v[28:29]
	v_pk_fma_f32 v[28:29], v[30:31], v[48:49], v[46:47] op_sel_hi:[1,0,1]
	s_nop 0
	v_mul_f32_e32 v30, 0xbfb8aa3b, v28
	v_mul_f32_e32 v31, 0xbfb8aa3b, v29
	v_exp_f32_e32 v30, v30
	v_exp_f32_e32 v31, v31
	v_add_f32_e32 v30, 1.0, v30
	v_add_f32_e32 v31, 1.0, v31
	v_rcp_f32_e32 v30, v30
	v_rcp_f32_e32 v31, v31
	s_nop 0
	v_pk_mul_f32 v[28:29], v[28:29], v[30:31]
	s_nop 0
	v_pk_mul_f32 v[22:23], v[22:23], v[28:29]
	v_mul_f32_e32 v28, 0xbfb8aa3b, v24
	v_mul_f32_e32 v29, 0xbfb8aa3b, v25
	v_exp_f32_e32 v28, v28
	v_exp_f32_e32 v29, v29
	v_add_f32_e32 v28, 1.0, v28
	v_add_f32_e32 v29, 1.0, v29
	v_rcp_f32_e32 v28, v28
	v_rcp_f32_e32 v29, v29
	s_nop 0
	v_pk_mul_f32 v[24:25], v[24:25], v[28:29]
	s_nop 0
	v_pk_mul_f32 v[24:25], v[16:17], v[24:25]
	v_pk_fma_f32 v[16:17], v[26:27], v[48:49], v[38:39] op_sel_hi:[1,0,1]
	s_nop 0
	v_mul_f32_e32 v26, 0xbfb8aa3b, v16
	v_mul_f32_e32 v27, 0xbfb8aa3b, v17
	v_exp_f32_e32 v26, v26
	v_exp_f32_e32 v27, v27
	v_add_f32_e32 v26, 1.0, v26
	v_add_f32_e32 v27, 1.0, v27
	v_rcp_f32_e32 v26, v26
	v_rcp_f32_e32 v27, v27
	s_nop 0
	v_pk_mul_f32 v[16:17], v[16:17], v[26:27]
	s_nop 0
	v_pk_mul_f32 v[26:27], v[18:19], v[16:17]
	v_cvt_pk_bf16_f32 v16, v20, v21
	v_mad_i64_i32 v[20:21], s[4:5], v49, s12, v[134:135]
	v_cvt_pk_bf16_f32 v17, v22, v23
	v_cvt_pk_bf16_f32 v18, v24, v25
	v_cvt_pk_bf16_f32 v19, v26, v27
	v_lshl_add_u64 v[20:21], v[20:21], 0, v[136:137]
	global_store_dwordx4 v[20:21], v[16:19], off
	s_nop 0
	s_nop 0
	v_add_u32_e32 v17, 0xb0, v156
	v_fmamk_f32 v16, v192, 0x3a800000, v227
	s_nop 0
	v_rsq_f32_e32 v16, v16
	s_nop 0
	v_pk_fma_f32 v[12:13], v[12:13], v[16:17], v[44:45] op_sel_hi:[1,0,1]
	v_pk_fma_f32 v[4:5], v[4:5], v[16:17], v[40:41] op_sel_hi:[1,0,1]
	v_mul_f32_e32 v18, 0xbfb8aa3b, v12
	v_mul_f32_e32 v19, 0xbfb8aa3b, v13
	v_exp_f32_e32 v18, v18
	v_exp_f32_e32 v19, v19
	v_pk_fma_f32 v[6:7], v[6:7], v[16:17], v[42:43] op_sel_hi:[1,0,1]
	v_pk_fma_f32 v[8:9], v[8:9], v[16:17], v[36:37] op_sel_hi:[1,0,1]
	v_add_f32_e32 v18, 1.0, v18
	v_add_f32_e32 v19, 1.0, v19
	v_rcp_f32_e32 v18, v18
	v_rcp_f32_e32 v19, v19
	v_pk_fma_f32 v[0:1], v[0:1], v[16:17], v[32:33] op_sel_hi:[1,0,1]
	v_pk_fma_f32 v[2:3], v[2:3], v[16:17], v[34:35] op_sel_hi:[1,0,1]
	s_andn2_b64 vcc, exec, s[40:41]
	v_pk_mul_f32 v[12:13], v[12:13], v[18:19]
	s_nop 0
	v_pk_mul_f32 v[4:5], v[4:5], v[12:13]
	v_pk_fma_f32 v[12:13], v[14:15], v[16:17], v[46:47] op_sel_hi:[1,0,1]
	s_nop 0
	v_mul_f32_e32 v14, 0xbfb8aa3b, v12
	v_mul_f32_e32 v15, 0xbfb8aa3b, v13
	v_exp_f32_e32 v14, v14
	v_exp_f32_e32 v15, v15
	v_add_f32_e32 v14, 1.0, v14
	v_add_f32_e32 v15, 1.0, v15
	v_rcp_f32_e32 v14, v14
	v_rcp_f32_e32 v15, v15
	s_nop 0
	v_pk_mul_f32 v[12:13], v[12:13], v[14:15]
	s_nop 0
	v_pk_mul_f32 v[6:7], v[6:7], v[12:13]
	v_mul_f32_e32 v12, 0xbfb8aa3b, v8
	v_mul_f32_e32 v13, 0xbfb8aa3b, v9
	v_exp_f32_e32 v12, v12
	v_exp_f32_e32 v13, v13
	v_add_f32_e32 v12, 1.0, v12
	v_add_f32_e32 v13, 1.0, v13
	v_rcp_f32_e32 v12, v12
	v_rcp_f32_e32 v13, v13
	s_nop 0
	v_pk_mul_f32 v[8:9], v[8:9], v[12:13]
	s_nop 0
	v_pk_mul_f32 v[8:9], v[0:1], v[8:9]
	v_pk_fma_f32 v[0:1], v[10:11], v[16:17], v[38:39] op_sel_hi:[1,0,1]
	s_nop 0
	v_mul_f32_e32 v10, 0xbfb8aa3b, v0
	v_mul_f32_e32 v11, 0xbfb8aa3b, v1
	v_exp_f32_e32 v10, v10
	v_exp_f32_e32 v11, v11
	v_add_f32_e32 v10, 1.0, v10
	v_add_f32_e32 v11, 1.0, v11
	v_rcp_f32_e32 v10, v10
	v_rcp_f32_e32 v11, v11
	s_nop 0
	v_pk_mul_f32 v[0:1], v[0:1], v[10:11]
	s_nop 0
	v_pk_mul_f32 v[10:11], v[2:3], v[0:1]
	v_cvt_pk_bf16_f32 v0, v4, v5
	v_mad_i64_i32 v[4:5], s[4:5], v17, s12, v[134:135]
	v_cvt_pk_bf16_f32 v1, v6, v7
	v_cvt_pk_bf16_f32 v2, v8, v9
	v_cvt_pk_bf16_f32 v3, v10, v11
	v_lshl_add_u64 v[4:5], v[4:5], 0, v[136:137]
	global_store_dwordx4 v[4:5], v[0:3], off
	s_cbranch_vccnz .LBB0_900
	s_andn2_b64 vcc, exec, s[0:1]
	s_cbranch_vccnz .LBB0_899
	s_barrier
	s_branch .LBB0_899
